# K-loops: loop counter / pointer updates moved from the head of the next LDS-read segment to the tail of the last MFMA segment (before the barrier)
# baseline (speedup 1.0000x reference)
; #define PG8_STAGE(bufoff, gbase, voff) do { _Pragma("unroll") for (int _i = 0; _i < 2; ++_i) \
;         __builtin_amdgcn_global_load_lds((const unsigned*)((const char*)(gbase) + (voff)[_i]), (LAS unsigned*)(lds + (bufoff) + ldsw + _i * 8192), 16, 0, 0); } while (0)
; #define PG8_LDA(dst, b, h) do { _Pragma("unroll") for (int m = 0; m < 4; ++m) _Pragma("unroll") for (int k = 0; k < 2; ++k) dst[m][k] = *(const LAS bf16x8*)(lds + PG8_SA(b, h) + aoff + m * 2048 + k * 1024); } while (0)
; #define PG8_LDB(dst, b, h) do { _Pragma("unroll") for (int n = 0; n < 2; ++n) _Pragma("unroll") for (int k = 0; k < 2; ++k) dst[n][k] = *(const LAS bf16x8*)(lds + PG8_SB(b, h) + boff + n * 2048 + k * 1024); } while (0)
; #define PG8_WAIT_V(n) asm volatile("s_waitcnt vmcnt(" #n ")" ::: "memory")
; #define PG8_WAIT_L(n) asm volatile("s_waitcnt lgkmcnt(" #n ")" ::: "memory")
; #define PG8_BAR __builtin_amdgcn_s_barrier()
; #define PG8_SCHED __builtin_amdgcn_sched_barrier(0)
; template <bool F16, class Sched, class Epi>
; __device__ __forceinline__ void gemm_phase(LAS unsigned char* lds, const Gemm g, const Sched& S, const Epi& E, int wave_s) {
;     ...
;             const char* a2 = last ? nA : cA + (size_t)(t + 2) * kstep; const char* b2 = last ? nB : cB + (size_t)(t + 2) * kstep;
;             const char* a3 = a2 + kstep; const char* b3 = b2 + kstep;
;             PG8_LDB(B0, 0, 0); PG8_LDB(B1, 0, 1); PG8_SCHED; PG8_LDA(At, 0, 0); PG8_STAGE(PG8_SA(1, 1), a1 + hstepA, voffA);
;             PG8_WAIT_V(8); PG8_WAIT_L(0); PG8_BAR; PG8_MMA(0, 0, At, B0); PG8_MMA(0, 1, At, B1); PG8_BAR; PG8_SCHED;
;             PG8_LDA(At, 0, 1); PG8_STAGE(PG8_SB(0, 0), b2, voffB); PG8_STAGE(PG8_SB(0, 1), b2 + hstepB, voffB); PG8_STAGE(PG8_SA(0, 0), a2, voffA);
;             PG8_WAIT_V(8); PG8_WAIT_L(0); PG8_BAR; PG8_MMA(1, 0, At, B0); PG8_MMA(1, 1, At, B1); PG8_BAR; PG8_SCHED;
.LBB0_234:
	s_add_i32 s60, 0, 0x10000
	s_add_i32 s62, 0, 0x14000
	v_add_u32_e32 v150, s60, v163
	v_add_u32_e32 v170, s62, v163
	ds_read_b128 v[138:141], v150
	ds_read_b128 v[142:145], v150 offset:1024
	ds_read_b128 v[146:149], v150 offset:2048
	ds_read_b128 v[150:153], v150 offset:3072
	ds_read_b128 v[154:157], v170
	ds_read_b128 v[158:161], v170 offset:1024
	ds_read_b128 v[166:169], v170 offset:2048
	ds_read_b128 v[170:173], v170 offset:3072
	s_add_i32 m0, s41, 0xc000
	ds_read_b128 v[178:181], v165
	ds_read_b128 v[182:185], v165 offset:1024
	ds_read_b128 v[186:189], v165 offset:2048
	ds_read_b128 v[190:193], v165 offset:3072
	ds_read_b128 v[208:211], v165 offset:4096
	ds_read_b128 v[212:215], v165 offset:5120
	ds_read_b128 v[216:219], v165 offset:6144
	ds_read_b128 v[220:223], v165 offset:7168
	global_load_lds_dwordx4 v134, s[26:27]
	s_add_i32 m0, s41, 0xe000
	s_nop 0
	global_load_lds_dwordx4 v136, s[26:27]
	s_waitcnt vmcnt(8)
	s_waitcnt lgkmcnt(0)
	s_barrier
	s_setprio 1
	s_waitcnt lgkmcnt(0)
	v_mfma_f32_16x16x32_bf16 v[124:127], v[138:141], v[178:181], v[124:127]
	v_mfma_f32_16x16x32_bf16 v[120:123], v[146:149], v[178:181], v[120:123]
	v_mfma_f32_16x16x32_bf16 v[108:111], v[138:141], v[186:189], v[108:111]
	v_mfma_f32_16x16x32_bf16 v[104:107], v[146:149], v[186:189], v[104:107]
	v_mfma_f32_16x16x32_bf16 v[96:99], v[138:141], v[208:211], v[96:99]
	v_mfma_f32_16x16x32_bf16 v[92:95], v[146:149], v[208:211], v[92:95]
	v_mfma_f32_16x16x32_bf16 v[84:87], v[138:141], v[216:219], v[84:87]
	v_mfma_f32_16x16x32_bf16 v[76:79], v[146:149], v[216:219], v[76:79]
	v_mfma_f32_16x16x32_bf16 v[124:127], v[142:145], v[182:185], v[124:127]
	v_mfma_f32_16x16x32_bf16 v[120:123], v[150:153], v[182:185], v[120:123]
	v_mfma_f32_16x16x32_bf16 v[108:111], v[142:145], v[190:193], v[108:111]
	v_mfma_f32_16x16x32_bf16 v[104:107], v[150:153], v[190:193], v[104:107]
	v_mfma_f32_16x16x32_bf16 v[96:99], v[142:145], v[212:215], v[96:99]
	v_mfma_f32_16x16x32_bf16 v[92:95], v[150:153], v[212:215], v[92:95]
	v_mfma_f32_16x16x32_bf16 v[84:87], v[142:145], v[220:223], v[84:87]
	v_mfma_f32_16x16x32_bf16 v[76:79], v[150:153], v[220:223], v[76:79]
	s_setprio 0
	s_setprio 1
	v_mfma_f32_16x16x32_bf16 v[116:119], v[154:157], v[178:181], v[116:119]
	v_mfma_f32_16x16x32_bf16 v[112:115], v[166:169], v[178:181], v[112:115]
	v_mfma_f32_16x16x32_bf16 v[100:103], v[154:157], v[186:189], v[100:103]
	v_mfma_f32_16x16x32_bf16 v[88:91], v[166:169], v[186:189], v[88:91]
	v_mfma_f32_16x16x32_bf16 v[80:83], v[154:157], v[208:211], v[80:83]
	v_mfma_f32_16x16x32_bf16 v[72:75], v[166:169], v[208:211], v[72:75]
	v_mfma_f32_16x16x32_bf16 v[68:71], v[154:157], v[216:219], v[68:71]
	v_mfma_f32_16x16x32_bf16 v[64:67], v[166:169], v[216:219], v[64:67]
	v_mfma_f32_16x16x32_bf16 v[116:119], v[158:161], v[182:185], v[116:119]
	v_mfma_f32_16x16x32_bf16 v[112:115], v[170:173], v[182:185], v[112:115]
	v_mfma_f32_16x16x32_bf16 v[100:103], v[158:161], v[190:193], v[100:103]
	v_mfma_f32_16x16x32_bf16 v[88:91], v[170:173], v[190:193], v[88:91]
	v_mfma_f32_16x16x32_bf16 v[80:83], v[158:161], v[212:215], v[80:83]
	v_mfma_f32_16x16x32_bf16 v[72:75], v[170:173], v[212:215], v[72:75]
	v_mfma_f32_16x16x32_bf16 v[68:71], v[158:161], v[220:223], v[68:71]
	v_mfma_f32_16x16x32_bf16 v[64:67], v[170:173], v[220:223], v[64:67]
	s_setprio 0
	s_barrier
	s_add_u32 s28, s26, 0xfff80080
	s_addc_u32 s29, s27, -1
	s_cmp_eq_u32 s59, 4
	s_cselect_b32 s31, s13, s29
	s_cselect_b32 s30, s12, s28
	s_cselect_b32 s29, s0, s58
	s_cselect_b32 s28, s1, s53
	s_add_i32 s60, s60, s39
	v_lshl_add_u64 v[174:175], s[28:29], 0, v[176:177]
	s_mov_b32 m0, s60
	ds_read_b128 v[178:181], v165 offset:16384
	ds_read_b128 v[182:185], v165 offset:17408
	ds_read_b128 v[186:189], v165 offset:18432
	ds_read_b128 v[190:193], v165 offset:19456
	ds_read_b128 v[208:211], v165 offset:20480
	ds_read_b128 v[212:215], v165 offset:21504
	ds_read_b128 v[216:219], v165 offset:22528
	ds_read_b128 v[220:223], v165 offset:23552
	global_load_lds_dwordx4 v[174:175], off
	s_add_i32 m0, s60, 0x2000
	s_add_u32 s60, s28, 0x20000
	v_lshl_add_u64 v[194:195], s[28:29], 0, v[128:129]
	s_addc_u32 s61, s29, 0
	s_add_i32 s62, s62, s39
	global_load_lds_dwordx4 v[194:195], off
	v_lshl_add_u64 v[198:199], s[60:61], 0, v[176:177]
	s_mov_b32 m0, s62
	v_lshl_add_u64 v[200:201], s[30:31], 0, v[130:131]
	global_load_lds_dwordx4 v[198:199], off
	v_lshl_add_u64 v[198:199], s[60:61], 0, v[128:129]
	s_add_i32 m0, s62, 0x2000
	s_nop 0
	global_load_lds_dwordx4 v[198:199], off
	v_lshl_add_u64 v[198:199], s[30:31], 0, v[132:133]
	s_mov_b32 m0, s41
	s_nop 0
	global_load_lds_dwordx4 v[198:199], off
	s_mov_b32 m0, s42
	s_nop 0
	global_load_lds_dwordx4 v[200:201], off
	s_add_u32 s30, s30, 0x80000
	s_addc_u32 s31, s31, 0
	s_waitcnt vmcnt(8)
	s_waitcnt lgkmcnt(0)
	s_barrier
; #define PG8_STAGE(bufoff, gbase, voff) do { _Pragma("unroll") for (int _i = 0; _i < 2; ++_i) \
;         __builtin_amdgcn_global_load_lds((const unsigned*)((const char*)(gbase) + (voff)[_i]), (LAS unsigned*)(lds + (bufoff) + ldsw + _i * 8192), 16, 0, 0); } while (0)
; #define PG8_LDA(dst, b, h) do { _Pragma("unroll") for (int m = 0; m < 4; ++m) _Pragma("unroll") for (int k = 0; k < 2; ++k) dst[m][k] = *(const LAS bf16x8*)(lds + PG8_SA(b, h) + aoff + m * 2048 + k * 1024); } while (0)
; #define PG8_LDB(dst, b, h) do { _Pragma("unroll") for (int n = 0; n < 2; ++n) _Pragma("unroll") for (int k = 0; k < 2; ++k) dst[n][k] = *(const LAS bf16x8*)(lds + PG8_SB(b, h) + boff + n * 2048 + k * 1024); } while (0)
; #define PG8_WAIT_V(n) asm volatile("s_waitcnt vmcnt(" #n ")" ::: "memory")
; #define PG8_WAIT_L(n) asm volatile("s_waitcnt lgkmcnt(" #n ")" ::: "memory")
; #define PG8_BAR __builtin_amdgcn_s_barrier()
; #define PG8_SCHED __builtin_amdgcn_sched_barrier(0)
; template <bool F16, class Sched, class Epi>
; __device__ __forceinline__ void gemm_phase(LAS unsigned char* lds, const Gemm g, const Sched& S, const Epi& E, int wave_s) {
;     ...
;             PG8_WAIT_V(8); PG8_WAIT_L(0); PG8_BAR; PG8_MMA(1, 0, At, B0); PG8_MMA(1, 1, At, B1); PG8_BAR; PG8_SCHED;
;             PG8_LDB(B0, 1, 0); PG8_LDB(B1, 1, 1); PG8_SCHED; PG8_LDA(At, 1, 0); PG8_STAGE(PG8_SA(0, 1), a2 + hstepA, voffA);
;             PG8_WAIT_V(8); PG8_WAIT_L(0); PG8_BAR; PG8_MMA(0, 0, At, B0); PG8_MMA(0, 1, At, B1); PG8_BAR; PG8_SCHED;
	s_setprio 1
	s_waitcnt lgkmcnt(0)
	v_mfma_f32_16x16x32_bf16 v[60:63], v[138:141], v[178:181], v[60:63]
	v_mfma_f32_16x16x32_bf16 v[56:59], v[146:149], v[178:181], v[56:59]
	v_mfma_f32_16x16x32_bf16 v[52:55], v[138:141], v[186:189], v[52:55]
	v_mfma_f32_16x16x32_bf16 v[44:47], v[146:149], v[186:189], v[44:47]
	v_mfma_f32_16x16x32_bf16 v[36:39], v[138:141], v[208:211], v[36:39]
	v_mfma_f32_16x16x32_bf16 v[28:31], v[146:149], v[208:211], v[28:31]
	v_mfma_f32_16x16x32_bf16 v[20:23], v[138:141], v[216:219], v[20:23]
	v_mfma_f32_16x16x32_bf16 v[12:15], v[146:149], v[216:219], v[12:15]
	v_mfma_f32_16x16x32_bf16 v[60:63], v[142:145], v[182:185], v[60:63]
	v_mfma_f32_16x16x32_bf16 v[56:59], v[150:153], v[182:185], v[56:59]
	v_mfma_f32_16x16x32_bf16 v[52:55], v[142:145], v[190:193], v[52:55]
	v_mfma_f32_16x16x32_bf16 v[44:47], v[150:153], v[190:193], v[44:47]
	v_mfma_f32_16x16x32_bf16 v[36:39], v[142:145], v[212:215], v[36:39]
	v_mfma_f32_16x16x32_bf16 v[28:31], v[150:153], v[212:215], v[28:31]
	v_mfma_f32_16x16x32_bf16 v[20:23], v[142:145], v[220:223], v[20:23]
	v_mfma_f32_16x16x32_bf16 v[12:15], v[150:153], v[220:223], v[12:15]
	s_setprio 0
	s_setprio 1
	v_mfma_f32_16x16x32_bf16 v[48:51], v[154:157], v[178:181], v[48:51]
	v_mfma_f32_16x16x32_bf16 v[40:43], v[166:169], v[178:181], v[40:43]
	v_mfma_f32_16x16x32_bf16 v[32:35], v[154:157], v[186:189], v[32:35]
	v_mfma_f32_16x16x32_bf16 v[24:27], v[166:169], v[186:189], v[24:27]
	v_mfma_f32_16x16x32_bf16 v[16:19], v[154:157], v[208:211], v[16:19]
	v_mfma_f32_16x16x32_bf16 v[8:11], v[166:169], v[208:211], v[8:11]
	v_mfma_f32_16x16x32_bf16 v[4:7], v[154:157], v[216:219], v[4:7]
	v_mfma_f32_16x16x32_bf16 v[0:3], v[166:169], v[216:219], v[0:3]
	v_mfma_f32_16x16x32_bf16 v[48:51], v[158:161], v[182:185], v[48:51]
	v_mfma_f32_16x16x32_bf16 v[40:43], v[170:173], v[182:185], v[40:43]
	v_mfma_f32_16x16x32_bf16 v[32:35], v[158:161], v[190:193], v[32:35]
	v_mfma_f32_16x16x32_bf16 v[24:27], v[170:173], v[190:193], v[24:27]
	v_mfma_f32_16x16x32_bf16 v[16:19], v[158:161], v[212:215], v[16:19]
	v_mfma_f32_16x16x32_bf16 v[8:11], v[170:173], v[212:215], v[8:11]
	v_mfma_f32_16x16x32_bf16 v[4:7], v[158:161], v[220:223], v[4:7]
	v_mfma_f32_16x16x32_bf16 v[0:3], v[170:173], v[220:223], v[0:3]
	s_setprio 0
	s_barrier
	s_add_i32 s60, 0, 0x18000
	s_add_i32 s61, 0, 0x1c000
	v_add_u32_e32 v150, s60, v163
	v_add_u32_e32 v170, s61, v163
	ds_read_b128 v[138:141], v150
	ds_read_b128 v[142:145], v150 offset:1024
	ds_read_b128 v[146:149], v150 offset:2048
	ds_read_b128 v[150:153], v150 offset:3072
	ds_read_b128 v[154:157], v170
	ds_read_b128 v[158:161], v170 offset:1024
	ds_read_b128 v[166:169], v170 offset:2048
	ds_read_b128 v[170:173], v170 offset:3072
	s_mov_b32 m0, s43
	ds_read_b128 v[178:181], v165 offset:32768
	ds_read_b128 v[182:185], v165 offset:33792
	ds_read_b128 v[186:189], v165 offset:34816
	ds_read_b128 v[190:193], v165 offset:35840
	ds_read_b128 v[208:211], v165 offset:36864
	ds_read_b128 v[212:215], v165 offset:37888
	ds_read_b128 v[216:219], v165 offset:38912
	ds_read_b128 v[220:223], v165 offset:39936
	global_load_lds_dwordx4 v132, s[30:31]
	s_mov_b32 m0, s44
	s_nop 0
	global_load_lds_dwordx4 v130, s[30:31]
	s_waitcnt vmcnt(8)
	s_waitcnt lgkmcnt(0)
	s_barrier
	s_setprio 1
	s_waitcnt lgkmcnt(0)
	v_mfma_f32_16x16x32_bf16 v[124:127], v[138:141], v[178:181], v[124:127]
	v_mfma_f32_16x16x32_bf16 v[120:123], v[146:149], v[178:181], v[120:123]
	v_mfma_f32_16x16x32_bf16 v[108:111], v[138:141], v[186:189], v[108:111]
	v_mfma_f32_16x16x32_bf16 v[104:107], v[146:149], v[186:189], v[104:107]
	v_mfma_f32_16x16x32_bf16 v[96:99], v[138:141], v[208:211], v[96:99]
	v_mfma_f32_16x16x32_bf16 v[92:95], v[146:149], v[208:211], v[92:95]
	v_mfma_f32_16x16x32_bf16 v[84:87], v[138:141], v[216:219], v[84:87]
	v_mfma_f32_16x16x32_bf16 v[76:79], v[146:149], v[216:219], v[76:79]
	v_mfma_f32_16x16x32_bf16 v[124:127], v[142:145], v[182:185], v[124:127]
	v_mfma_f32_16x16x32_bf16 v[120:123], v[150:153], v[182:185], v[120:123]
	v_mfma_f32_16x16x32_bf16 v[108:111], v[142:145], v[190:193], v[108:111]
	v_mfma_f32_16x16x32_bf16 v[104:107], v[150:153], v[190:193], v[104:107]
	v_mfma_f32_16x16x32_bf16 v[96:99], v[142:145], v[212:215], v[96:99]
	v_mfma_f32_16x16x32_bf16 v[92:95], v[150:153], v[212:215], v[92:95]
	v_mfma_f32_16x16x32_bf16 v[84:87], v[142:145], v[220:223], v[84:87]
	v_mfma_f32_16x16x32_bf16 v[76:79], v[150:153], v[220:223], v[76:79]
	s_setprio 0
	s_setprio 1
	v_mfma_f32_16x16x32_bf16 v[116:119], v[154:157], v[178:181], v[116:119]
	v_mfma_f32_16x16x32_bf16 v[112:115], v[166:169], v[178:181], v[112:115]
	v_mfma_f32_16x16x32_bf16 v[100:103], v[154:157], v[186:189], v[100:103]
	v_mfma_f32_16x16x32_bf16 v[88:91], v[166:169], v[186:189], v[88:91]
	v_mfma_f32_16x16x32_bf16 v[80:83], v[154:157], v[208:211], v[80:83]
	v_mfma_f32_16x16x32_bf16 v[72:75], v[166:169], v[208:211], v[72:75]
	v_mfma_f32_16x16x32_bf16 v[68:71], v[154:157], v[216:219], v[68:71]
	v_mfma_f32_16x16x32_bf16 v[64:67], v[166:169], v[216:219], v[64:67]
	v_mfma_f32_16x16x32_bf16 v[116:119], v[158:161], v[182:185], v[116:119]
	v_mfma_f32_16x16x32_bf16 v[112:115], v[170:173], v[182:185], v[112:115]
	v_mfma_f32_16x16x32_bf16 v[100:103], v[158:161], v[190:193], v[100:103]
	v_mfma_f32_16x16x32_bf16 v[88:91], v[170:173], v[190:193], v[88:91]
	v_mfma_f32_16x16x32_bf16 v[80:83], v[158:161], v[212:215], v[80:83]
	v_mfma_f32_16x16x32_bf16 v[72:75], v[170:173], v[212:215], v[72:75]
	v_mfma_f32_16x16x32_bf16 v[68:71], v[158:161], v[220:223], v[68:71]
	v_mfma_f32_16x16x32_bf16 v[64:67], v[170:173], v[220:223], v[64:67]
	s_setprio 0
	s_barrier
; #define PG8_STAGE(bufoff, gbase, voff) do { _Pragma("unroll") for (int _i = 0; _i < 2; ++_i) \
;         __builtin_amdgcn_global_load_lds((const unsigned*)((const char*)(gbase) + (voff)[_i]), (LAS unsigned*)(lds + (bufoff) + ldsw + _i * 8192), 16, 0, 0); } while (0)
; #define PG8_LDA(dst, b, h) do { _Pragma("unroll") for (int m = 0; m < 4; ++m) _Pragma("unroll") for (int k = 0; k < 2; ++k) dst[m][k] = *(const LAS bf16x8*)(lds + PG8_SA(b, h) + aoff + m * 2048 + k * 1024); } while (0)
; #define PG8_WAIT_V(n) asm volatile("s_waitcnt vmcnt(" #n ")" ::: "memory")
; #define PG8_WAIT_L(n) asm volatile("s_waitcnt lgkmcnt(" #n ")" ::: "memory")
; #define PG8_BAR __builtin_amdgcn_s_barrier()
; #define PG8_SCHED __builtin_amdgcn_sched_barrier(0)
; template <bool F16, class Sched, class Epi>
; __device__ __forceinline__ void gemm_phase(LAS unsigned char* lds, const Gemm g, const Sched& S, const Epi& E, int wave_s) {
;     ...
;         for (int t = 0; t < nt; t += 2) {
;     ...
;             PG8_LDA(At, 1, 1); PG8_STAGE(PG8_SB(1, 0), b3, voffB); PG8_STAGE(PG8_SB(1, 1), b3 + hstepB, voffB); PG8_STAGE(PG8_SA(1, 0), a3, voffA);
;             PG8_WAIT_V(8); PG8_WAIT_L(0); PG8_BAR; PG8_MMA(1, 0, At, B0); PG8_MMA(1, 1, At, B1); PG8_BAR; PG8_SCHED;
	s_add_i32 s30, s60, s39
	v_lshl_add_u64 v[174:175], v[174:175], 0, s[54:55]
	s_mov_b32 m0, s30
	ds_read_b128 v[178:181], v165 offset:49152
	ds_read_b128 v[182:185], v165 offset:50176
	ds_read_b128 v[186:189], v165 offset:51200
	ds_read_b128 v[190:193], v165 offset:52224
	ds_read_b128 v[208:211], v165 offset:53248
	ds_read_b128 v[212:215], v165 offset:54272
	ds_read_b128 v[216:219], v165 offset:55296
	ds_read_b128 v[220:223], v165 offset:56320
	global_load_lds_dwordx4 v[174:175], off
	s_add_i32 m0, s30, 0x2000
	s_add_u32 s28, s28, 0x20080
	v_lshl_add_u64 v[174:175], v[194:195], 0, s[54:55]
	s_addc_u32 s29, s29, 0
	s_add_i32 s30, s61, s39
	global_load_lds_dwordx4 v[174:175], off
	v_lshl_add_u64 v[174:175], s[28:29], 0, v[176:177]
	s_mov_b32 m0, s30
	s_nop 0
	global_load_lds_dwordx4 v[174:175], off
	v_lshl_add_u64 v[174:175], s[28:29], 0, v[128:129]
	s_add_i32 m0, s30, 0x2000
	s_nop 0
	global_load_lds_dwordx4 v[174:175], off
	v_lshl_add_u64 v[174:175], v[198:199], 0, s[54:55]
	s_mov_b32 m0, s19
	s_nop 0
	global_load_lds_dwordx4 v[174:175], off
	v_lshl_add_u64 v[174:175], v[200:201], 0, s[54:55]
	s_mov_b32 m0, s45
	s_nop 0
	global_load_lds_dwordx4 v[174:175], off
	s_waitcnt vmcnt(8)
	s_waitcnt lgkmcnt(0)
	s_barrier
	s_setprio 1
	s_waitcnt lgkmcnt(0)
	v_mfma_f32_16x16x32_bf16 v[60:63], v[138:141], v[178:181], v[60:63]
	v_mfma_f32_16x16x32_bf16 v[56:59], v[146:149], v[178:181], v[56:59]
	v_mfma_f32_16x16x32_bf16 v[52:55], v[138:141], v[186:189], v[52:55]
	v_mfma_f32_16x16x32_bf16 v[44:47], v[146:149], v[186:189], v[44:47]
	v_mfma_f32_16x16x32_bf16 v[36:39], v[138:141], v[208:211], v[36:39]
	v_mfma_f32_16x16x32_bf16 v[28:31], v[146:149], v[208:211], v[28:31]
	v_mfma_f32_16x16x32_bf16 v[20:23], v[138:141], v[216:219], v[20:23]
	v_mfma_f32_16x16x32_bf16 v[12:15], v[146:149], v[216:219], v[12:15]
	v_mfma_f32_16x16x32_bf16 v[60:63], v[142:145], v[182:185], v[60:63]
	v_mfma_f32_16x16x32_bf16 v[56:59], v[150:153], v[182:185], v[56:59]
	v_mfma_f32_16x16x32_bf16 v[52:55], v[142:145], v[190:193], v[52:55]
	v_mfma_f32_16x16x32_bf16 v[44:47], v[150:153], v[190:193], v[44:47]
	v_mfma_f32_16x16x32_bf16 v[36:39], v[142:145], v[212:215], v[36:39]
	v_mfma_f32_16x16x32_bf16 v[28:31], v[150:153], v[212:215], v[28:31]
	v_mfma_f32_16x16x32_bf16 v[20:23], v[142:145], v[220:223], v[20:23]
	v_mfma_f32_16x16x32_bf16 v[12:15], v[150:153], v[220:223], v[12:15]
	s_setprio 0
	s_setprio 1
	v_mfma_f32_16x16x32_bf16 v[48:51], v[154:157], v[178:181], v[48:51]
	v_mfma_f32_16x16x32_bf16 v[40:43], v[166:169], v[178:181], v[40:43]
	v_mfma_f32_16x16x32_bf16 v[32:35], v[154:157], v[186:189], v[32:35]
	v_mfma_f32_16x16x32_bf16 v[24:27], v[166:169], v[186:189], v[24:27]
	v_mfma_f32_16x16x32_bf16 v[16:19], v[154:157], v[208:211], v[16:19]
	v_mfma_f32_16x16x32_bf16 v[8:11], v[166:169], v[208:211], v[8:11]
	v_mfma_f32_16x16x32_bf16 v[4:7], v[154:157], v[216:219], v[4:7]
	v_mfma_f32_16x16x32_bf16 v[0:3], v[166:169], v[216:219], v[0:3]
	v_mfma_f32_16x16x32_bf16 v[48:51], v[158:161], v[182:185], v[48:51]
	v_mfma_f32_16x16x32_bf16 v[40:43], v[170:173], v[182:185], v[40:43]
	v_mfma_f32_16x16x32_bf16 v[32:35], v[158:161], v[190:193], v[32:35]
	v_mfma_f32_16x16x32_bf16 v[24:27], v[170:173], v[190:193], v[24:27]
	v_mfma_f32_16x16x32_bf16 v[16:19], v[158:161], v[212:215], v[16:19]
	v_mfma_f32_16x16x32_bf16 v[8:11], v[170:173], v[212:215], v[8:11]
	v_mfma_f32_16x16x32_bf16 v[4:7], v[158:161], v[220:223], v[4:7]
	v_mfma_f32_16x16x32_bf16 v[0:3], v[170:173], v[220:223], v[0:3]
	s_add_i32 s59, s59, 2
	s_add_u32 s26, s26, 0x100
	s_addc_u32 s27, s27, 0
	s_add_u32 s53, s53, 0x100
	s_addc_u32 s58, s58, 0
	s_cmp_gt_u32 s59, 5
	s_setprio 0
	s_barrier
	s_cbranch_scc0 .LBB0_234
	s_and_b64 vcc, exec, s[10:11]
	s_cbranch_vccz .LBB0_237
	s_barrier

; #define PG8_STAGE(bufoff, gbase, voff) do { _Pragma("unroll") for (int _i = 0; _i < 2; ++_i) \
;         __builtin_amdgcn_global_load_lds((const unsigned*)((const char*)(gbase) + (voff)[_i]), (LAS unsigned*)(lds + (bufoff) + ldsw + _i * 8192), 16, 0, 0); } while (0)
; #define PG8_LDA(dst, b, h) do { _Pragma("unroll") for (int m = 0; m < 4; ++m) _Pragma("unroll") for (int k = 0; k < 2; ++k) dst[m][k] = *(const LAS bf16x8*)(lds + PG8_SA(b, h) + aoff + m * 2048 + k * 1024); } while (0)
; #define PG8_LDB(dst, b, h) do { _Pragma("unroll") for (int n = 0; n < 2; ++n) _Pragma("unroll") for (int k = 0; k < 2; ++k) dst[n][k] = *(const LAS bf16x8*)(lds + PG8_SB(b, h) + boff + n * 2048 + k * 1024); } while (0)
; #define PG8_WAIT_V(n) asm volatile("s_waitcnt vmcnt(" #n ")" ::: "memory")
; #define PG8_WAIT_L(n) asm volatile("s_waitcnt lgkmcnt(" #n ")" ::: "memory")
; #define PG8_BAR __builtin_amdgcn_s_barrier()
; #define PG8_SCHED __builtin_amdgcn_sched_barrier(0)
; template <bool F16, class Sched, class Epi>
; __device__ __forceinline__ void gemm_phase(LAS unsigned char* lds, const Gemm g, const Sched& S, const Epi& E, int wave_s) {
;     ...
;             const char* a2 = last ? nA : cA + (size_t)(t + 2) * kstep; const char* b2 = last ? nB : cB + (size_t)(t + 2) * kstep;
;             const char* a3 = a2 + kstep; const char* b3 = b2 + kstep;
;             PG8_LDB(B0, 0, 0); PG8_LDB(B1, 0, 1); PG8_SCHED; PG8_LDA(At, 0, 0); PG8_STAGE(PG8_SA(1, 1), a1 + hstepA, voffA);
;             PG8_WAIT_V(8); PG8_WAIT_L(0); PG8_BAR; PG8_MMA(0, 0, At, B0); PG8_MMA(0, 1, At, B1); PG8_BAR; PG8_SCHED;
;             PG8_LDA(At, 0, 1); PG8_STAGE(PG8_SB(0, 0), b2, voffB); PG8_STAGE(PG8_SB(0, 1), b2 + hstepB, voffB); PG8_STAGE(PG8_SA(0, 0), a2, voffA);
;             PG8_WAIT_V(8); PG8_WAIT_L(0); PG8_BAR; PG8_MMA(1, 0, At, B0); PG8_MMA(1, 1, At, B1); PG8_BAR; PG8_SCHED;
.LBB0_304:
	s_add_i32 s71, 0, 0x10000
	s_add_i32 s74, 0, 0x14000
	v_add_u32_e32 v150, s71, v162
	v_add_u32_e32 v158, s74, v162
	ds_read_b128 v[138:141], v150
	ds_read_b128 v[142:145], v150 offset:1024
	ds_read_b128 v[146:149], v150 offset:2048
	ds_read_b128 v[150:153], v150 offset:3072
	ds_read_b128 v[154:157], v158
	ds_read_b128 v[166:169], v158 offset:1024
	ds_read_b128 v[170:173], v158 offset:2048
	ds_read_b128 v[178:181], v158 offset:3072
	s_add_i32 m0, s49, 0xc000
	ds_read_b128 v[182:185], v164
	ds_read_b128 v[186:189], v164 offset:1024
	ds_read_b128 v[190:193], v164 offset:2048
	ds_read_b128 v[208:211], v164 offset:3072
	ds_read_b128 v[212:215], v164 offset:4096
	ds_read_b128 v[216:219], v164 offset:5120
	ds_read_b128 v[220:223], v164 offset:6144
	ds_read_b128 v[224:227], v164 offset:7168
	global_load_lds_dwordx4 v134, s[2:3]
	s_add_i32 m0, s49, 0xe000
	s_nop 0
	global_load_lds_dwordx4 v136, s[2:3]
	s_waitcnt vmcnt(8)
	s_waitcnt lgkmcnt(0)
	s_barrier
	s_setprio 1
	s_waitcnt lgkmcnt(0)
	v_mfma_f32_16x16x32_bf16 v[124:127], v[138:141], v[182:185], v[124:127]
	v_mfma_f32_16x16x32_bf16 v[120:123], v[146:149], v[182:185], v[120:123]
	v_mfma_f32_16x16x32_bf16 v[108:111], v[138:141], v[190:193], v[108:111]
	v_mfma_f32_16x16x32_bf16 v[104:107], v[146:149], v[190:193], v[104:107]
	v_mfma_f32_16x16x32_bf16 v[92:95], v[138:141], v[212:215], v[92:95]
	v_mfma_f32_16x16x32_bf16 v[88:91], v[146:149], v[212:215], v[88:91]
	v_mfma_f32_16x16x32_bf16 v[76:79], v[138:141], v[220:223], v[76:79]
	v_mfma_f32_16x16x32_bf16 v[72:75], v[146:149], v[220:223], v[72:75]
	v_mfma_f32_16x16x32_bf16 v[124:127], v[142:145], v[186:189], v[124:127]
	v_mfma_f32_16x16x32_bf16 v[120:123], v[150:153], v[186:189], v[120:123]
	v_mfma_f32_16x16x32_bf16 v[108:111], v[142:145], v[208:211], v[108:111]
	v_mfma_f32_16x16x32_bf16 v[104:107], v[150:153], v[208:211], v[104:107]
	v_mfma_f32_16x16x32_bf16 v[92:95], v[142:145], v[216:219], v[92:95]
	v_mfma_f32_16x16x32_bf16 v[88:91], v[150:153], v[216:219], v[88:91]
	v_mfma_f32_16x16x32_bf16 v[76:79], v[142:145], v[224:227], v[76:79]
	v_mfma_f32_16x16x32_bf16 v[72:75], v[150:153], v[224:227], v[72:75]
	s_setprio 0
	s_setprio 1
	v_mfma_f32_16x16x32_bf16 v[116:119], v[154:157], v[182:185], v[116:119]
	v_mfma_f32_16x16x32_bf16 v[112:115], v[170:173], v[182:185], v[112:115]
	v_mfma_f32_16x16x32_bf16 v[100:103], v[154:157], v[190:193], v[100:103]
	v_mfma_f32_16x16x32_bf16 v[96:99], v[170:173], v[190:193], v[96:99]
	v_mfma_f32_16x16x32_bf16 v[84:87], v[154:157], v[212:215], v[84:87]
	v_mfma_f32_16x16x32_bf16 v[80:83], v[170:173], v[212:215], v[80:83]
	v_mfma_f32_16x16x32_bf16 v[68:71], v[154:157], v[220:223], v[68:71]
	v_mfma_f32_16x16x32_bf16 v[64:67], v[170:173], v[220:223], v[64:67]
	v_mfma_f32_16x16x32_bf16 v[116:119], v[166:169], v[186:189], v[116:119]
	v_mfma_f32_16x16x32_bf16 v[112:115], v[178:181], v[186:189], v[112:115]
	v_mfma_f32_16x16x32_bf16 v[100:103], v[166:169], v[208:211], v[100:103]
	v_mfma_f32_16x16x32_bf16 v[96:99], v[178:181], v[208:211], v[96:99]
	v_mfma_f32_16x16x32_bf16 v[84:87], v[166:169], v[216:219], v[84:87]
	v_mfma_f32_16x16x32_bf16 v[80:83], v[178:181], v[216:219], v[80:83]
	v_mfma_f32_16x16x32_bf16 v[68:71], v[166:169], v[224:227], v[68:71]
	v_mfma_f32_16x16x32_bf16 v[64:67], v[178:181], v[224:227], v[64:67]
	s_setprio 0
	s_barrier
	s_add_u32 s4, s2, 0xfff80080
	s_addc_u32 s5, s3, -1
	s_cmp_eq_u32 s70, 28
	s_cselect_b32 s39, s62, s5
	s_cselect_b32 s38, s63, s4
	s_cselect_b32 s5, s64, s69
	s_cselect_b32 s4, s65, s68
	s_add_i32 s71, s71, s46
	v_lshl_add_u64 v[158:159], s[4:5], 0, v[176:177]
	s_mov_b32 m0, s71
	ds_read_b128 v[182:185], v164 offset:16384
	ds_read_b128 v[186:189], v164 offset:17408
	ds_read_b128 v[190:193], v164 offset:18432
	ds_read_b128 v[208:211], v164 offset:19456
	ds_read_b128 v[212:215], v164 offset:20480
	ds_read_b128 v[216:219], v164 offset:21504
	ds_read_b128 v[220:223], v164 offset:22528
	ds_read_b128 v[224:227], v164 offset:23552
	global_load_lds_dwordx4 v[158:159], off
	s_add_i32 m0, s71, 0x2000
	s_add_u32 s72, s4, 0x80000
	v_lshl_add_u64 v[174:175], s[4:5], 0, v[128:129]
	s_addc_u32 s73, s5, 0
	s_add_i32 s71, s74, s46
	global_load_lds_dwordx4 v[174:175], off
	v_lshl_add_u64 v[194:195], s[72:73], 0, v[176:177]
	s_mov_b32 m0, s71
	v_lshl_add_u64 v[198:199], s[38:39], 0, v[130:131]
	global_load_lds_dwordx4 v[194:195], off
	v_lshl_add_u64 v[194:195], s[72:73], 0, v[128:129]
	s_add_i32 m0, s71, 0x2000
	s_nop 0
	global_load_lds_dwordx4 v[194:195], off
	v_lshl_add_u64 v[194:195], s[38:39], 0, v[132:133]
	s_mov_b32 m0, s49
	s_nop 0
	global_load_lds_dwordx4 v[194:195], off
	s_mov_b32 m0, s52
	s_nop 0
	global_load_lds_dwordx4 v[198:199], off
	s_add_u32 s38, s38, 0x80000
	s_addc_u32 s39, s39, 0
	s_waitcnt vmcnt(8)
	s_waitcnt lgkmcnt(0)
	s_barrier
; #define PG8_STAGE(bufoff, gbase, voff) do { _Pragma("unroll") for (int _i = 0; _i < 2; ++_i) \
;         __builtin_amdgcn_global_load_lds((const unsigned*)((const char*)(gbase) + (voff)[_i]), (LAS unsigned*)(lds + (bufoff) + ldsw + _i * 8192), 16, 0, 0); } while (0)
; #define PG8_LDA(dst, b, h) do { _Pragma("unroll") for (int m = 0; m < 4; ++m) _Pragma("unroll") for (int k = 0; k < 2; ++k) dst[m][k] = *(const LAS bf16x8*)(lds + PG8_SA(b, h) + aoff + m * 2048 + k * 1024); } while (0)
; #define PG8_LDB(dst, b, h) do { _Pragma("unroll") for (int n = 0; n < 2; ++n) _Pragma("unroll") for (int k = 0; k < 2; ++k) dst[n][k] = *(const LAS bf16x8*)(lds + PG8_SB(b, h) + boff + n * 2048 + k * 1024); } while (0)
; #define PG8_WAIT_V(n) asm volatile("s_waitcnt vmcnt(" #n ")" ::: "memory")
; #define PG8_WAIT_L(n) asm volatile("s_waitcnt lgkmcnt(" #n ")" ::: "memory")
; #define PG8_BAR __builtin_amdgcn_s_barrier()
; #define PG8_SCHED __builtin_amdgcn_sched_barrier(0)
; template <bool F16, class Sched, class Epi>
; __device__ __forceinline__ void gemm_phase(LAS unsigned char* lds, const Gemm g, const Sched& S, const Epi& E, int wave_s) {
;     ...
;             PG8_WAIT_V(8); PG8_WAIT_L(0); PG8_BAR; PG8_MMA(1, 0, At, B0); PG8_MMA(1, 1, At, B1); PG8_BAR; PG8_SCHED;
;             PG8_LDB(B0, 1, 0); PG8_LDB(B1, 1, 1); PG8_SCHED; PG8_LDA(At, 1, 0); PG8_STAGE(PG8_SA(0, 1), a2 + hstepA, voffA);
;             PG8_WAIT_V(8); PG8_WAIT_L(0); PG8_BAR; PG8_MMA(0, 0, At, B0); PG8_MMA(0, 1, At, B1); PG8_BAR; PG8_SCHED;
	s_setprio 1
	s_waitcnt lgkmcnt(0)
	v_mfma_f32_16x16x32_bf16 v[60:63], v[138:141], v[182:185], v[60:63]
	v_mfma_f32_16x16x32_bf16 v[56:59], v[146:149], v[182:185], v[56:59]
	v_mfma_f32_16x16x32_bf16 v[44:47], v[138:141], v[190:193], v[44:47]
	v_mfma_f32_16x16x32_bf16 v[40:43], v[146:149], v[190:193], v[40:43]
	v_mfma_f32_16x16x32_bf16 v[28:31], v[138:141], v[212:215], v[28:31]
	v_mfma_f32_16x16x32_bf16 v[24:27], v[146:149], v[212:215], v[24:27]
	v_mfma_f32_16x16x32_bf16 v[12:15], v[138:141], v[220:223], v[12:15]
	v_mfma_f32_16x16x32_bf16 v[8:11], v[146:149], v[220:223], v[8:11]
	v_mfma_f32_16x16x32_bf16 v[60:63], v[142:145], v[186:189], v[60:63]
	v_mfma_f32_16x16x32_bf16 v[56:59], v[150:153], v[186:189], v[56:59]
	v_mfma_f32_16x16x32_bf16 v[44:47], v[142:145], v[208:211], v[44:47]
	v_mfma_f32_16x16x32_bf16 v[40:43], v[150:153], v[208:211], v[40:43]
	v_mfma_f32_16x16x32_bf16 v[28:31], v[142:145], v[216:219], v[28:31]
	v_mfma_f32_16x16x32_bf16 v[24:27], v[150:153], v[216:219], v[24:27]
	v_mfma_f32_16x16x32_bf16 v[12:15], v[142:145], v[224:227], v[12:15]
	v_mfma_f32_16x16x32_bf16 v[8:11], v[150:153], v[224:227], v[8:11]
	s_setprio 0
	s_setprio 1
	v_mfma_f32_16x16x32_bf16 v[52:55], v[154:157], v[182:185], v[52:55]
	v_mfma_f32_16x16x32_bf16 v[48:51], v[170:173], v[182:185], v[48:51]
	v_mfma_f32_16x16x32_bf16 v[36:39], v[154:157], v[190:193], v[36:39]
	v_mfma_f32_16x16x32_bf16 v[32:35], v[170:173], v[190:193], v[32:35]
	v_mfma_f32_16x16x32_bf16 v[20:23], v[154:157], v[212:215], v[20:23]
	v_mfma_f32_16x16x32_bf16 v[16:19], v[170:173], v[212:215], v[16:19]
	v_mfma_f32_16x16x32_bf16 v[4:7], v[154:157], v[220:223], v[4:7]
	v_mfma_f32_16x16x32_bf16 v[0:3], v[170:173], v[220:223], v[0:3]
	v_mfma_f32_16x16x32_bf16 v[52:55], v[166:169], v[186:189], v[52:55]
	v_mfma_f32_16x16x32_bf16 v[48:51], v[178:181], v[186:189], v[48:51]
	v_mfma_f32_16x16x32_bf16 v[36:39], v[166:169], v[208:211], v[36:39]
	v_mfma_f32_16x16x32_bf16 v[32:35], v[178:181], v[208:211], v[32:35]
	v_mfma_f32_16x16x32_bf16 v[20:23], v[166:169], v[216:219], v[20:23]
	v_mfma_f32_16x16x32_bf16 v[16:19], v[178:181], v[216:219], v[16:19]
	v_mfma_f32_16x16x32_bf16 v[4:7], v[166:169], v[224:227], v[4:7]
	v_mfma_f32_16x16x32_bf16 v[0:3], v[178:181], v[224:227], v[0:3]
	s_setprio 0
	s_barrier
	s_add_i32 s71, 0, 0x18000
	s_add_i32 s72, 0, 0x1c000
	v_add_u32_e32 v150, s71, v162
	v_add_u32_e32 v160, s72, v162
	ds_read_b128 v[138:141], v150
	ds_read_b128 v[142:145], v150 offset:1024
	ds_read_b128 v[146:149], v150 offset:2048
	ds_read_b128 v[150:153], v150 offset:3072
	ds_read_b128 v[154:157], v160
	ds_read_b128 v[166:169], v160 offset:1024
	ds_read_b128 v[170:173], v160 offset:2048
	ds_read_b128 v[178:181], v160 offset:3072
	s_mov_b32 m0, s53
	ds_read_b128 v[182:185], v164 offset:32768
	ds_read_b128 v[186:189], v164 offset:33792
	ds_read_b128 v[190:193], v164 offset:34816
	ds_read_b128 v[208:211], v164 offset:35840
	ds_read_b128 v[212:215], v164 offset:36864
	ds_read_b128 v[216:219], v164 offset:37888
	ds_read_b128 v[220:223], v164 offset:38912
	ds_read_b128 v[224:227], v164 offset:39936
	global_load_lds_dwordx4 v132, s[38:39]
	s_mov_b32 m0, s58
	s_nop 0
	global_load_lds_dwordx4 v130, s[38:39]
	s_waitcnt vmcnt(8)
	s_waitcnt lgkmcnt(0)
	s_barrier
	s_setprio 1
	s_waitcnt lgkmcnt(0)
	v_mfma_f32_16x16x32_bf16 v[124:127], v[138:141], v[182:185], v[124:127]
	v_mfma_f32_16x16x32_bf16 v[120:123], v[146:149], v[182:185], v[120:123]
	v_mfma_f32_16x16x32_bf16 v[108:111], v[138:141], v[190:193], v[108:111]
	v_mfma_f32_16x16x32_bf16 v[104:107], v[146:149], v[190:193], v[104:107]
	v_mfma_f32_16x16x32_bf16 v[92:95], v[138:141], v[212:215], v[92:95]
	v_mfma_f32_16x16x32_bf16 v[88:91], v[146:149], v[212:215], v[88:91]
	v_mfma_f32_16x16x32_bf16 v[76:79], v[138:141], v[220:223], v[76:79]
	v_mfma_f32_16x16x32_bf16 v[72:75], v[146:149], v[220:223], v[72:75]
	v_mfma_f32_16x16x32_bf16 v[124:127], v[142:145], v[186:189], v[124:127]
	v_mfma_f32_16x16x32_bf16 v[120:123], v[150:153], v[186:189], v[120:123]
	v_mfma_f32_16x16x32_bf16 v[108:111], v[142:145], v[208:211], v[108:111]
	v_mfma_f32_16x16x32_bf16 v[104:107], v[150:153], v[208:211], v[104:107]
	v_mfma_f32_16x16x32_bf16 v[92:95], v[142:145], v[216:219], v[92:95]
	v_mfma_f32_16x16x32_bf16 v[88:91], v[150:153], v[216:219], v[88:91]
	v_mfma_f32_16x16x32_bf16 v[76:79], v[142:145], v[224:227], v[76:79]
	v_mfma_f32_16x16x32_bf16 v[72:75], v[150:153], v[224:227], v[72:75]
	s_setprio 0
	s_setprio 1
	v_mfma_f32_16x16x32_bf16 v[116:119], v[154:157], v[182:185], v[116:119]
	v_mfma_f32_16x16x32_bf16 v[112:115], v[170:173], v[182:185], v[112:115]
	v_mfma_f32_16x16x32_bf16 v[100:103], v[154:157], v[190:193], v[100:103]
	v_mfma_f32_16x16x32_bf16 v[96:99], v[170:173], v[190:193], v[96:99]
	v_mfma_f32_16x16x32_bf16 v[84:87], v[154:157], v[212:215], v[84:87]
	v_mfma_f32_16x16x32_bf16 v[80:83], v[170:173], v[212:215], v[80:83]
	v_mfma_f32_16x16x32_bf16 v[68:71], v[154:157], v[220:223], v[68:71]
	v_mfma_f32_16x16x32_bf16 v[64:67], v[170:173], v[220:223], v[64:67]
	v_mfma_f32_16x16x32_bf16 v[116:119], v[166:169], v[186:189], v[116:119]
	v_mfma_f32_16x16x32_bf16 v[112:115], v[178:181], v[186:189], v[112:115]
	v_mfma_f32_16x16x32_bf16 v[100:103], v[166:169], v[208:211], v[100:103]
	v_mfma_f32_16x16x32_bf16 v[96:99], v[178:181], v[208:211], v[96:99]
	v_mfma_f32_16x16x32_bf16 v[84:87], v[166:169], v[216:219], v[84:87]
	v_mfma_f32_16x16x32_bf16 v[80:83], v[178:181], v[216:219], v[80:83]
	v_mfma_f32_16x16x32_bf16 v[68:71], v[166:169], v[224:227], v[68:71]
	v_mfma_f32_16x16x32_bf16 v[64:67], v[178:181], v[224:227], v[64:67]
	s_setprio 0
	s_barrier
; #define PG8_STAGE(bufoff, gbase, voff) do { _Pragma("unroll") for (int _i = 0; _i < 2; ++_i) \
;         __builtin_amdgcn_global_load_lds((const unsigned*)((const char*)(gbase) + (voff)[_i]), (LAS unsigned*)(lds + (bufoff) + ldsw + _i * 8192), 16, 0, 0); } while (0)
; #define PG8_LDA(dst, b, h) do { _Pragma("unroll") for (int m = 0; m < 4; ++m) _Pragma("unroll") for (int k = 0; k < 2; ++k) dst[m][k] = *(const LAS bf16x8*)(lds + PG8_SA(b, h) + aoff + m * 2048 + k * 1024); } while (0)
; #define PG8_WAIT_V(n) asm volatile("s_waitcnt vmcnt(" #n ")" ::: "memory")
; #define PG8_WAIT_L(n) asm volatile("s_waitcnt lgkmcnt(" #n ")" ::: "memory")
; #define PG8_BAR __builtin_amdgcn_s_barrier()
; #define PG8_SCHED __builtin_amdgcn_sched_barrier(0)
; template <bool F16, class Sched, class Epi>
; __device__ __forceinline__ void gemm_phase(LAS unsigned char* lds, const Gemm g, const Sched& S, const Epi& E, int wave_s) {
;     ...
;         for (int t = 0; t < nt; t += 2) {
;     ...
;             PG8_LDA(At, 1, 1); PG8_STAGE(PG8_SB(1, 0), b3, voffB); PG8_STAGE(PG8_SB(1, 1), b3 + hstepB, voffB); PG8_STAGE(PG8_SA(1, 0), a3, voffA);
;             PG8_WAIT_V(8); PG8_WAIT_L(0); PG8_BAR; PG8_MMA(1, 0, At, B0); PG8_MMA(1, 1, At, B1); PG8_BAR; PG8_SCHED;
	s_add_i32 s38, s71, s46
	v_lshl_add_u64 v[158:159], v[158:159], 0, s[54:55]
	s_mov_b32 m0, s38
	ds_read_b128 v[182:185], v164 offset:49152
	ds_read_b128 v[186:189], v164 offset:50176
	ds_read_b128 v[190:193], v164 offset:51200
	ds_read_b128 v[208:211], v164 offset:52224
	ds_read_b128 v[212:215], v164 offset:53248
	ds_read_b128 v[216:219], v164 offset:54272
	ds_read_b128 v[220:223], v164 offset:55296
	ds_read_b128 v[224:227], v164 offset:56320
	global_load_lds_dwordx4 v[158:159], off
	s_add_i32 m0, s38, 0x2000
	s_add_u32 s4, s4, 0x80080
	v_lshl_add_u64 v[158:159], v[174:175], 0, s[54:55]
	s_addc_u32 s5, s5, 0
	s_add_i32 s38, s72, s46
	global_load_lds_dwordx4 v[158:159], off
	v_lshl_add_u64 v[158:159], s[4:5], 0, v[176:177]
	s_mov_b32 m0, s38
	s_nop 0
	global_load_lds_dwordx4 v[158:159], off
	v_lshl_add_u64 v[158:159], s[4:5], 0, v[128:129]
	s_add_i32 m0, s38, 0x2000
	s_nop 0
	global_load_lds_dwordx4 v[158:159], off
	v_lshl_add_u64 v[158:159], v[194:195], 0, s[54:55]
	s_mov_b32 m0, s59
	s_nop 0
	global_load_lds_dwordx4 v[158:159], off
	v_lshl_add_u64 v[158:159], v[198:199], 0, s[54:55]
	s_mov_b32 m0, s60
	s_nop 0
	global_load_lds_dwordx4 v[158:159], off
	s_waitcnt vmcnt(8)
	s_waitcnt lgkmcnt(0)
	s_barrier
	s_setprio 1
	s_waitcnt lgkmcnt(0)
	v_mfma_f32_16x16x32_bf16 v[60:63], v[138:141], v[182:185], v[60:63]
	v_mfma_f32_16x16x32_bf16 v[56:59], v[146:149], v[182:185], v[56:59]
	v_mfma_f32_16x16x32_bf16 v[44:47], v[138:141], v[190:193], v[44:47]
	v_mfma_f32_16x16x32_bf16 v[40:43], v[146:149], v[190:193], v[40:43]
	v_mfma_f32_16x16x32_bf16 v[28:31], v[138:141], v[212:215], v[28:31]
	v_mfma_f32_16x16x32_bf16 v[24:27], v[146:149], v[212:215], v[24:27]
	v_mfma_f32_16x16x32_bf16 v[12:15], v[138:141], v[220:223], v[12:15]
	v_mfma_f32_16x16x32_bf16 v[8:11], v[146:149], v[220:223], v[8:11]
	v_mfma_f32_16x16x32_bf16 v[60:63], v[142:145], v[186:189], v[60:63]
	v_mfma_f32_16x16x32_bf16 v[56:59], v[150:153], v[186:189], v[56:59]
	v_mfma_f32_16x16x32_bf16 v[44:47], v[142:145], v[208:211], v[44:47]
	v_mfma_f32_16x16x32_bf16 v[40:43], v[150:153], v[208:211], v[40:43]
	v_mfma_f32_16x16x32_bf16 v[28:31], v[142:145], v[216:219], v[28:31]
	v_mfma_f32_16x16x32_bf16 v[24:27], v[150:153], v[216:219], v[24:27]
	v_mfma_f32_16x16x32_bf16 v[12:15], v[142:145], v[224:227], v[12:15]
	v_mfma_f32_16x16x32_bf16 v[8:11], v[150:153], v[224:227], v[8:11]
	s_setprio 0
	s_setprio 1
	v_mfma_f32_16x16x32_bf16 v[52:55], v[154:157], v[182:185], v[52:55]
	v_mfma_f32_16x16x32_bf16 v[48:51], v[170:173], v[182:185], v[48:51]
	v_mfma_f32_16x16x32_bf16 v[36:39], v[154:157], v[190:193], v[36:39]
	v_mfma_f32_16x16x32_bf16 v[32:35], v[170:173], v[190:193], v[32:35]
	v_mfma_f32_16x16x32_bf16 v[20:23], v[154:157], v[212:215], v[20:23]
	v_mfma_f32_16x16x32_bf16 v[16:19], v[170:173], v[212:215], v[16:19]
	v_mfma_f32_16x16x32_bf16 v[4:7], v[154:157], v[220:223], v[4:7]
	v_mfma_f32_16x16x32_bf16 v[0:3], v[170:173], v[220:223], v[0:3]
	v_mfma_f32_16x16x32_bf16 v[52:55], v[166:169], v[186:189], v[52:55]
	v_mfma_f32_16x16x32_bf16 v[48:51], v[178:181], v[186:189], v[48:51]
	v_mfma_f32_16x16x32_bf16 v[36:39], v[166:169], v[208:211], v[36:39]
	v_mfma_f32_16x16x32_bf16 v[32:35], v[178:181], v[208:211], v[32:35]
	v_mfma_f32_16x16x32_bf16 v[20:23], v[166:169], v[216:219], v[20:23]
	v_mfma_f32_16x16x32_bf16 v[16:19], v[178:181], v[216:219], v[16:19]
	v_mfma_f32_16x16x32_bf16 v[4:7], v[166:169], v[224:227], v[4:7]
	v_mfma_f32_16x16x32_bf16 v[0:3], v[178:181], v[224:227], v[0:3]
	s_add_i32 s70, s70, 2
	s_add_u32 s2, s2, 0x100
	s_addc_u32 s3, s3, 0
	s_add_u32 s68, s68, 0x100
	s_addc_u32 s69, s69, 0
	s_cmp_gt_u32 s70, 29
	s_setprio 0
	s_barrier
	s_cbranch_scc0 .LBB0_304
	s_and_b64 vcc, exec, s[28:29]
	s_cbranch_vccz .LBB0_307
	s_barrier

; #define PG8_STAGE(bufoff, gbase, voff) do { _Pragma("unroll") for (int _i = 0; _i < 2; ++_i) \
;         __builtin_amdgcn_global_load_lds((const unsigned*)((const char*)(gbase) + (voff)[_i]), (LAS unsigned*)(lds + (bufoff) + ldsw + _i * 8192), 16, 0, 0); } while (0)
; #define PG8_LDA(dst, b, h) do { _Pragma("unroll") for (int m = 0; m < 4; ++m) _Pragma("unroll") for (int k = 0; k < 2; ++k) dst[m][k] = *(const LAS bf16x8*)(lds + PG8_SA(b, h) + aoff + m * 2048 + k * 1024); } while (0)
; #define PG8_LDB(dst, b, h) do { _Pragma("unroll") for (int n = 0; n < 2; ++n) _Pragma("unroll") for (int k = 0; k < 2; ++k) dst[n][k] = *(const LAS bf16x8*)(lds + PG8_SB(b, h) + boff + n * 2048 + k * 1024); } while (0)
; #define PG8_WAIT_V(n) asm volatile("s_waitcnt vmcnt(" #n ")" ::: "memory")
; #define PG8_WAIT_L(n) asm volatile("s_waitcnt lgkmcnt(" #n ")" ::: "memory")
; #define PG8_BAR __builtin_amdgcn_s_barrier()
; #define PG8_SCHED __builtin_amdgcn_sched_barrier(0)
; template <bool F16, class Sched, class Epi>
; __device__ __forceinline__ void gemm_phase(LAS unsigned char* lds, const Gemm g, const Sched& S, const Epi& E, int wave_s) {
;     ...
;             const char* a2 = last ? nA : cA + (size_t)(t + 2) * kstep; const char* b2 = last ? nB : cB + (size_t)(t + 2) * kstep;
;             const char* a3 = a2 + kstep; const char* b3 = b2 + kstep;
;             PG8_LDB(B0, 0, 0); PG8_LDB(B1, 0, 1); PG8_SCHED; PG8_LDA(At, 0, 0); PG8_STAGE(PG8_SA(1, 1), a1 + hstepA, voffA);
;             PG8_WAIT_V(8); PG8_WAIT_L(0); PG8_BAR; PG8_MMA(0, 0, At, B0); PG8_MMA(0, 1, At, B1); PG8_BAR; PG8_SCHED;
;             PG8_LDA(At, 0, 1); PG8_STAGE(PG8_SB(0, 0), b2, voffB); PG8_STAGE(PG8_SB(0, 1), b2 + hstepB, voffB); PG8_STAGE(PG8_SA(0, 0), a2, voffA);
;             PG8_WAIT_V(8); PG8_WAIT_L(0); PG8_BAR; PG8_MMA(1, 0, At, B0); PG8_MMA(1, 1, At, B1); PG8_BAR; PG8_SCHED;
.LBB0_358:
	s_add_i32 s65, 0, 0x10000
	s_add_i32 s70, 0, 0x14000
	v_add_u32_e32 v150, s65, v163
	v_add_u32_e32 v158, s70, v163
	ds_read_b128 v[138:141], v150
	ds_read_b128 v[142:145], v150 offset:1024
	ds_read_b128 v[146:149], v150 offset:2048
	ds_read_b128 v[150:153], v150 offset:3072
	ds_read_b128 v[154:157], v158
	ds_read_b128 v[168:171], v158 offset:1024
	ds_read_b128 v[172:175], v158 offset:2048
	ds_read_b128 v[178:181], v158 offset:3072
	s_add_i32 m0, s44, 0xc000
	ds_read_b128 v[182:185], v167
	ds_read_b128 v[186:189], v167 offset:1024
	ds_read_b128 v[190:193], v167 offset:2048
	ds_read_b128 v[208:211], v167 offset:3072
	ds_read_b128 v[212:215], v167 offset:4096
	ds_read_b128 v[216:219], v167 offset:5120
	ds_read_b128 v[220:223], v167 offset:6144
	ds_read_b128 v[224:227], v167 offset:7168
	global_load_lds_dwordx4 v134, s[2:3]
	s_add_i32 m0, s44, 0xe000
	s_nop 0
	global_load_lds_dwordx4 v136, s[2:3]
	s_waitcnt vmcnt(8)
	s_waitcnt lgkmcnt(0)
	s_barrier
	s_setprio 1
	s_waitcnt lgkmcnt(0)
	v_mfma_f32_16x16x32_bf16 v[124:127], v[138:141], v[182:185], v[124:127]
	v_mfma_f32_16x16x32_bf16 v[120:123], v[146:149], v[182:185], v[120:123]
	v_mfma_f32_16x16x32_bf16 v[108:111], v[138:141], v[190:193], v[108:111]
	v_mfma_f32_16x16x32_bf16 v[104:107], v[146:149], v[190:193], v[104:107]
	v_mfma_f32_16x16x32_bf16 v[92:95], v[138:141], v[212:215], v[92:95]
	v_mfma_f32_16x16x32_bf16 v[88:91], v[146:149], v[212:215], v[88:91]
	v_mfma_f32_16x16x32_bf16 v[76:79], v[138:141], v[220:223], v[76:79]
	v_mfma_f32_16x16x32_bf16 v[72:75], v[146:149], v[220:223], v[72:75]
	v_mfma_f32_16x16x32_bf16 v[124:127], v[142:145], v[186:189], v[124:127]
	v_mfma_f32_16x16x32_bf16 v[120:123], v[150:153], v[186:189], v[120:123]
	v_mfma_f32_16x16x32_bf16 v[108:111], v[142:145], v[208:211], v[108:111]
	v_mfma_f32_16x16x32_bf16 v[104:107], v[150:153], v[208:211], v[104:107]
	v_mfma_f32_16x16x32_bf16 v[92:95], v[142:145], v[216:219], v[92:95]
	v_mfma_f32_16x16x32_bf16 v[88:91], v[150:153], v[216:219], v[88:91]
	v_mfma_f32_16x16x32_bf16 v[76:79], v[142:145], v[224:227], v[76:79]
	v_mfma_f32_16x16x32_bf16 v[72:75], v[150:153], v[224:227], v[72:75]
	s_setprio 0
	s_setprio 1
	v_mfma_f32_16x16x32_bf16 v[116:119], v[154:157], v[182:185], v[116:119]
	v_mfma_f32_16x16x32_bf16 v[112:115], v[172:175], v[182:185], v[112:115]
	v_mfma_f32_16x16x32_bf16 v[100:103], v[154:157], v[190:193], v[100:103]
	v_mfma_f32_16x16x32_bf16 v[96:99], v[172:175], v[190:193], v[96:99]
	v_mfma_f32_16x16x32_bf16 v[84:87], v[154:157], v[212:215], v[84:87]
	v_mfma_f32_16x16x32_bf16 v[80:83], v[172:175], v[212:215], v[80:83]
	v_mfma_f32_16x16x32_bf16 v[68:71], v[154:157], v[220:223], v[68:71]
	v_mfma_f32_16x16x32_bf16 v[64:67], v[172:175], v[220:223], v[64:67]
	v_mfma_f32_16x16x32_bf16 v[116:119], v[168:171], v[186:189], v[116:119]
	v_mfma_f32_16x16x32_bf16 v[112:115], v[178:181], v[186:189], v[112:115]
	v_mfma_f32_16x16x32_bf16 v[100:103], v[168:171], v[208:211], v[100:103]
	v_mfma_f32_16x16x32_bf16 v[96:99], v[178:181], v[208:211], v[96:99]
	v_mfma_f32_16x16x32_bf16 v[84:87], v[168:171], v[216:219], v[84:87]
	v_mfma_f32_16x16x32_bf16 v[80:83], v[178:181], v[216:219], v[80:83]
	v_mfma_f32_16x16x32_bf16 v[68:71], v[168:171], v[224:227], v[68:71]
	v_mfma_f32_16x16x32_bf16 v[64:67], v[178:181], v[224:227], v[64:67]
	s_setprio 0
	s_barrier
	s_add_u32 s30, s2, 0xfff80080
	s_addc_u32 s31, s3, -1
	s_cmp_eq_u32 s64, 28
	s_cselect_b32 s35, s58, s31
	s_cselect_b32 s34, s59, s30
	s_cselect_b32 s31, s60, s63
	s_cselect_b32 s30, s61, s62
	s_add_i32 s65, s65, s42
	v_lshl_add_u64 v[158:159], s[30:31], 0, v[176:177]
	s_mov_b32 m0, s65
	ds_read_b128 v[182:185], v167 offset:16384
	ds_read_b128 v[186:189], v167 offset:17408
	ds_read_b128 v[190:193], v167 offset:18432
	ds_read_b128 v[208:211], v167 offset:19456
	ds_read_b128 v[212:215], v167 offset:20480
	ds_read_b128 v[216:219], v167 offset:21504
	ds_read_b128 v[220:223], v167 offset:22528
	ds_read_b128 v[224:227], v167 offset:23552
	global_load_lds_dwordx4 v[158:159], off
	s_add_i32 m0, s65, 0x2000
	s_add_u32 s68, s30, 0x80000
	v_lshl_add_u64 v[194:195], s[30:31], 0, v[128:129]
	s_addc_u32 s69, s31, 0
	s_add_i32 s65, s70, s42
	global_load_lds_dwordx4 v[194:195], off
	v_lshl_add_u64 v[198:199], s[68:69], 0, v[176:177]
	s_mov_b32 m0, s65
	v_lshl_add_u64 v[200:201], s[34:35], 0, v[130:131]
	global_load_lds_dwordx4 v[198:199], off
	v_lshl_add_u64 v[198:199], s[68:69], 0, v[128:129]
	s_add_i32 m0, s65, 0x2000
	s_nop 0
	global_load_lds_dwordx4 v[198:199], off
	v_lshl_add_u64 v[198:199], s[34:35], 0, v[132:133]
	s_mov_b32 m0, s44
	s_nop 0
	global_load_lds_dwordx4 v[198:199], off
	s_mov_b32 m0, s46
	s_nop 0
	global_load_lds_dwordx4 v[200:201], off
	s_add_u32 s34, s34, 0x80000
	s_addc_u32 s35, s35, 0
	s_waitcnt vmcnt(8)
	s_waitcnt lgkmcnt(0)
	s_barrier
; #define PG8_STAGE(bufoff, gbase, voff) do { _Pragma("unroll") for (int _i = 0; _i < 2; ++_i) \
;         __builtin_amdgcn_global_load_lds((const unsigned*)((const char*)(gbase) + (voff)[_i]), (LAS unsigned*)(lds + (bufoff) + ldsw + _i * 8192), 16, 0, 0); } while (0)
; #define PG8_LDA(dst, b, h) do { _Pragma("unroll") for (int m = 0; m < 4; ++m) _Pragma("unroll") for (int k = 0; k < 2; ++k) dst[m][k] = *(const LAS bf16x8*)(lds + PG8_SA(b, h) + aoff + m * 2048 + k * 1024); } while (0)
; #define PG8_LDB(dst, b, h) do { _Pragma("unroll") for (int n = 0; n < 2; ++n) _Pragma("unroll") for (int k = 0; k < 2; ++k) dst[n][k] = *(const LAS bf16x8*)(lds + PG8_SB(b, h) + boff + n * 2048 + k * 1024); } while (0)
; #define PG8_WAIT_V(n) asm volatile("s_waitcnt vmcnt(" #n ")" ::: "memory")
; #define PG8_WAIT_L(n) asm volatile("s_waitcnt lgkmcnt(" #n ")" ::: "memory")
; #define PG8_BAR __builtin_amdgcn_s_barrier()
; #define PG8_SCHED __builtin_amdgcn_sched_barrier(0)
; template <bool F16, class Sched, class Epi>
; __device__ __forceinline__ void gemm_phase(LAS unsigned char* lds, const Gemm g, const Sched& S, const Epi& E, int wave_s) {
;     ...
;             PG8_WAIT_V(8); PG8_WAIT_L(0); PG8_BAR; PG8_MMA(1, 0, At, B0); PG8_MMA(1, 1, At, B1); PG8_BAR; PG8_SCHED;
;             PG8_LDB(B0, 1, 0); PG8_LDB(B1, 1, 1); PG8_SCHED; PG8_LDA(At, 1, 0); PG8_STAGE(PG8_SA(0, 1), a2 + hstepA, voffA);
;             PG8_WAIT_V(8); PG8_WAIT_L(0); PG8_BAR; PG8_MMA(0, 0, At, B0); PG8_MMA(0, 1, At, B1); PG8_BAR; PG8_SCHED;
	s_setprio 1
	s_waitcnt lgkmcnt(0)
	v_mfma_f32_16x16x32_bf16 v[60:63], v[138:141], v[182:185], v[60:63]
	v_mfma_f32_16x16x32_bf16 v[56:59], v[146:149], v[182:185], v[56:59]
	v_mfma_f32_16x16x32_bf16 v[48:51], v[138:141], v[190:193], v[48:51]
	v_mfma_f32_16x16x32_bf16 v[40:43], v[146:149], v[190:193], v[40:43]
	v_mfma_f32_16x16x32_bf16 v[32:35], v[138:141], v[212:215], v[32:35]
	v_mfma_f32_16x16x32_bf16 v[24:27], v[146:149], v[212:215], v[24:27]
	v_mfma_f32_16x16x32_bf16 v[16:19], v[138:141], v[220:223], v[16:19]
	v_mfma_f32_16x16x32_bf16 v[8:11], v[146:149], v[220:223], v[8:11]
	v_mfma_f32_16x16x32_bf16 v[60:63], v[142:145], v[186:189], v[60:63]
	v_mfma_f32_16x16x32_bf16 v[56:59], v[150:153], v[186:189], v[56:59]
	v_mfma_f32_16x16x32_bf16 v[48:51], v[142:145], v[208:211], v[48:51]
	v_mfma_f32_16x16x32_bf16 v[40:43], v[150:153], v[208:211], v[40:43]
	v_mfma_f32_16x16x32_bf16 v[32:35], v[142:145], v[216:219], v[32:35]
	v_mfma_f32_16x16x32_bf16 v[24:27], v[150:153], v[216:219], v[24:27]
	v_mfma_f32_16x16x32_bf16 v[16:19], v[142:145], v[224:227], v[16:19]
	v_mfma_f32_16x16x32_bf16 v[8:11], v[150:153], v[224:227], v[8:11]
	s_setprio 0
	s_setprio 1
	v_mfma_f32_16x16x32_bf16 v[52:55], v[154:157], v[182:185], v[52:55]
	v_mfma_f32_16x16x32_bf16 v[44:47], v[172:175], v[182:185], v[44:47]
	v_mfma_f32_16x16x32_bf16 v[36:39], v[154:157], v[190:193], v[36:39]
	v_mfma_f32_16x16x32_bf16 v[28:31], v[172:175], v[190:193], v[28:31]
	v_mfma_f32_16x16x32_bf16 v[20:23], v[154:157], v[212:215], v[20:23]
	v_mfma_f32_16x16x32_bf16 v[12:15], v[172:175], v[212:215], v[12:15]
	v_mfma_f32_16x16x32_bf16 v[4:7], v[154:157], v[220:223], v[4:7]
	v_mfma_f32_16x16x32_bf16 v[0:3], v[172:175], v[220:223], v[0:3]
	v_mfma_f32_16x16x32_bf16 v[52:55], v[168:171], v[186:189], v[52:55]
	v_mfma_f32_16x16x32_bf16 v[44:47], v[178:181], v[186:189], v[44:47]
	v_mfma_f32_16x16x32_bf16 v[36:39], v[168:171], v[208:211], v[36:39]
	v_mfma_f32_16x16x32_bf16 v[28:31], v[178:181], v[208:211], v[28:31]
	v_mfma_f32_16x16x32_bf16 v[20:23], v[168:171], v[216:219], v[20:23]
	v_mfma_f32_16x16x32_bf16 v[12:15], v[178:181], v[216:219], v[12:15]
	v_mfma_f32_16x16x32_bf16 v[4:7], v[168:171], v[224:227], v[4:7]
	v_mfma_f32_16x16x32_bf16 v[0:3], v[178:181], v[224:227], v[0:3]
	s_setprio 0
	s_barrier
	s_add_i32 s65, 0, 0x18000
	s_add_i32 s68, 0, 0x1c000
	v_add_u32_e32 v150, s65, v163
	v_add_u32_e32 v160, s68, v163
	ds_read_b128 v[138:141], v150
	ds_read_b128 v[142:145], v150 offset:1024
	ds_read_b128 v[146:149], v150 offset:2048
	ds_read_b128 v[150:153], v150 offset:3072
	ds_read_b128 v[154:157], v160
	ds_read_b128 v[168:171], v160 offset:1024
	ds_read_b128 v[172:175], v160 offset:2048
	ds_read_b128 v[178:181], v160 offset:3072
	s_mov_b32 m0, s47
	ds_read_b128 v[182:185], v167 offset:32768
	ds_read_b128 v[186:189], v167 offset:33792
	ds_read_b128 v[190:193], v167 offset:34816
	ds_read_b128 v[208:211], v167 offset:35840
	ds_read_b128 v[212:215], v167 offset:36864
	ds_read_b128 v[216:219], v167 offset:37888
	ds_read_b128 v[220:223], v167 offset:38912
	ds_read_b128 v[224:227], v167 offset:39936
	global_load_lds_dwordx4 v132, s[34:35]
	s_mov_b32 m0, s48
	s_nop 0
	global_load_lds_dwordx4 v130, s[34:35]
	s_waitcnt vmcnt(8)
	s_waitcnt lgkmcnt(0)
	s_barrier
	s_setprio 1
	s_waitcnt lgkmcnt(0)
	v_mfma_f32_16x16x32_bf16 v[124:127], v[138:141], v[182:185], v[124:127]
	v_mfma_f32_16x16x32_bf16 v[120:123], v[146:149], v[182:185], v[120:123]
	v_mfma_f32_16x16x32_bf16 v[108:111], v[138:141], v[190:193], v[108:111]
	v_mfma_f32_16x16x32_bf16 v[104:107], v[146:149], v[190:193], v[104:107]
	v_mfma_f32_16x16x32_bf16 v[92:95], v[138:141], v[212:215], v[92:95]
	v_mfma_f32_16x16x32_bf16 v[88:91], v[146:149], v[212:215], v[88:91]
	v_mfma_f32_16x16x32_bf16 v[76:79], v[138:141], v[220:223], v[76:79]
	v_mfma_f32_16x16x32_bf16 v[72:75], v[146:149], v[220:223], v[72:75]
	v_mfma_f32_16x16x32_bf16 v[124:127], v[142:145], v[186:189], v[124:127]
	v_mfma_f32_16x16x32_bf16 v[120:123], v[150:153], v[186:189], v[120:123]
	v_mfma_f32_16x16x32_bf16 v[108:111], v[142:145], v[208:211], v[108:111]
	v_mfma_f32_16x16x32_bf16 v[104:107], v[150:153], v[208:211], v[104:107]
	v_mfma_f32_16x16x32_bf16 v[92:95], v[142:145], v[216:219], v[92:95]
	v_mfma_f32_16x16x32_bf16 v[88:91], v[150:153], v[216:219], v[88:91]
	v_mfma_f32_16x16x32_bf16 v[76:79], v[142:145], v[224:227], v[76:79]
	v_mfma_f32_16x16x32_bf16 v[72:75], v[150:153], v[224:227], v[72:75]
	s_setprio 0
	s_setprio 1
	v_mfma_f32_16x16x32_bf16 v[116:119], v[154:157], v[182:185], v[116:119]
	v_mfma_f32_16x16x32_bf16 v[112:115], v[172:175], v[182:185], v[112:115]
	v_mfma_f32_16x16x32_bf16 v[100:103], v[154:157], v[190:193], v[100:103]
	v_mfma_f32_16x16x32_bf16 v[96:99], v[172:175], v[190:193], v[96:99]
	v_mfma_f32_16x16x32_bf16 v[84:87], v[154:157], v[212:215], v[84:87]
	v_mfma_f32_16x16x32_bf16 v[80:83], v[172:175], v[212:215], v[80:83]
	v_mfma_f32_16x16x32_bf16 v[68:71], v[154:157], v[220:223], v[68:71]
	v_mfma_f32_16x16x32_bf16 v[64:67], v[172:175], v[220:223], v[64:67]
	v_mfma_f32_16x16x32_bf16 v[116:119], v[168:171], v[186:189], v[116:119]
	v_mfma_f32_16x16x32_bf16 v[112:115], v[178:181], v[186:189], v[112:115]
	v_mfma_f32_16x16x32_bf16 v[100:103], v[168:171], v[208:211], v[100:103]
	v_mfma_f32_16x16x32_bf16 v[96:99], v[178:181], v[208:211], v[96:99]
	v_mfma_f32_16x16x32_bf16 v[84:87], v[168:171], v[216:219], v[84:87]
	v_mfma_f32_16x16x32_bf16 v[80:83], v[178:181], v[216:219], v[80:83]
	v_mfma_f32_16x16x32_bf16 v[68:71], v[168:171], v[224:227], v[68:71]
	v_mfma_f32_16x16x32_bf16 v[64:67], v[178:181], v[224:227], v[64:67]
	s_setprio 0
	s_barrier
; #define PG8_STAGE(bufoff, gbase, voff) do { _Pragma("unroll") for (int _i = 0; _i < 2; ++_i) \
;         __builtin_amdgcn_global_load_lds((const unsigned*)((const char*)(gbase) + (voff)[_i]), (LAS unsigned*)(lds + (bufoff) + ldsw + _i * 8192), 16, 0, 0); } while (0)
; #define PG8_LDA(dst, b, h) do { _Pragma("unroll") for (int m = 0; m < 4; ++m) _Pragma("unroll") for (int k = 0; k < 2; ++k) dst[m][k] = *(const LAS bf16x8*)(lds + PG8_SA(b, h) + aoff + m * 2048 + k * 1024); } while (0)
; #define PG8_WAIT_V(n) asm volatile("s_waitcnt vmcnt(" #n ")" ::: "memory")
; #define PG8_WAIT_L(n) asm volatile("s_waitcnt lgkmcnt(" #n ")" ::: "memory")
; #define PG8_BAR __builtin_amdgcn_s_barrier()
; #define PG8_SCHED __builtin_amdgcn_sched_barrier(0)
; template <bool F16, class Sched, class Epi>
; __device__ __forceinline__ void gemm_phase(LAS unsigned char* lds, const Gemm g, const Sched& S, const Epi& E, int wave_s) {
;     ...
;         for (int t = 0; t < nt; t += 2) {
;     ...
;             PG8_LDA(At, 1, 1); PG8_STAGE(PG8_SB(1, 0), b3, voffB); PG8_STAGE(PG8_SB(1, 1), b3 + hstepB, voffB); PG8_STAGE(PG8_SA(1, 0), a3, voffA);
;             PG8_WAIT_V(8); PG8_WAIT_L(0); PG8_BAR; PG8_MMA(1, 0, At, B0); PG8_MMA(1, 1, At, B1); PG8_BAR; PG8_SCHED;
	s_add_i32 s34, s65, s42
	v_lshl_add_u64 v[158:159], v[158:159], 0, s[54:55]
	s_mov_b32 m0, s34
	ds_read_b128 v[182:185], v167 offset:49152
	ds_read_b128 v[186:189], v167 offset:50176
	ds_read_b128 v[190:193], v167 offset:51200
	ds_read_b128 v[208:211], v167 offset:52224
	ds_read_b128 v[212:215], v167 offset:53248
	ds_read_b128 v[216:219], v167 offset:54272
	ds_read_b128 v[220:223], v167 offset:55296
	ds_read_b128 v[224:227], v167 offset:56320
	global_load_lds_dwordx4 v[158:159], off
	s_add_i32 m0, s34, 0x2000
	s_add_u32 s30, s30, 0x80080
	v_lshl_add_u64 v[158:159], v[194:195], 0, s[54:55]
	s_addc_u32 s31, s31, 0
	s_add_i32 s34, s68, s42
	global_load_lds_dwordx4 v[158:159], off
	v_lshl_add_u64 v[158:159], s[30:31], 0, v[176:177]
	s_mov_b32 m0, s34
	s_nop 0
	global_load_lds_dwordx4 v[158:159], off
	v_lshl_add_u64 v[158:159], s[30:31], 0, v[128:129]
	s_add_i32 m0, s34, 0x2000
	s_nop 0
	global_load_lds_dwordx4 v[158:159], off
	v_lshl_add_u64 v[158:159], v[198:199], 0, s[54:55]
	s_mov_b32 m0, s49
	s_nop 0
	global_load_lds_dwordx4 v[158:159], off
	v_lshl_add_u64 v[158:159], v[200:201], 0, s[54:55]
	s_mov_b32 m0, s52
	s_nop 0
	global_load_lds_dwordx4 v[158:159], off
	s_waitcnt vmcnt(8)
	s_waitcnt lgkmcnt(0)
	s_barrier
	s_setprio 1
	s_waitcnt lgkmcnt(0)
	v_mfma_f32_16x16x32_bf16 v[60:63], v[138:141], v[182:185], v[60:63]
	v_mfma_f32_16x16x32_bf16 v[56:59], v[146:149], v[182:185], v[56:59]
	v_mfma_f32_16x16x32_bf16 v[48:51], v[138:141], v[190:193], v[48:51]
	v_mfma_f32_16x16x32_bf16 v[40:43], v[146:149], v[190:193], v[40:43]
	v_mfma_f32_16x16x32_bf16 v[32:35], v[138:141], v[212:215], v[32:35]
	v_mfma_f32_16x16x32_bf16 v[24:27], v[146:149], v[212:215], v[24:27]
	v_mfma_f32_16x16x32_bf16 v[16:19], v[138:141], v[220:223], v[16:19]
	v_mfma_f32_16x16x32_bf16 v[8:11], v[146:149], v[220:223], v[8:11]
	v_mfma_f32_16x16x32_bf16 v[60:63], v[142:145], v[186:189], v[60:63]
	v_mfma_f32_16x16x32_bf16 v[56:59], v[150:153], v[186:189], v[56:59]
	v_mfma_f32_16x16x32_bf16 v[48:51], v[142:145], v[208:211], v[48:51]
	v_mfma_f32_16x16x32_bf16 v[40:43], v[150:153], v[208:211], v[40:43]
	v_mfma_f32_16x16x32_bf16 v[32:35], v[142:145], v[216:219], v[32:35]
	v_mfma_f32_16x16x32_bf16 v[24:27], v[150:153], v[216:219], v[24:27]
	v_mfma_f32_16x16x32_bf16 v[16:19], v[142:145], v[224:227], v[16:19]
	v_mfma_f32_16x16x32_bf16 v[8:11], v[150:153], v[224:227], v[8:11]
	s_setprio 0
	s_setprio 1
	v_mfma_f32_16x16x32_bf16 v[52:55], v[154:157], v[182:185], v[52:55]
	v_mfma_f32_16x16x32_bf16 v[44:47], v[172:175], v[182:185], v[44:47]
	v_mfma_f32_16x16x32_bf16 v[36:39], v[154:157], v[190:193], v[36:39]
	v_mfma_f32_16x16x32_bf16 v[28:31], v[172:175], v[190:193], v[28:31]
	v_mfma_f32_16x16x32_bf16 v[20:23], v[154:157], v[212:215], v[20:23]
	v_mfma_f32_16x16x32_bf16 v[12:15], v[172:175], v[212:215], v[12:15]
	v_mfma_f32_16x16x32_bf16 v[4:7], v[154:157], v[220:223], v[4:7]
	v_mfma_f32_16x16x32_bf16 v[0:3], v[172:175], v[220:223], v[0:3]
	v_mfma_f32_16x16x32_bf16 v[52:55], v[168:171], v[186:189], v[52:55]
	v_mfma_f32_16x16x32_bf16 v[44:47], v[178:181], v[186:189], v[44:47]
	v_mfma_f32_16x16x32_bf16 v[36:39], v[168:171], v[208:211], v[36:39]
	v_mfma_f32_16x16x32_bf16 v[28:31], v[178:181], v[208:211], v[28:31]
	v_mfma_f32_16x16x32_bf16 v[20:23], v[168:171], v[216:219], v[20:23]
	v_mfma_f32_16x16x32_bf16 v[12:15], v[178:181], v[216:219], v[12:15]
	v_mfma_f32_16x16x32_bf16 v[4:7], v[168:171], v[224:227], v[4:7]
	v_mfma_f32_16x16x32_bf16 v[0:3], v[178:181], v[224:227], v[0:3]
	s_add_i32 s64, s64, 2
	s_add_u32 s2, s2, 0x100
	s_addc_u32 s3, s3, 0
	s_add_u32 s62, s62, 0x100
	s_addc_u32 s63, s63, 0
	s_cmp_gt_u32 s64, 29
	s_setprio 0
	s_barrier
	s_cbranch_scc0 .LBB0_358
	s_and_b64 vcc, exec, s[26:27]
	s_cbranch_vccz .LBB0_361
	s_barrier

; #define PG8_STAGE(bufoff, gbase, voff) do { _Pragma("unroll") for (int _i = 0; _i < 2; ++_i) \
;         __builtin_amdgcn_global_load_lds((const unsigned*)((const char*)(gbase) + (voff)[_i]), (LAS unsigned*)(lds + (bufoff) + ldsw + _i * 8192), 16, 0, 0); } while (0)
; #define PG8_LDA(dst, b, h) do { _Pragma("unroll") for (int m = 0; m < 4; ++m) _Pragma("unroll") for (int k = 0; k < 2; ++k) dst[m][k] = *(const LAS bf16x8*)(lds + PG8_SA(b, h) + aoff + m * 2048 + k * 1024); } while (0)
; #define PG8_LDB(dst, b, h) do { _Pragma("unroll") for (int n = 0; n < 2; ++n) _Pragma("unroll") for (int k = 0; k < 2; ++k) dst[n][k] = *(const LAS bf16x8*)(lds + PG8_SB(b, h) + boff + n * 2048 + k * 1024); } while (0)
; #define PG8_WAIT_V(n) asm volatile("s_waitcnt vmcnt(" #n ")" ::: "memory")
; #define PG8_WAIT_L(n) asm volatile("s_waitcnt lgkmcnt(" #n ")" ::: "memory")
; #define PG8_BAR __builtin_amdgcn_s_barrier()
; #define PG8_SCHED __builtin_amdgcn_sched_barrier(0)
; template <bool F16, class Sched, class Epi>
; __device__ __forceinline__ void gemm_phase(LAS unsigned char* lds, const Gemm g, const Sched& S, const Epi& E, int wave_s) {
;     ...
;             const char* a2 = last ? nA : cA + (size_t)(t + 2) * kstep; const char* b2 = last ? nB : cB + (size_t)(t + 2) * kstep;
;             const char* a3 = a2 + kstep; const char* b3 = b2 + kstep;
;             PG8_LDB(B0, 0, 0); PG8_LDB(B1, 0, 1); PG8_SCHED; PG8_LDA(At, 0, 0); PG8_STAGE(PG8_SA(1, 1), a1 + hstepA, voffA);
;             PG8_WAIT_V(8); PG8_WAIT_L(0); PG8_BAR; PG8_MMA(0, 0, At, B0); PG8_MMA(0, 1, At, B1); PG8_BAR; PG8_SCHED;
;             PG8_LDA(At, 0, 1); PG8_STAGE(PG8_SB(0, 0), b2, voffB); PG8_STAGE(PG8_SB(0, 1), b2 + hstepB, voffB); PG8_STAGE(PG8_SA(0, 0), a2, voffA);
;             PG8_WAIT_V(8); PG8_WAIT_L(0); PG8_BAR; PG8_MMA(1, 0, At, B0); PG8_MMA(1, 1, At, B1); PG8_BAR; PG8_SCHED;
.LBB0_598:
	s_add_i32 s61, 0, 0x10000
	s_add_i32 s64, 0, 0x14000
	v_add_u32_e32 v150, s61, v163
	v_add_u32_e32 v170, s64, v163
	ds_read_b128 v[138:141], v150
	ds_read_b128 v[142:145], v150 offset:1024
	ds_read_b128 v[146:149], v150 offset:2048
	ds_read_b128 v[150:153], v150 offset:3072
	ds_read_b128 v[154:157], v170
	ds_read_b128 v[158:161], v170 offset:1024
	ds_read_b128 v[166:169], v170 offset:2048
	ds_read_b128 v[170:173], v170 offset:3072
	s_add_i32 m0, s43, 0xc000
	ds_read_b128 v[178:181], v165
	ds_read_b128 v[182:185], v165 offset:1024
	ds_read_b128 v[186:189], v165 offset:2048
	ds_read_b128 v[190:193], v165 offset:3072
	ds_read_b128 v[208:211], v165 offset:4096
	ds_read_b128 v[212:215], v165 offset:5120
	ds_read_b128 v[216:219], v165 offset:6144
	ds_read_b128 v[220:223], v165 offset:7168
	global_load_lds_dwordx4 v134, s[26:27]
	s_add_i32 m0, s43, 0xe000
	s_nop 0
	global_load_lds_dwordx4 v136, s[26:27]
	s_waitcnt vmcnt(8)
	s_waitcnt lgkmcnt(0)
	s_barrier
	s_setprio 1
	s_waitcnt lgkmcnt(0)
	v_mfma_f32_16x16x32_bf16 v[124:127], v[138:141], v[178:181], v[124:127]
	v_mfma_f32_16x16x32_bf16 v[120:123], v[146:149], v[178:181], v[120:123]
	v_mfma_f32_16x16x32_bf16 v[108:111], v[138:141], v[186:189], v[108:111]
	v_mfma_f32_16x16x32_bf16 v[104:107], v[146:149], v[186:189], v[104:107]
	v_mfma_f32_16x16x32_bf16 v[96:99], v[138:141], v[208:211], v[96:99]
	v_mfma_f32_16x16x32_bf16 v[92:95], v[146:149], v[208:211], v[92:95]
	v_mfma_f32_16x16x32_bf16 v[84:87], v[138:141], v[216:219], v[84:87]
	v_mfma_f32_16x16x32_bf16 v[76:79], v[146:149], v[216:219], v[76:79]
	v_mfma_f32_16x16x32_bf16 v[124:127], v[142:145], v[182:185], v[124:127]
	v_mfma_f32_16x16x32_bf16 v[120:123], v[150:153], v[182:185], v[120:123]
	v_mfma_f32_16x16x32_bf16 v[108:111], v[142:145], v[190:193], v[108:111]
	v_mfma_f32_16x16x32_bf16 v[104:107], v[150:153], v[190:193], v[104:107]
	v_mfma_f32_16x16x32_bf16 v[96:99], v[142:145], v[212:215], v[96:99]
	v_mfma_f32_16x16x32_bf16 v[92:95], v[150:153], v[212:215], v[92:95]
	v_mfma_f32_16x16x32_bf16 v[84:87], v[142:145], v[220:223], v[84:87]
	v_mfma_f32_16x16x32_bf16 v[76:79], v[150:153], v[220:223], v[76:79]
	s_setprio 0
	s_setprio 1
	v_mfma_f32_16x16x32_bf16 v[116:119], v[154:157], v[178:181], v[116:119]
	v_mfma_f32_16x16x32_bf16 v[112:115], v[166:169], v[178:181], v[112:115]
	v_mfma_f32_16x16x32_bf16 v[100:103], v[154:157], v[186:189], v[100:103]
	v_mfma_f32_16x16x32_bf16 v[88:91], v[166:169], v[186:189], v[88:91]
	v_mfma_f32_16x16x32_bf16 v[80:83], v[154:157], v[208:211], v[80:83]
	v_mfma_f32_16x16x32_bf16 v[72:75], v[166:169], v[208:211], v[72:75]
	v_mfma_f32_16x16x32_bf16 v[68:71], v[154:157], v[216:219], v[68:71]
	v_mfma_f32_16x16x32_bf16 v[64:67], v[166:169], v[216:219], v[64:67]
	v_mfma_f32_16x16x32_bf16 v[116:119], v[158:161], v[182:185], v[116:119]
	v_mfma_f32_16x16x32_bf16 v[112:115], v[170:173], v[182:185], v[112:115]
	v_mfma_f32_16x16x32_bf16 v[100:103], v[158:161], v[190:193], v[100:103]
	v_mfma_f32_16x16x32_bf16 v[88:91], v[170:173], v[190:193], v[88:91]
	v_mfma_f32_16x16x32_bf16 v[80:83], v[158:161], v[212:215], v[80:83]
	v_mfma_f32_16x16x32_bf16 v[72:75], v[170:173], v[212:215], v[72:75]
	v_mfma_f32_16x16x32_bf16 v[68:71], v[158:161], v[220:223], v[68:71]
	v_mfma_f32_16x16x32_bf16 v[64:67], v[170:173], v[220:223], v[64:67]
	s_setprio 0
	s_barrier
	s_add_u32 s28, s26, 0xfff80080
	s_addc_u32 s29, s27, -1
	s_cmp_eq_u32 s60, 28
	s_cselect_b32 s31, s49, s29
	s_cselect_b32 s30, s50, s28
	s_cselect_b32 s29, s52, s59
	s_cselect_b32 s28, s53, s58
	s_add_i32 s61, s61, s39
	v_lshl_add_u64 v[174:175], s[28:29], 0, v[176:177]
	s_mov_b32 m0, s61
	ds_read_b128 v[178:181], v165 offset:16384
	ds_read_b128 v[182:185], v165 offset:17408
	ds_read_b128 v[186:189], v165 offset:18432
	ds_read_b128 v[190:193], v165 offset:19456
	ds_read_b128 v[208:211], v165 offset:20480
	ds_read_b128 v[212:215], v165 offset:21504
	ds_read_b128 v[216:219], v165 offset:22528
	ds_read_b128 v[220:223], v165 offset:23552
	global_load_lds_dwordx4 v[174:175], off
	s_add_i32 m0, s61, 0x2000
	s_add_u32 s62, s28, 0x80000
	v_lshl_add_u64 v[194:195], s[28:29], 0, v[128:129]
	s_addc_u32 s63, s29, 0
	s_add_i32 s61, s64, s39
	global_load_lds_dwordx4 v[194:195], off
	v_lshl_add_u64 v[198:199], s[62:63], 0, v[176:177]
	s_mov_b32 m0, s61
	v_lshl_add_u64 v[200:201], s[30:31], 0, v[130:131]
	global_load_lds_dwordx4 v[198:199], off
	v_lshl_add_u64 v[198:199], s[62:63], 0, v[128:129]
	s_add_i32 m0, s61, 0x2000
	s_nop 0
	global_load_lds_dwordx4 v[198:199], off
	v_lshl_add_u64 v[198:199], s[30:31], 0, v[132:133]
	s_mov_b32 m0, s43
	s_nop 0
	global_load_lds_dwordx4 v[198:199], off
	s_mov_b32 m0, s44
	s_nop 0
	global_load_lds_dwordx4 v[200:201], off
	s_add_u32 s30, s30, 0x80000
	s_addc_u32 s31, s31, 0
	s_waitcnt vmcnt(8)
	s_waitcnt lgkmcnt(0)
	s_barrier
; #define PG8_STAGE(bufoff, gbase, voff) do { _Pragma("unroll") for (int _i = 0; _i < 2; ++_i) \
;         __builtin_amdgcn_global_load_lds((const unsigned*)((const char*)(gbase) + (voff)[_i]), (LAS unsigned*)(lds + (bufoff) + ldsw + _i * 8192), 16, 0, 0); } while (0)
; #define PG8_LDA(dst, b, h) do { _Pragma("unroll") for (int m = 0; m < 4; ++m) _Pragma("unroll") for (int k = 0; k < 2; ++k) dst[m][k] = *(const LAS bf16x8*)(lds + PG8_SA(b, h) + aoff + m * 2048 + k * 1024); } while (0)
; #define PG8_LDB(dst, b, h) do { _Pragma("unroll") for (int n = 0; n < 2; ++n) _Pragma("unroll") for (int k = 0; k < 2; ++k) dst[n][k] = *(const LAS bf16x8*)(lds + PG8_SB(b, h) + boff + n * 2048 + k * 1024); } while (0)
; #define PG8_WAIT_V(n) asm volatile("s_waitcnt vmcnt(" #n ")" ::: "memory")
; #define PG8_WAIT_L(n) asm volatile("s_waitcnt lgkmcnt(" #n ")" ::: "memory")
; #define PG8_BAR __builtin_amdgcn_s_barrier()
; #define PG8_SCHED __builtin_amdgcn_sched_barrier(0)
; template <bool F16, class Sched, class Epi>
; __device__ __forceinline__ void gemm_phase(LAS unsigned char* lds, const Gemm g, const Sched& S, const Epi& E, int wave_s) {
;     ...
;             PG8_WAIT_V(8); PG8_WAIT_L(0); PG8_BAR; PG8_MMA(1, 0, At, B0); PG8_MMA(1, 1, At, B1); PG8_BAR; PG8_SCHED;
;             PG8_LDB(B0, 1, 0); PG8_LDB(B1, 1, 1); PG8_SCHED; PG8_LDA(At, 1, 0); PG8_STAGE(PG8_SA(0, 1), a2 + hstepA, voffA);
;             PG8_WAIT_V(8); PG8_WAIT_L(0); PG8_BAR; PG8_MMA(0, 0, At, B0); PG8_MMA(0, 1, At, B1); PG8_BAR; PG8_SCHED;
	s_setprio 1
	s_waitcnt lgkmcnt(0)
	v_mfma_f32_16x16x32_bf16 v[60:63], v[138:141], v[178:181], v[60:63]
	v_mfma_f32_16x16x32_bf16 v[56:59], v[146:149], v[178:181], v[56:59]
	v_mfma_f32_16x16x32_bf16 v[52:55], v[138:141], v[186:189], v[52:55]
	v_mfma_f32_16x16x32_bf16 v[44:47], v[146:149], v[186:189], v[44:47]
	v_mfma_f32_16x16x32_bf16 v[36:39], v[138:141], v[208:211], v[36:39]
	v_mfma_f32_16x16x32_bf16 v[28:31], v[146:149], v[208:211], v[28:31]
	v_mfma_f32_16x16x32_bf16 v[20:23], v[138:141], v[216:219], v[20:23]
	v_mfma_f32_16x16x32_bf16 v[12:15], v[146:149], v[216:219], v[12:15]
	v_mfma_f32_16x16x32_bf16 v[60:63], v[142:145], v[182:185], v[60:63]
	v_mfma_f32_16x16x32_bf16 v[56:59], v[150:153], v[182:185], v[56:59]
	v_mfma_f32_16x16x32_bf16 v[52:55], v[142:145], v[190:193], v[52:55]
	v_mfma_f32_16x16x32_bf16 v[44:47], v[150:153], v[190:193], v[44:47]
	v_mfma_f32_16x16x32_bf16 v[36:39], v[142:145], v[212:215], v[36:39]
	v_mfma_f32_16x16x32_bf16 v[28:31], v[150:153], v[212:215], v[28:31]
	v_mfma_f32_16x16x32_bf16 v[20:23], v[142:145], v[220:223], v[20:23]
	v_mfma_f32_16x16x32_bf16 v[12:15], v[150:153], v[220:223], v[12:15]
	s_setprio 0
	s_setprio 1
	v_mfma_f32_16x16x32_bf16 v[48:51], v[154:157], v[178:181], v[48:51]
	v_mfma_f32_16x16x32_bf16 v[40:43], v[166:169], v[178:181], v[40:43]
	v_mfma_f32_16x16x32_bf16 v[32:35], v[154:157], v[186:189], v[32:35]
	v_mfma_f32_16x16x32_bf16 v[24:27], v[166:169], v[186:189], v[24:27]
	v_mfma_f32_16x16x32_bf16 v[16:19], v[154:157], v[208:211], v[16:19]
	v_mfma_f32_16x16x32_bf16 v[8:11], v[166:169], v[208:211], v[8:11]
	v_mfma_f32_16x16x32_bf16 v[4:7], v[154:157], v[216:219], v[4:7]
	v_mfma_f32_16x16x32_bf16 v[0:3], v[166:169], v[216:219], v[0:3]
	v_mfma_f32_16x16x32_bf16 v[48:51], v[158:161], v[182:185], v[48:51]
	v_mfma_f32_16x16x32_bf16 v[40:43], v[170:173], v[182:185], v[40:43]
	v_mfma_f32_16x16x32_bf16 v[32:35], v[158:161], v[190:193], v[32:35]
	v_mfma_f32_16x16x32_bf16 v[24:27], v[170:173], v[190:193], v[24:27]
	v_mfma_f32_16x16x32_bf16 v[16:19], v[158:161], v[212:215], v[16:19]
	v_mfma_f32_16x16x32_bf16 v[8:11], v[170:173], v[212:215], v[8:11]
	v_mfma_f32_16x16x32_bf16 v[4:7], v[158:161], v[220:223], v[4:7]
	v_mfma_f32_16x16x32_bf16 v[0:3], v[170:173], v[220:223], v[0:3]
	s_setprio 0
	s_barrier
	s_add_i32 s61, 0, 0x18000
	s_add_i32 s62, 0, 0x1c000
	v_add_u32_e32 v150, s61, v163
	v_add_u32_e32 v170, s62, v163
	ds_read_b128 v[138:141], v150
	ds_read_b128 v[142:145], v150 offset:1024
	ds_read_b128 v[146:149], v150 offset:2048
	ds_read_b128 v[150:153], v150 offset:3072
	ds_read_b128 v[154:157], v170
	ds_read_b128 v[158:161], v170 offset:1024
	ds_read_b128 v[166:169], v170 offset:2048
	ds_read_b128 v[170:173], v170 offset:3072
	s_mov_b32 m0, s45
	ds_read_b128 v[178:181], v165 offset:32768
	ds_read_b128 v[182:185], v165 offset:33792
	ds_read_b128 v[186:189], v165 offset:34816
	ds_read_b128 v[190:193], v165 offset:35840
	ds_read_b128 v[208:211], v165 offset:36864
	ds_read_b128 v[212:215], v165 offset:37888
	ds_read_b128 v[216:219], v165 offset:38912
	ds_read_b128 v[220:223], v165 offset:39936
	global_load_lds_dwordx4 v132, s[30:31]
	s_mov_b32 m0, s46
	s_nop 0
	global_load_lds_dwordx4 v130, s[30:31]
	s_waitcnt vmcnt(8)
	s_waitcnt lgkmcnt(0)
	s_barrier
	s_setprio 1
	s_waitcnt lgkmcnt(0)
	v_mfma_f32_16x16x32_bf16 v[124:127], v[138:141], v[178:181], v[124:127]
	v_mfma_f32_16x16x32_bf16 v[120:123], v[146:149], v[178:181], v[120:123]
	v_mfma_f32_16x16x32_bf16 v[108:111], v[138:141], v[186:189], v[108:111]
	v_mfma_f32_16x16x32_bf16 v[104:107], v[146:149], v[186:189], v[104:107]
	v_mfma_f32_16x16x32_bf16 v[96:99], v[138:141], v[208:211], v[96:99]
	v_mfma_f32_16x16x32_bf16 v[92:95], v[146:149], v[208:211], v[92:95]
	v_mfma_f32_16x16x32_bf16 v[84:87], v[138:141], v[216:219], v[84:87]
	v_mfma_f32_16x16x32_bf16 v[76:79], v[146:149], v[216:219], v[76:79]
	v_mfma_f32_16x16x32_bf16 v[124:127], v[142:145], v[182:185], v[124:127]
	v_mfma_f32_16x16x32_bf16 v[120:123], v[150:153], v[182:185], v[120:123]
	v_mfma_f32_16x16x32_bf16 v[108:111], v[142:145], v[190:193], v[108:111]
	v_mfma_f32_16x16x32_bf16 v[104:107], v[150:153], v[190:193], v[104:107]
	v_mfma_f32_16x16x32_bf16 v[96:99], v[142:145], v[212:215], v[96:99]
	v_mfma_f32_16x16x32_bf16 v[92:95], v[150:153], v[212:215], v[92:95]
	v_mfma_f32_16x16x32_bf16 v[84:87], v[142:145], v[220:223], v[84:87]
	v_mfma_f32_16x16x32_bf16 v[76:79], v[150:153], v[220:223], v[76:79]
	s_setprio 0
	s_setprio 1
	v_mfma_f32_16x16x32_bf16 v[116:119], v[154:157], v[178:181], v[116:119]
	v_mfma_f32_16x16x32_bf16 v[112:115], v[166:169], v[178:181], v[112:115]
	v_mfma_f32_16x16x32_bf16 v[100:103], v[154:157], v[186:189], v[100:103]
	v_mfma_f32_16x16x32_bf16 v[88:91], v[166:169], v[186:189], v[88:91]
	v_mfma_f32_16x16x32_bf16 v[80:83], v[154:157], v[208:211], v[80:83]
	v_mfma_f32_16x16x32_bf16 v[72:75], v[166:169], v[208:211], v[72:75]
	v_mfma_f32_16x16x32_bf16 v[68:71], v[154:157], v[216:219], v[68:71]
	v_mfma_f32_16x16x32_bf16 v[64:67], v[166:169], v[216:219], v[64:67]
	v_mfma_f32_16x16x32_bf16 v[116:119], v[158:161], v[182:185], v[116:119]
	v_mfma_f32_16x16x32_bf16 v[112:115], v[170:173], v[182:185], v[112:115]
	v_mfma_f32_16x16x32_bf16 v[100:103], v[158:161], v[190:193], v[100:103]
	v_mfma_f32_16x16x32_bf16 v[88:91], v[170:173], v[190:193], v[88:91]
	v_mfma_f32_16x16x32_bf16 v[80:83], v[158:161], v[212:215], v[80:83]
	v_mfma_f32_16x16x32_bf16 v[72:75], v[170:173], v[212:215], v[72:75]
	v_mfma_f32_16x16x32_bf16 v[68:71], v[158:161], v[220:223], v[68:71]
	v_mfma_f32_16x16x32_bf16 v[64:67], v[170:173], v[220:223], v[64:67]
	s_setprio 0
	s_barrier
; #define PG8_STAGE(bufoff, gbase, voff) do { _Pragma("unroll") for (int _i = 0; _i < 2; ++_i) \
;         __builtin_amdgcn_global_load_lds((const unsigned*)((const char*)(gbase) + (voff)[_i]), (LAS unsigned*)(lds + (bufoff) + ldsw + _i * 8192), 16, 0, 0); } while (0)
; #define PG8_LDA(dst, b, h) do { _Pragma("unroll") for (int m = 0; m < 4; ++m) _Pragma("unroll") for (int k = 0; k < 2; ++k) dst[m][k] = *(const LAS bf16x8*)(lds + PG8_SA(b, h) + aoff + m * 2048 + k * 1024); } while (0)
; #define PG8_WAIT_V(n) asm volatile("s_waitcnt vmcnt(" #n ")" ::: "memory")
; #define PG8_WAIT_L(n) asm volatile("s_waitcnt lgkmcnt(" #n ")" ::: "memory")
; #define PG8_BAR __builtin_amdgcn_s_barrier()
; #define PG8_SCHED __builtin_amdgcn_sched_barrier(0)
; template <bool F16, class Sched, class Epi>
; __device__ __forceinline__ void gemm_phase(LAS unsigned char* lds, const Gemm g, const Sched& S, const Epi& E, int wave_s) {
;     ...
;         for (int t = 0; t < nt; t += 2) {
;     ...
;             PG8_LDA(At, 1, 1); PG8_STAGE(PG8_SB(1, 0), b3, voffB); PG8_STAGE(PG8_SB(1, 1), b3 + hstepB, voffB); PG8_STAGE(PG8_SA(1, 0), a3, voffA);
;             PG8_WAIT_V(8); PG8_WAIT_L(0); PG8_BAR; PG8_MMA(1, 0, At, B0); PG8_MMA(1, 1, At, B1); PG8_BAR; PG8_SCHED;
	s_add_i32 s30, s61, s39
	v_lshl_add_u64 v[174:175], v[174:175], 0, s[54:55]
	s_mov_b32 m0, s30
	ds_read_b128 v[178:181], v165 offset:49152
	ds_read_b128 v[182:185], v165 offset:50176
	ds_read_b128 v[186:189], v165 offset:51200
	ds_read_b128 v[190:193], v165 offset:52224
	ds_read_b128 v[208:211], v165 offset:53248
	ds_read_b128 v[212:215], v165 offset:54272
	ds_read_b128 v[216:219], v165 offset:55296
	ds_read_b128 v[220:223], v165 offset:56320
	global_load_lds_dwordx4 v[174:175], off
	s_add_i32 m0, s30, 0x2000
	s_add_u32 s28, s28, 0x80080
	v_lshl_add_u64 v[174:175], v[194:195], 0, s[54:55]
	s_addc_u32 s29, s29, 0
	s_add_i32 s30, s62, s39
	global_load_lds_dwordx4 v[174:175], off
	v_lshl_add_u64 v[174:175], s[28:29], 0, v[176:177]
	s_mov_b32 m0, s30
	s_nop 0
	global_load_lds_dwordx4 v[174:175], off
	v_lshl_add_u64 v[174:175], s[28:29], 0, v[128:129]
	s_add_i32 m0, s30, 0x2000
	s_nop 0
	global_load_lds_dwordx4 v[174:175], off
	v_lshl_add_u64 v[174:175], v[198:199], 0, s[54:55]
	s_mov_b32 m0, s19
	s_nop 0
	global_load_lds_dwordx4 v[174:175], off
	v_lshl_add_u64 v[174:175], v[200:201], 0, s[54:55]
	s_mov_b32 m0, s47
	s_nop 0
	global_load_lds_dwordx4 v[174:175], off
	s_waitcnt vmcnt(8)
	s_waitcnt lgkmcnt(0)
	s_barrier
	s_setprio 1
	s_waitcnt lgkmcnt(0)
	v_mfma_f32_16x16x32_bf16 v[60:63], v[138:141], v[178:181], v[60:63]
	v_mfma_f32_16x16x32_bf16 v[56:59], v[146:149], v[178:181], v[56:59]
	v_mfma_f32_16x16x32_bf16 v[52:55], v[138:141], v[186:189], v[52:55]
	v_mfma_f32_16x16x32_bf16 v[44:47], v[146:149], v[186:189], v[44:47]
	v_mfma_f32_16x16x32_bf16 v[36:39], v[138:141], v[208:211], v[36:39]
	v_mfma_f32_16x16x32_bf16 v[28:31], v[146:149], v[208:211], v[28:31]
	v_mfma_f32_16x16x32_bf16 v[20:23], v[138:141], v[216:219], v[20:23]
	v_mfma_f32_16x16x32_bf16 v[12:15], v[146:149], v[216:219], v[12:15]
	v_mfma_f32_16x16x32_bf16 v[60:63], v[142:145], v[182:185], v[60:63]
	v_mfma_f32_16x16x32_bf16 v[56:59], v[150:153], v[182:185], v[56:59]
	v_mfma_f32_16x16x32_bf16 v[52:55], v[142:145], v[190:193], v[52:55]
	v_mfma_f32_16x16x32_bf16 v[44:47], v[150:153], v[190:193], v[44:47]
	v_mfma_f32_16x16x32_bf16 v[36:39], v[142:145], v[212:215], v[36:39]
	v_mfma_f32_16x16x32_bf16 v[28:31], v[150:153], v[212:215], v[28:31]
	v_mfma_f32_16x16x32_bf16 v[20:23], v[142:145], v[220:223], v[20:23]
	v_mfma_f32_16x16x32_bf16 v[12:15], v[150:153], v[220:223], v[12:15]
	s_setprio 0
	s_setprio 1
	v_mfma_f32_16x16x32_bf16 v[48:51], v[154:157], v[178:181], v[48:51]
	v_mfma_f32_16x16x32_bf16 v[40:43], v[166:169], v[178:181], v[40:43]
	v_mfma_f32_16x16x32_bf16 v[32:35], v[154:157], v[186:189], v[32:35]
	v_mfma_f32_16x16x32_bf16 v[24:27], v[166:169], v[186:189], v[24:27]
	v_mfma_f32_16x16x32_bf16 v[16:19], v[154:157], v[208:211], v[16:19]
	v_mfma_f32_16x16x32_bf16 v[8:11], v[166:169], v[208:211], v[8:11]
	v_mfma_f32_16x16x32_bf16 v[4:7], v[154:157], v[216:219], v[4:7]
	v_mfma_f32_16x16x32_bf16 v[0:3], v[166:169], v[216:219], v[0:3]
	v_mfma_f32_16x16x32_bf16 v[48:51], v[158:161], v[182:185], v[48:51]
	v_mfma_f32_16x16x32_bf16 v[40:43], v[170:173], v[182:185], v[40:43]
	v_mfma_f32_16x16x32_bf16 v[32:35], v[158:161], v[190:193], v[32:35]
	v_mfma_f32_16x16x32_bf16 v[24:27], v[170:173], v[190:193], v[24:27]
	v_mfma_f32_16x16x32_bf16 v[16:19], v[158:161], v[212:215], v[16:19]
	v_mfma_f32_16x16x32_bf16 v[8:11], v[170:173], v[212:215], v[8:11]
	v_mfma_f32_16x16x32_bf16 v[4:7], v[158:161], v[220:223], v[4:7]
	v_mfma_f32_16x16x32_bf16 v[0:3], v[170:173], v[220:223], v[0:3]
	s_add_i32 s60, s60, 2
	s_add_u32 s26, s26, 0x100
	s_addc_u32 s27, s27, 0
	s_add_u32 s58, s58, 0x100
	s_addc_u32 s59, s59, 0
	s_cmp_gt_u32 s60, 29
	s_setprio 0
	s_barrier
	s_cbranch_scc0 .LBB0_598
	s_and_b64 vcc, exec, s[14:15]
	s_cbranch_vccz .LBB0_601
	s_barrier

; #define PG8_STAGE(bufoff, gbase, voff) do { _Pragma("unroll") for (int _i = 0; _i < 2; ++_i) \
;         __builtin_amdgcn_global_load_lds((const unsigned*)((const char*)(gbase) + (voff)[_i]), (LAS unsigned*)(lds + (bufoff) + ldsw + _i * 8192), 16, 0, 0); } while (0)
; #define PG8_LDA(dst, b, h) do { _Pragma("unroll") for (int m = 0; m < 4; ++m) _Pragma("unroll") for (int k = 0; k < 2; ++k) dst[m][k] = *(const LAS bf16x8*)(lds + PG8_SA(b, h) + aoff + m * 2048 + k * 1024); } while (0)
; #define PG8_LDB(dst, b, h) do { _Pragma("unroll") for (int n = 0; n < 2; ++n) _Pragma("unroll") for (int k = 0; k < 2; ++k) dst[n][k] = *(const LAS bf16x8*)(lds + PG8_SB(b, h) + boff + n * 2048 + k * 1024); } while (0)
; #define PG8_WAIT_V(n) asm volatile("s_waitcnt vmcnt(" #n ")" ::: "memory")
; #define PG8_WAIT_L(n) asm volatile("s_waitcnt lgkmcnt(" #n ")" ::: "memory")
; #define PG8_BAR __builtin_amdgcn_s_barrier()
; #define PG8_SCHED __builtin_amdgcn_sched_barrier(0)
; template <bool F16, class Sched, class Epi>
; __device__ __forceinline__ void gemm_phase(LAS unsigned char* lds, const Gemm g, const Sched& S, const Epi& E, int wave_s) {
;     ...
;             const char* a2 = last ? nA : cA + (size_t)(t + 2) * kstep; const char* b2 = last ? nB : cB + (size_t)(t + 2) * kstep;
;             const char* a3 = a2 + kstep; const char* b3 = b2 + kstep;
;             PG8_LDB(B0, 0, 0); PG8_LDB(B1, 0, 1); PG8_SCHED; PG8_LDA(At, 0, 0); PG8_STAGE(PG8_SA(1, 1), a1 + hstepA, voffA);
;             PG8_WAIT_V(8); PG8_WAIT_L(0); PG8_BAR; PG8_MMA(0, 0, At, B0); PG8_MMA(0, 1, At, B1); PG8_BAR; PG8_SCHED;
;             PG8_LDA(At, 0, 1); PG8_STAGE(PG8_SB(0, 0), b2, voffB); PG8_STAGE(PG8_SB(0, 1), b2 + hstepB, voffB); PG8_STAGE(PG8_SA(0, 0), a2, voffA);
;             PG8_WAIT_V(8); PG8_WAIT_L(0); PG8_BAR; PG8_MMA(1, 0, At, B0); PG8_MMA(1, 1, At, B1); PG8_BAR; PG8_SCHED;
.LBB0_681:
	s_add_i32 s61, 0, 0x10000
	v_add_u32_e32 v146, s61, v149
	s_add_i32 s64, 0, 0x14000
	ds_read_b128 v[138:141], v146
	ds_read_b128 v[142:145], v146 offset:1024
	ds_read_b128 v[154:157], v146 offset:2048
	ds_read_b128 v[158:161], v146 offset:3072
	v_add_u32_e32 v146, s64, v149
	ds_read_b128 v[162:165], v146
	ds_read_b128 v[166:169], v146 offset:1024
	ds_read_b128 v[170:173], v146 offset:2048
	ds_read_b128 v[178:181], v146 offset:3072
	s_add_i32 m0, s39, 0xc000
	ds_read_b128 v[182:185], v152
	ds_read_b128 v[186:189], v152 offset:1024
	ds_read_b128 v[190:193], v152 offset:2048
	ds_read_b128 v[208:211], v152 offset:3072
	ds_read_b128 v[212:215], v152 offset:4096
	ds_read_b128 v[216:219], v152 offset:5120
	ds_read_b128 v[220:223], v152 offset:6144
	ds_read_b128 v[224:227], v152 offset:7168
	global_load_lds_dwordx4 v134, s[24:25]
	s_add_i32 m0, s39, 0xe000
	s_nop 0
	global_load_lds_dwordx4 v136, s[24:25]
	s_waitcnt vmcnt(8)
	s_waitcnt lgkmcnt(0)
	s_barrier
	s_setprio 1
	s_waitcnt lgkmcnt(0)
	v_mfma_f32_16x16x32_bf16 v[124:127], v[138:141], v[182:185], v[124:127]
	v_mfma_f32_16x16x32_bf16 v[116:119], v[154:157], v[182:185], v[116:119]
	v_mfma_f32_16x16x32_bf16 v[108:111], v[138:141], v[190:193], v[108:111]
	v_mfma_f32_16x16x32_bf16 v[100:103], v[154:157], v[190:193], v[100:103]
	v_mfma_f32_16x16x32_bf16 v[92:95], v[138:141], v[212:215], v[92:95]
	v_mfma_f32_16x16x32_bf16 v[84:87], v[154:157], v[212:215], v[84:87]
	v_mfma_f32_16x16x32_bf16 v[76:79], v[138:141], v[220:223], v[76:79]
	v_mfma_f32_16x16x32_bf16 v[68:71], v[154:157], v[220:223], v[68:71]
	v_mfma_f32_16x16x32_bf16 v[124:127], v[142:145], v[186:189], v[124:127]
	v_mfma_f32_16x16x32_bf16 v[116:119], v[158:161], v[186:189], v[116:119]
	v_mfma_f32_16x16x32_bf16 v[108:111], v[142:145], v[208:211], v[108:111]
	v_mfma_f32_16x16x32_bf16 v[100:103], v[158:161], v[208:211], v[100:103]
	v_mfma_f32_16x16x32_bf16 v[92:95], v[142:145], v[216:219], v[92:95]
	v_mfma_f32_16x16x32_bf16 v[84:87], v[158:161], v[216:219], v[84:87]
	v_mfma_f32_16x16x32_bf16 v[76:79], v[142:145], v[224:227], v[76:79]
	v_mfma_f32_16x16x32_bf16 v[68:71], v[158:161], v[224:227], v[68:71]
	s_setprio 0
	s_setprio 1
	v_mfma_f32_16x16x32_bf16 v[120:123], v[162:165], v[182:185], v[120:123]
	v_mfma_f32_16x16x32_bf16 v[112:115], v[170:173], v[182:185], v[112:115]
	v_mfma_f32_16x16x32_bf16 v[104:107], v[162:165], v[190:193], v[104:107]
	v_mfma_f32_16x16x32_bf16 v[96:99], v[170:173], v[190:193], v[96:99]
	v_mfma_f32_16x16x32_bf16 v[88:91], v[162:165], v[212:215], v[88:91]
	v_mfma_f32_16x16x32_bf16 v[80:83], v[170:173], v[212:215], v[80:83]
	v_mfma_f32_16x16x32_bf16 v[72:75], v[162:165], v[220:223], v[72:75]
	v_mfma_f32_16x16x32_bf16 v[64:67], v[170:173], v[220:223], v[64:67]
	v_mfma_f32_16x16x32_bf16 v[120:123], v[166:169], v[186:189], v[120:123]
	v_mfma_f32_16x16x32_bf16 v[112:115], v[178:181], v[186:189], v[112:115]
	v_mfma_f32_16x16x32_bf16 v[104:107], v[166:169], v[208:211], v[104:107]
	v_mfma_f32_16x16x32_bf16 v[96:99], v[178:181], v[208:211], v[96:99]
	v_mfma_f32_16x16x32_bf16 v[88:91], v[166:169], v[216:219], v[88:91]
	v_mfma_f32_16x16x32_bf16 v[80:83], v[178:181], v[216:219], v[80:83]
	v_mfma_f32_16x16x32_bf16 v[72:75], v[166:169], v[224:227], v[72:75]
	v_mfma_f32_16x16x32_bf16 v[64:67], v[178:181], v[224:227], v[64:67]
	s_setprio 0
	s_barrier
	s_add_u32 s26, s24, 0xfff80080
	s_addc_u32 s27, s25, -1
	s_cmp_eq_u32 s60, 28
	s_cselect_b32 s29, s49, s27
	s_cselect_b32 s28, s50, s26
	s_cselect_b32 s27, s52, s59
	s_cselect_b32 s26, s53, s58
	s_add_i32 s61, s61, s38
	v_lshl_add_u64 v[146:147], s[26:27], 0, v[176:177]
	s_mov_b32 m0, s61
	ds_read_b128 v[182:185], v152 offset:16384
	ds_read_b128 v[186:189], v152 offset:17408
	ds_read_b128 v[190:193], v152 offset:18432
	ds_read_b128 v[208:211], v152 offset:19456
	ds_read_b128 v[212:215], v152 offset:20480
	ds_read_b128 v[216:219], v152 offset:21504
	ds_read_b128 v[220:223], v152 offset:22528
	ds_read_b128 v[224:227], v152 offset:23552
	global_load_lds_dwordx4 v[146:147], off
	s_add_i32 m0, s61, 0x2000
	s_add_u32 s62, s26, 0x80000
	v_lshl_add_u64 v[174:175], s[26:27], 0, v[128:129]
	s_addc_u32 s63, s27, 0
	s_add_i32 s61, s64, s38
	global_load_lds_dwordx4 v[174:175], off
	v_lshl_add_u64 v[194:195], s[62:63], 0, v[176:177]
	s_mov_b32 m0, s61
	v_lshl_add_u64 v[198:199], s[28:29], 0, v[130:131]
	global_load_lds_dwordx4 v[194:195], off
	v_lshl_add_u64 v[194:195], s[62:63], 0, v[128:129]
	s_add_i32 m0, s61, 0x2000
	s_nop 0
	global_load_lds_dwordx4 v[194:195], off
	v_lshl_add_u64 v[194:195], s[28:29], 0, v[132:133]
	s_mov_b32 m0, s39
	s_nop 0
	global_load_lds_dwordx4 v[194:195], off
	s_mov_b32 m0, s43
	s_nop 0
	global_load_lds_dwordx4 v[198:199], off
	s_add_u32 s28, s28, 0x80000
	s_addc_u32 s29, s29, 0
	s_waitcnt vmcnt(8)
	s_waitcnt lgkmcnt(0)
	s_barrier
; #define PG8_STAGE(bufoff, gbase, voff) do { _Pragma("unroll") for (int _i = 0; _i < 2; ++_i) \
;         __builtin_amdgcn_global_load_lds((const unsigned*)((const char*)(gbase) + (voff)[_i]), (LAS unsigned*)(lds + (bufoff) + ldsw + _i * 8192), 16, 0, 0); } while (0)
; #define PG8_LDA(dst, b, h) do { _Pragma("unroll") for (int m = 0; m < 4; ++m) _Pragma("unroll") for (int k = 0; k < 2; ++k) dst[m][k] = *(const LAS bf16x8*)(lds + PG8_SA(b, h) + aoff + m * 2048 + k * 1024); } while (0)
; #define PG8_LDB(dst, b, h) do { _Pragma("unroll") for (int n = 0; n < 2; ++n) _Pragma("unroll") for (int k = 0; k < 2; ++k) dst[n][k] = *(const LAS bf16x8*)(lds + PG8_SB(b, h) + boff + n * 2048 + k * 1024); } while (0)
; #define PG8_WAIT_V(n) asm volatile("s_waitcnt vmcnt(" #n ")" ::: "memory")
; #define PG8_WAIT_L(n) asm volatile("s_waitcnt lgkmcnt(" #n ")" ::: "memory")
; #define PG8_BAR __builtin_amdgcn_s_barrier()
; #define PG8_SCHED __builtin_amdgcn_sched_barrier(0)
; template <bool F16, class Sched, class Epi>
; __device__ __forceinline__ void gemm_phase(LAS unsigned char* lds, const Gemm g, const Sched& S, const Epi& E, int wave_s) {
;     ...
;             PG8_WAIT_V(8); PG8_WAIT_L(0); PG8_BAR; PG8_MMA(1, 0, At, B0); PG8_MMA(1, 1, At, B1); PG8_BAR; PG8_SCHED;
;             PG8_LDB(B0, 1, 0); PG8_LDB(B1, 1, 1); PG8_SCHED; PG8_LDA(At, 1, 0); PG8_STAGE(PG8_SA(0, 1), a2 + hstepA, voffA);
;             PG8_WAIT_V(8); PG8_WAIT_L(0); PG8_BAR; PG8_MMA(0, 0, At, B0); PG8_MMA(0, 1, At, B1); PG8_BAR; PG8_SCHED;
	s_setprio 1
	s_waitcnt lgkmcnt(0)
	v_mfma_f32_16x16x32_bf16 v[60:63], v[138:141], v[182:185], v[60:63]
	v_mfma_f32_16x16x32_bf16 v[52:55], v[154:157], v[182:185], v[52:55]
	v_mfma_f32_16x16x32_bf16 v[44:47], v[138:141], v[190:193], v[44:47]
	v_mfma_f32_16x16x32_bf16 v[36:39], v[154:157], v[190:193], v[36:39]
	v_mfma_f32_16x16x32_bf16 v[28:31], v[138:141], v[212:215], v[28:31]
	v_mfma_f32_16x16x32_bf16 v[20:23], v[154:157], v[212:215], v[20:23]
	v_mfma_f32_16x16x32_bf16 v[12:15], v[138:141], v[220:223], v[12:15]
	v_mfma_f32_16x16x32_bf16 v[4:7], v[154:157], v[220:223], v[4:7]
	v_mfma_f32_16x16x32_bf16 v[60:63], v[142:145], v[186:189], v[60:63]
	v_mfma_f32_16x16x32_bf16 v[52:55], v[158:161], v[186:189], v[52:55]
	v_mfma_f32_16x16x32_bf16 v[44:47], v[142:145], v[208:211], v[44:47]
	v_mfma_f32_16x16x32_bf16 v[36:39], v[158:161], v[208:211], v[36:39]
	v_mfma_f32_16x16x32_bf16 v[28:31], v[142:145], v[216:219], v[28:31]
	v_mfma_f32_16x16x32_bf16 v[20:23], v[158:161], v[216:219], v[20:23]
	v_mfma_f32_16x16x32_bf16 v[12:15], v[142:145], v[224:227], v[12:15]
	v_mfma_f32_16x16x32_bf16 v[4:7], v[158:161], v[224:227], v[4:7]
	s_setprio 0
	s_setprio 1
	v_mfma_f32_16x16x32_bf16 v[56:59], v[162:165], v[182:185], v[56:59]
	v_mfma_f32_16x16x32_bf16 v[48:51], v[170:173], v[182:185], v[48:51]
	v_mfma_f32_16x16x32_bf16 v[40:43], v[162:165], v[190:193], v[40:43]
	v_mfma_f32_16x16x32_bf16 v[32:35], v[170:173], v[190:193], v[32:35]
	v_mfma_f32_16x16x32_bf16 v[24:27], v[162:165], v[212:215], v[24:27]
	v_mfma_f32_16x16x32_bf16 v[16:19], v[170:173], v[212:215], v[16:19]
	v_mfma_f32_16x16x32_bf16 v[8:11], v[162:165], v[220:223], v[8:11]
	v_mfma_f32_16x16x32_bf16 v[0:3], v[170:173], v[220:223], v[0:3]
	v_mfma_f32_16x16x32_bf16 v[56:59], v[166:169], v[186:189], v[56:59]
	v_mfma_f32_16x16x32_bf16 v[48:51], v[178:181], v[186:189], v[48:51]
	v_mfma_f32_16x16x32_bf16 v[40:43], v[166:169], v[208:211], v[40:43]
	v_mfma_f32_16x16x32_bf16 v[32:35], v[178:181], v[208:211], v[32:35]
	v_mfma_f32_16x16x32_bf16 v[24:27], v[166:169], v[216:219], v[24:27]
	v_mfma_f32_16x16x32_bf16 v[16:19], v[178:181], v[216:219], v[16:19]
	v_mfma_f32_16x16x32_bf16 v[8:11], v[166:169], v[224:227], v[8:11]
	v_mfma_f32_16x16x32_bf16 v[0:3], v[178:181], v[224:227], v[0:3]
	s_setprio 0
	s_barrier
	s_add_i32 s61, 0, 0x18000
	v_add_u32_e32 v153, s61, v149
	s_add_i32 s62, 0, 0x1c000
	ds_read_b128 v[138:141], v153
	ds_read_b128 v[142:145], v153 offset:1024
	ds_read_b128 v[154:157], v153 offset:2048
	ds_read_b128 v[158:161], v153 offset:3072
	v_add_u32_e32 v153, s62, v149
	ds_read_b128 v[162:165], v153
	ds_read_b128 v[166:169], v153 offset:1024
	ds_read_b128 v[170:173], v153 offset:2048
	ds_read_b128 v[178:181], v153 offset:3072
	s_mov_b32 m0, s44
	ds_read_b128 v[182:185], v152 offset:32768
	ds_read_b128 v[186:189], v152 offset:33792
	ds_read_b128 v[190:193], v152 offset:34816
	ds_read_b128 v[208:211], v152 offset:35840
	ds_read_b128 v[212:215], v152 offset:36864
	ds_read_b128 v[216:219], v152 offset:37888
	ds_read_b128 v[220:223], v152 offset:38912
	ds_read_b128 v[224:227], v152 offset:39936
	global_load_lds_dwordx4 v132, s[28:29]
	s_mov_b32 m0, s45
	s_nop 0
	global_load_lds_dwordx4 v130, s[28:29]
	s_waitcnt vmcnt(8)
	s_waitcnt lgkmcnt(0)
	s_barrier
	s_setprio 1
	s_waitcnt lgkmcnt(0)
	v_mfma_f32_16x16x32_bf16 v[124:127], v[138:141], v[182:185], v[124:127]
	v_mfma_f32_16x16x32_bf16 v[116:119], v[154:157], v[182:185], v[116:119]
	v_mfma_f32_16x16x32_bf16 v[108:111], v[138:141], v[190:193], v[108:111]
	v_mfma_f32_16x16x32_bf16 v[100:103], v[154:157], v[190:193], v[100:103]
	v_mfma_f32_16x16x32_bf16 v[92:95], v[138:141], v[212:215], v[92:95]
	v_mfma_f32_16x16x32_bf16 v[84:87], v[154:157], v[212:215], v[84:87]
	v_mfma_f32_16x16x32_bf16 v[76:79], v[138:141], v[220:223], v[76:79]
	v_mfma_f32_16x16x32_bf16 v[68:71], v[154:157], v[220:223], v[68:71]
	v_mfma_f32_16x16x32_bf16 v[124:127], v[142:145], v[186:189], v[124:127]
	v_mfma_f32_16x16x32_bf16 v[116:119], v[158:161], v[186:189], v[116:119]
	v_mfma_f32_16x16x32_bf16 v[108:111], v[142:145], v[208:211], v[108:111]
	v_mfma_f32_16x16x32_bf16 v[100:103], v[158:161], v[208:211], v[100:103]
	v_mfma_f32_16x16x32_bf16 v[92:95], v[142:145], v[216:219], v[92:95]
	v_mfma_f32_16x16x32_bf16 v[84:87], v[158:161], v[216:219], v[84:87]
	v_mfma_f32_16x16x32_bf16 v[76:79], v[142:145], v[224:227], v[76:79]
	v_mfma_f32_16x16x32_bf16 v[68:71], v[158:161], v[224:227], v[68:71]
	s_setprio 0
	s_setprio 1
	v_mfma_f32_16x16x32_bf16 v[120:123], v[162:165], v[182:185], v[120:123]
	v_mfma_f32_16x16x32_bf16 v[112:115], v[170:173], v[182:185], v[112:115]
	v_mfma_f32_16x16x32_bf16 v[104:107], v[162:165], v[190:193], v[104:107]
	v_mfma_f32_16x16x32_bf16 v[96:99], v[170:173], v[190:193], v[96:99]
	v_mfma_f32_16x16x32_bf16 v[88:91], v[162:165], v[212:215], v[88:91]
	v_mfma_f32_16x16x32_bf16 v[80:83], v[170:173], v[212:215], v[80:83]
	v_mfma_f32_16x16x32_bf16 v[72:75], v[162:165], v[220:223], v[72:75]
	v_mfma_f32_16x16x32_bf16 v[64:67], v[170:173], v[220:223], v[64:67]
	v_mfma_f32_16x16x32_bf16 v[120:123], v[166:169], v[186:189], v[120:123]
	v_mfma_f32_16x16x32_bf16 v[112:115], v[178:181], v[186:189], v[112:115]
	v_mfma_f32_16x16x32_bf16 v[104:107], v[166:169], v[208:211], v[104:107]
	v_mfma_f32_16x16x32_bf16 v[96:99], v[178:181], v[208:211], v[96:99]
	v_mfma_f32_16x16x32_bf16 v[88:91], v[166:169], v[216:219], v[88:91]
	v_mfma_f32_16x16x32_bf16 v[80:83], v[178:181], v[216:219], v[80:83]
	v_mfma_f32_16x16x32_bf16 v[72:75], v[166:169], v[224:227], v[72:75]
	v_mfma_f32_16x16x32_bf16 v[64:67], v[178:181], v[224:227], v[64:67]
	s_setprio 0
	s_barrier
; #define PG8_STAGE(bufoff, gbase, voff) do { _Pragma("unroll") for (int _i = 0; _i < 2; ++_i) \
;         __builtin_amdgcn_global_load_lds((const unsigned*)((const char*)(gbase) + (voff)[_i]), (LAS unsigned*)(lds + (bufoff) + ldsw + _i * 8192), 16, 0, 0); } while (0)
; #define PG8_LDA(dst, b, h) do { _Pragma("unroll") for (int m = 0; m < 4; ++m) _Pragma("unroll") for (int k = 0; k < 2; ++k) dst[m][k] = *(const LAS bf16x8*)(lds + PG8_SA(b, h) + aoff + m * 2048 + k * 1024); } while (0)
; #define PG8_WAIT_V(n) asm volatile("s_waitcnt vmcnt(" #n ")" ::: "memory")
; #define PG8_WAIT_L(n) asm volatile("s_waitcnt lgkmcnt(" #n ")" ::: "memory")
; #define PG8_BAR __builtin_amdgcn_s_barrier()
; #define PG8_SCHED __builtin_amdgcn_sched_barrier(0)
; template <bool F16, class Sched, class Epi>
; __device__ __forceinline__ void gemm_phase(LAS unsigned char* lds, const Gemm g, const Sched& S, const Epi& E, int wave_s) {
;     ...
;         for (int t = 0; t < nt; t += 2) {
;     ...
;             PG8_LDA(At, 1, 1); PG8_STAGE(PG8_SB(1, 0), b3, voffB); PG8_STAGE(PG8_SB(1, 1), b3 + hstepB, voffB); PG8_STAGE(PG8_SA(1, 0), a3, voffA);
;             PG8_WAIT_V(8); PG8_WAIT_L(0); PG8_BAR; PG8_MMA(1, 0, At, B0); PG8_MMA(1, 1, At, B1); PG8_BAR; PG8_SCHED;
	s_add_i32 s28, s61, s38
	v_lshl_add_u64 v[146:147], v[146:147], 0, s[54:55]
	s_mov_b32 m0, s28
	ds_read_b128 v[182:185], v152 offset:49152
	ds_read_b128 v[186:189], v152 offset:50176
	ds_read_b128 v[190:193], v152 offset:51200
	ds_read_b128 v[208:211], v152 offset:52224
	ds_read_b128 v[212:215], v152 offset:53248
	ds_read_b128 v[216:219], v152 offset:54272
	ds_read_b128 v[220:223], v152 offset:55296
	ds_read_b128 v[224:227], v152 offset:56320
	global_load_lds_dwordx4 v[146:147], off
	s_add_i32 m0, s28, 0x2000
	s_add_u32 s26, s26, 0x80080
	v_lshl_add_u64 v[146:147], v[174:175], 0, s[54:55]
	s_addc_u32 s27, s27, 0
	s_add_i32 s28, s62, s38
	global_load_lds_dwordx4 v[146:147], off
	v_lshl_add_u64 v[146:147], s[26:27], 0, v[176:177]
	s_mov_b32 m0, s28
	s_nop 0
	global_load_lds_dwordx4 v[146:147], off
	v_lshl_add_u64 v[146:147], s[26:27], 0, v[128:129]
	s_add_i32 m0, s28, 0x2000
	s_nop 0
	global_load_lds_dwordx4 v[146:147], off
	v_lshl_add_u64 v[146:147], v[194:195], 0, s[54:55]
	s_mov_b32 m0, s46
	s_nop 0
	global_load_lds_dwordx4 v[146:147], off
	v_lshl_add_u64 v[146:147], v[198:199], 0, s[54:55]
	s_mov_b32 m0, s47
	s_nop 0
	global_load_lds_dwordx4 v[146:147], off
	s_waitcnt vmcnt(8)
	s_waitcnt lgkmcnt(0)
	s_barrier
	s_setprio 1
	s_waitcnt lgkmcnt(0)
	v_mfma_f32_16x16x32_bf16 v[60:63], v[138:141], v[182:185], v[60:63]
	v_mfma_f32_16x16x32_bf16 v[52:55], v[154:157], v[182:185], v[52:55]
	v_mfma_f32_16x16x32_bf16 v[44:47], v[138:141], v[190:193], v[44:47]
	v_mfma_f32_16x16x32_bf16 v[36:39], v[154:157], v[190:193], v[36:39]
	v_mfma_f32_16x16x32_bf16 v[28:31], v[138:141], v[212:215], v[28:31]
	v_mfma_f32_16x16x32_bf16 v[20:23], v[154:157], v[212:215], v[20:23]
	v_mfma_f32_16x16x32_bf16 v[12:15], v[138:141], v[220:223], v[12:15]
	v_mfma_f32_16x16x32_bf16 v[4:7], v[154:157], v[220:223], v[4:7]
	v_mfma_f32_16x16x32_bf16 v[60:63], v[142:145], v[186:189], v[60:63]
	v_mfma_f32_16x16x32_bf16 v[52:55], v[158:161], v[186:189], v[52:55]
	v_mfma_f32_16x16x32_bf16 v[44:47], v[142:145], v[208:211], v[44:47]
	v_mfma_f32_16x16x32_bf16 v[36:39], v[158:161], v[208:211], v[36:39]
	v_mfma_f32_16x16x32_bf16 v[28:31], v[142:145], v[216:219], v[28:31]
	v_mfma_f32_16x16x32_bf16 v[20:23], v[158:161], v[216:219], v[20:23]
	v_mfma_f32_16x16x32_bf16 v[12:15], v[142:145], v[224:227], v[12:15]
	v_mfma_f32_16x16x32_bf16 v[4:7], v[158:161], v[224:227], v[4:7]
	s_setprio 0
	s_setprio 1
	v_mfma_f32_16x16x32_bf16 v[56:59], v[162:165], v[182:185], v[56:59]
	v_mfma_f32_16x16x32_bf16 v[48:51], v[170:173], v[182:185], v[48:51]
	v_mfma_f32_16x16x32_bf16 v[40:43], v[162:165], v[190:193], v[40:43]
	v_mfma_f32_16x16x32_bf16 v[32:35], v[170:173], v[190:193], v[32:35]
	v_mfma_f32_16x16x32_bf16 v[24:27], v[162:165], v[212:215], v[24:27]
	v_mfma_f32_16x16x32_bf16 v[16:19], v[170:173], v[212:215], v[16:19]
	v_mfma_f32_16x16x32_bf16 v[8:11], v[162:165], v[220:223], v[8:11]
	v_mfma_f32_16x16x32_bf16 v[0:3], v[170:173], v[220:223], v[0:3]
	v_mfma_f32_16x16x32_bf16 v[56:59], v[166:169], v[186:189], v[56:59]
	v_mfma_f32_16x16x32_bf16 v[48:51], v[178:181], v[186:189], v[48:51]
	v_mfma_f32_16x16x32_bf16 v[40:43], v[166:169], v[208:211], v[40:43]
	v_mfma_f32_16x16x32_bf16 v[32:35], v[178:181], v[208:211], v[32:35]
	v_mfma_f32_16x16x32_bf16 v[24:27], v[166:169], v[216:219], v[24:27]
	v_mfma_f32_16x16x32_bf16 v[16:19], v[178:181], v[216:219], v[16:19]
	v_mfma_f32_16x16x32_bf16 v[8:11], v[166:169], v[224:227], v[8:11]
	v_mfma_f32_16x16x32_bf16 v[0:3], v[178:181], v[224:227], v[0:3]
	s_add_i32 s60, s60, 2
	s_add_u32 s24, s24, 0x100
	s_addc_u32 s25, s25, 0
	s_add_u32 s58, s58, 0x100
	s_addc_u32 s59, s59, 0
	s_cmp_gt_u32 s60, 29
	s_setprio 0
	s_barrier
	s_cbranch_scc0 .LBB0_681
	s_and_b64 vcc, exec, s[12:13]
	s_cbranch_vccz .LBB0_684
	s_barrier

; #define PG8_STAGE(bufoff, gbase, voff) do { _Pragma("unroll") for (int _i = 0; _i < 2; ++_i) \
;         __builtin_amdgcn_global_load_lds((const unsigned*)((const char*)(gbase) + (voff)[_i]), (LAS unsigned*)(lds + (bufoff) + ldsw + _i * 8192), 16, 0, 0); } while (0)
; #define PG8_LDA(dst, b, h) do { _Pragma("unroll") for (int m = 0; m < 4; ++m) _Pragma("unroll") for (int k = 0; k < 2; ++k) dst[m][k] = *(const LAS bf16x8*)(lds + PG8_SA(b, h) + aoff + m * 2048 + k * 1024); } while (0)
; #define PG8_LDB(dst, b, h) do { _Pragma("unroll") for (int n = 0; n < 2; ++n) _Pragma("unroll") for (int k = 0; k < 2; ++k) dst[n][k] = *(const LAS bf16x8*)(lds + PG8_SB(b, h) + boff + n * 2048 + k * 1024); } while (0)
; #define PG8_WAIT_V(n) asm volatile("s_waitcnt vmcnt(" #n ")" ::: "memory")
; #define PG8_WAIT_L(n) asm volatile("s_waitcnt lgkmcnt(" #n ")" ::: "memory")
; #define PG8_BAR __builtin_amdgcn_s_barrier()
; #define PG8_SCHED __builtin_amdgcn_sched_barrier(0)
; template <bool F16, class Sched, class Epi>
; __device__ __forceinline__ void gemm_phase(LAS unsigned char* lds, const Gemm g, const Sched& S, const Epi& E, int wave_s) {
;     ...
;             const char* a2 = last ? nA : cA + (size_t)(t + 2) * kstep; const char* b2 = last ? nB : cB + (size_t)(t + 2) * kstep;
;             const char* a3 = a2 + kstep; const char* b3 = b2 + kstep;
;             PG8_LDB(B0, 0, 0); PG8_LDB(B1, 0, 1); PG8_SCHED; PG8_LDA(At, 0, 0); PG8_STAGE(PG8_SA(1, 1), a1 + hstepA, voffA);
;             PG8_WAIT_V(8); PG8_WAIT_L(0); PG8_BAR; PG8_MMA(0, 0, At, B0); PG8_MMA(0, 1, At, B1); PG8_BAR; PG8_SCHED;
;             PG8_LDA(At, 0, 1); PG8_STAGE(PG8_SB(0, 0), b2, voffB); PG8_STAGE(PG8_SB(0, 1), b2 + hstepB, voffB); PG8_STAGE(PG8_SA(0, 0), a2, voffA);
;             PG8_WAIT_V(8); PG8_WAIT_L(0); PG8_BAR; PG8_MMA(1, 0, At, B0); PG8_MMA(1, 1, At, B1); PG8_BAR; PG8_SCHED;
.LBB0_795:
	s_add_i32 s64, 0, 0x10000
	s_add_i32 s65, 0, 0x14000
	v_add_u32_e32 v150, s64, v163
	v_add_u32_e32 v170, s65, v163
	ds_read_b128 v[138:141], v150
	ds_read_b128 v[142:145], v150 offset:1024
	ds_read_b128 v[146:149], v150 offset:2048
	ds_read_b128 v[150:153], v150 offset:3072
	ds_read_b128 v[154:157], v170
	ds_read_b128 v[158:161], v170 offset:1024
	ds_read_b128 v[166:169], v170 offset:2048
	ds_read_b128 v[170:173], v170 offset:3072
	v_lshl_add_u64 v[174:175], s[28:29], 0, v[134:135]
	s_add_i32 m0, s46, 0xc000
	ds_read_b128 v[178:181], v165
	ds_read_b128 v[182:185], v165 offset:1024
	ds_read_b128 v[186:189], v165 offset:2048
	ds_read_b128 v[190:193], v165 offset:3072
	ds_read_b128 v[198:201], v165 offset:4096
	ds_read_b128 v[208:211], v165 offset:5120
	ds_read_b128 v[212:215], v165 offset:6144
	ds_read_b128 v[216:219], v165 offset:7168
	global_load_lds_dwordx4 v[174:175], off
	v_lshl_add_u64 v[174:175], s[28:29], 0, v[136:137]
	s_add_i32 m0, s46, 0xe000
	s_nop 0
	global_load_lds_dwordx4 v[174:175], off
	s_waitcnt vmcnt(8)
	s_waitcnt lgkmcnt(0)
	s_barrier
	s_setprio 1
	s_waitcnt lgkmcnt(0)
	v_mfma_f32_16x16x32_bf16 v[124:127], v[138:141], v[178:181], v[124:127]
	v_mfma_f32_16x16x32_bf16 v[120:123], v[146:149], v[178:181], v[120:123]
	v_mfma_f32_16x16x32_bf16 v[108:111], v[138:141], v[186:189], v[108:111]
	v_mfma_f32_16x16x32_bf16 v[104:107], v[146:149], v[186:189], v[104:107]
	v_mfma_f32_16x16x32_bf16 v[96:99], v[138:141], v[198:201], v[96:99]
	v_mfma_f32_16x16x32_bf16 v[92:95], v[146:149], v[198:201], v[92:95]
	v_mfma_f32_16x16x32_bf16 v[84:87], v[138:141], v[212:215], v[84:87]
	v_mfma_f32_16x16x32_bf16 v[76:79], v[146:149], v[212:215], v[76:79]
	v_mfma_f32_16x16x32_bf16 v[124:127], v[142:145], v[182:185], v[124:127]
	v_mfma_f32_16x16x32_bf16 v[120:123], v[150:153], v[182:185], v[120:123]
	v_mfma_f32_16x16x32_bf16 v[108:111], v[142:145], v[190:193], v[108:111]
	v_mfma_f32_16x16x32_bf16 v[104:107], v[150:153], v[190:193], v[104:107]
	v_mfma_f32_16x16x32_bf16 v[96:99], v[142:145], v[208:211], v[96:99]
	v_mfma_f32_16x16x32_bf16 v[92:95], v[150:153], v[208:211], v[92:95]
	v_mfma_f32_16x16x32_bf16 v[84:87], v[142:145], v[216:219], v[84:87]
	v_mfma_f32_16x16x32_bf16 v[76:79], v[150:153], v[216:219], v[76:79]
	s_setprio 0
	s_setprio 1
	v_mfma_f32_16x16x32_bf16 v[116:119], v[154:157], v[178:181], v[116:119]
	v_mfma_f32_16x16x32_bf16 v[112:115], v[166:169], v[178:181], v[112:115]
	v_mfma_f32_16x16x32_bf16 v[100:103], v[154:157], v[186:189], v[100:103]
	v_mfma_f32_16x16x32_bf16 v[88:91], v[166:169], v[186:189], v[88:91]
	v_mfma_f32_16x16x32_bf16 v[80:83], v[154:157], v[198:201], v[80:83]
	v_mfma_f32_16x16x32_bf16 v[72:75], v[166:169], v[198:201], v[72:75]
	v_mfma_f32_16x16x32_bf16 v[68:71], v[154:157], v[212:215], v[68:71]
	v_mfma_f32_16x16x32_bf16 v[64:67], v[166:169], v[212:215], v[64:67]
	v_mfma_f32_16x16x32_bf16 v[116:119], v[158:161], v[182:185], v[116:119]
	v_mfma_f32_16x16x32_bf16 v[112:115], v[170:173], v[182:185], v[112:115]
	v_mfma_f32_16x16x32_bf16 v[100:103], v[158:161], v[190:193], v[100:103]
	v_mfma_f32_16x16x32_bf16 v[88:91], v[170:173], v[190:193], v[88:91]
	v_mfma_f32_16x16x32_bf16 v[80:83], v[158:161], v[208:211], v[80:83]
	v_mfma_f32_16x16x32_bf16 v[72:75], v[170:173], v[208:211], v[72:75]
	v_mfma_f32_16x16x32_bf16 v[68:71], v[158:161], v[216:219], v[68:71]
	v_mfma_f32_16x16x32_bf16 v[64:67], v[170:173], v[216:219], v[64:67]
	s_setprio 0
	s_barrier
	s_add_u32 s30, s28, 0x100
	s_addc_u32 s31, s29, 0
	s_cmpk_eq_i32 s63, 0x54
	s_cselect_b32 s37, s15, s31
	s_cselect_b32 s36, s14, s30
	s_cselect_b32 s35, s27, s1
	s_cselect_b32 s34, s26, s0
	s_add_i32 s28, s64, s45
	v_lshl_add_u64 v[174:175], s[34:35], 0, v[176:177]
	s_mov_b32 m0, s28
	ds_read_b128 v[178:181], v165 offset:16384
	ds_read_b128 v[182:185], v165 offset:17408
	ds_read_b128 v[186:189], v165 offset:18432
	ds_read_b128 v[190:193], v165 offset:19456
	ds_read_b128 v[198:201], v165 offset:20480
	ds_read_b128 v[208:211], v165 offset:21504
	ds_read_b128 v[212:215], v165 offset:22528
	ds_read_b128 v[216:219], v165 offset:23552
	global_load_lds_dwordx4 v[174:175], off
	s_add_i32 m0, s28, 0x2000
	s_add_u32 s28, s34, 0x160000
	v_lshl_add_u64 v[194:195], s[34:35], 0, v[128:129]
	s_addc_u32 s29, s35, 0
	s_add_i32 s64, s65, s45
	global_load_lds_dwordx4 v[194:195], off
	v_lshl_add_u64 v[202:203], s[28:29], 0, v[176:177]
	s_mov_b32 m0, s64
	v_lshl_add_u64 v[220:221], s[36:37], 0, v[130:131]
	global_load_lds_dwordx4 v[202:203], off
	v_lshl_add_u64 v[202:203], s[28:29], 0, v[128:129]
	s_add_i32 m0, s64, 0x2000
	s_nop 0
	global_load_lds_dwordx4 v[202:203], off
	v_lshl_add_u64 v[202:203], s[36:37], 0, v[132:133]
	s_mov_b32 m0, s46
	s_nop 0
	global_load_lds_dwordx4 v[202:203], off
	s_mov_b32 m0, s47
	s_nop 0
	global_load_lds_dwordx4 v[220:221], off
	s_add_u32 s28, s36, 0x160000
	s_addc_u32 s29, s37, 0
	s_waitcnt vmcnt(8)
	s_waitcnt lgkmcnt(0)
	s_barrier
; #define PG8_STAGE(bufoff, gbase, voff) do { _Pragma("unroll") for (int _i = 0; _i < 2; ++_i) \
;         __builtin_amdgcn_global_load_lds((const unsigned*)((const char*)(gbase) + (voff)[_i]), (LAS unsigned*)(lds + (bufoff) + ldsw + _i * 8192), 16, 0, 0); } while (0)
; #define PG8_LDA(dst, b, h) do { _Pragma("unroll") for (int m = 0; m < 4; ++m) _Pragma("unroll") for (int k = 0; k < 2; ++k) dst[m][k] = *(const LAS bf16x8*)(lds + PG8_SA(b, h) + aoff + m * 2048 + k * 1024); } while (0)
; #define PG8_LDB(dst, b, h) do { _Pragma("unroll") for (int n = 0; n < 2; ++n) _Pragma("unroll") for (int k = 0; k < 2; ++k) dst[n][k] = *(const LAS bf16x8*)(lds + PG8_SB(b, h) + boff + n * 2048 + k * 1024); } while (0)
; #define PG8_WAIT_V(n) asm volatile("s_waitcnt vmcnt(" #n ")" ::: "memory")
; #define PG8_WAIT_L(n) asm volatile("s_waitcnt lgkmcnt(" #n ")" ::: "memory")
; #define PG8_BAR __builtin_amdgcn_s_barrier()
; #define PG8_SCHED __builtin_amdgcn_sched_barrier(0)
; template <bool F16, class Sched, class Epi>
; __device__ __forceinline__ void gemm_phase(LAS unsigned char* lds, const Gemm g, const Sched& S, const Epi& E, int wave_s) {
;     ...
;             PG8_WAIT_V(8); PG8_WAIT_L(0); PG8_BAR; PG8_MMA(1, 0, At, B0); PG8_MMA(1, 1, At, B1); PG8_BAR; PG8_SCHED;
;             PG8_LDB(B0, 1, 0); PG8_LDB(B1, 1, 1); PG8_SCHED; PG8_LDA(At, 1, 0); PG8_STAGE(PG8_SA(0, 1), a2 + hstepA, voffA);
;             PG8_WAIT_V(8); PG8_WAIT_L(0); PG8_BAR; PG8_MMA(0, 0, At, B0); PG8_MMA(0, 1, At, B1); PG8_BAR; PG8_SCHED;
	s_setprio 1
	s_waitcnt lgkmcnt(0)
	v_mfma_f32_16x16x32_bf16 v[60:63], v[138:141], v[178:181], v[60:63]
	v_mfma_f32_16x16x32_bf16 v[56:59], v[146:149], v[178:181], v[56:59]
	v_mfma_f32_16x16x32_bf16 v[52:55], v[138:141], v[186:189], v[52:55]
	v_mfma_f32_16x16x32_bf16 v[44:47], v[146:149], v[186:189], v[44:47]
	v_mfma_f32_16x16x32_bf16 v[36:39], v[138:141], v[198:201], v[36:39]
	v_mfma_f32_16x16x32_bf16 v[28:31], v[146:149], v[198:201], v[28:31]
	v_mfma_f32_16x16x32_bf16 v[20:23], v[138:141], v[212:215], v[20:23]
	v_mfma_f32_16x16x32_bf16 v[12:15], v[146:149], v[212:215], v[12:15]
	v_mfma_f32_16x16x32_bf16 v[60:63], v[142:145], v[182:185], v[60:63]
	v_mfma_f32_16x16x32_bf16 v[56:59], v[150:153], v[182:185], v[56:59]
	v_mfma_f32_16x16x32_bf16 v[52:55], v[142:145], v[190:193], v[52:55]
	v_mfma_f32_16x16x32_bf16 v[44:47], v[150:153], v[190:193], v[44:47]
	v_mfma_f32_16x16x32_bf16 v[36:39], v[142:145], v[208:211], v[36:39]
	v_mfma_f32_16x16x32_bf16 v[28:31], v[150:153], v[208:211], v[28:31]
	v_mfma_f32_16x16x32_bf16 v[20:23], v[142:145], v[216:219], v[20:23]
	v_mfma_f32_16x16x32_bf16 v[12:15], v[150:153], v[216:219], v[12:15]
	s_setprio 0
	s_setprio 1
	v_mfma_f32_16x16x32_bf16 v[48:51], v[154:157], v[178:181], v[48:51]
	v_mfma_f32_16x16x32_bf16 v[40:43], v[166:169], v[178:181], v[40:43]
	v_mfma_f32_16x16x32_bf16 v[32:35], v[154:157], v[186:189], v[32:35]
	v_mfma_f32_16x16x32_bf16 v[24:27], v[166:169], v[186:189], v[24:27]
	v_mfma_f32_16x16x32_bf16 v[16:19], v[154:157], v[198:201], v[16:19]
	v_mfma_f32_16x16x32_bf16 v[8:11], v[166:169], v[198:201], v[8:11]
	v_mfma_f32_16x16x32_bf16 v[4:7], v[154:157], v[212:215], v[4:7]
	v_mfma_f32_16x16x32_bf16 v[0:3], v[166:169], v[212:215], v[0:3]
	v_mfma_f32_16x16x32_bf16 v[48:51], v[158:161], v[182:185], v[48:51]
	v_mfma_f32_16x16x32_bf16 v[40:43], v[170:173], v[182:185], v[40:43]
	v_mfma_f32_16x16x32_bf16 v[32:35], v[158:161], v[190:193], v[32:35]
	v_mfma_f32_16x16x32_bf16 v[24:27], v[170:173], v[190:193], v[24:27]
	v_mfma_f32_16x16x32_bf16 v[16:19], v[158:161], v[208:211], v[16:19]
	v_mfma_f32_16x16x32_bf16 v[8:11], v[170:173], v[208:211], v[8:11]
	v_mfma_f32_16x16x32_bf16 v[4:7], v[158:161], v[216:219], v[4:7]
	v_mfma_f32_16x16x32_bf16 v[0:3], v[170:173], v[216:219], v[0:3]
	s_setprio 0
	s_barrier
	s_add_i32 s64, 0, 0x18000
	s_add_i32 s65, 0, 0x1c000
	v_add_u32_e32 v150, s64, v163
	v_add_u32_e32 v170, s65, v163
	ds_read_b128 v[138:141], v150
	ds_read_b128 v[142:145], v150 offset:1024
	ds_read_b128 v[146:149], v150 offset:2048
	ds_read_b128 v[150:153], v150 offset:3072
	ds_read_b128 v[154:157], v170
	ds_read_b128 v[158:161], v170 offset:1024
	ds_read_b128 v[166:169], v170 offset:2048
	ds_read_b128 v[170:173], v170 offset:3072
	s_mov_b32 m0, s48
	ds_read_b128 v[178:181], v165 offset:32768
	ds_read_b128 v[182:185], v165 offset:33792
	ds_read_b128 v[186:189], v165 offset:34816
	ds_read_b128 v[190:193], v165 offset:35840
	ds_read_b128 v[198:201], v165 offset:36864
	ds_read_b128 v[208:211], v165 offset:37888
	ds_read_b128 v[212:215], v165 offset:38912
	ds_read_b128 v[216:219], v165 offset:39936
	global_load_lds_dwordx4 v132, s[28:29]
	s_mov_b32 m0, s49
	s_nop 0
	global_load_lds_dwordx4 v130, s[28:29]
	s_waitcnt vmcnt(8)
	s_waitcnt lgkmcnt(0)
	s_barrier
	s_setprio 1
	s_waitcnt lgkmcnt(0)
	v_mfma_f32_16x16x32_bf16 v[124:127], v[138:141], v[178:181], v[124:127]
	v_mfma_f32_16x16x32_bf16 v[120:123], v[146:149], v[178:181], v[120:123]
	v_mfma_f32_16x16x32_bf16 v[108:111], v[138:141], v[186:189], v[108:111]
	v_mfma_f32_16x16x32_bf16 v[104:107], v[146:149], v[186:189], v[104:107]
	v_mfma_f32_16x16x32_bf16 v[96:99], v[138:141], v[198:201], v[96:99]
	v_mfma_f32_16x16x32_bf16 v[92:95], v[146:149], v[198:201], v[92:95]
	v_mfma_f32_16x16x32_bf16 v[84:87], v[138:141], v[212:215], v[84:87]
	v_mfma_f32_16x16x32_bf16 v[76:79], v[146:149], v[212:215], v[76:79]
	v_mfma_f32_16x16x32_bf16 v[124:127], v[142:145], v[182:185], v[124:127]
	v_mfma_f32_16x16x32_bf16 v[120:123], v[150:153], v[182:185], v[120:123]
	v_mfma_f32_16x16x32_bf16 v[108:111], v[142:145], v[190:193], v[108:111]
	v_mfma_f32_16x16x32_bf16 v[104:107], v[150:153], v[190:193], v[104:107]
	v_mfma_f32_16x16x32_bf16 v[96:99], v[142:145], v[208:211], v[96:99]
	v_mfma_f32_16x16x32_bf16 v[92:95], v[150:153], v[208:211], v[92:95]
	v_mfma_f32_16x16x32_bf16 v[84:87], v[142:145], v[216:219], v[84:87]
	v_mfma_f32_16x16x32_bf16 v[76:79], v[150:153], v[216:219], v[76:79]
	s_setprio 0
	s_setprio 1
	v_mfma_f32_16x16x32_bf16 v[116:119], v[154:157], v[178:181], v[116:119]
	v_mfma_f32_16x16x32_bf16 v[112:115], v[166:169], v[178:181], v[112:115]
	v_mfma_f32_16x16x32_bf16 v[100:103], v[154:157], v[186:189], v[100:103]
	v_mfma_f32_16x16x32_bf16 v[88:91], v[166:169], v[186:189], v[88:91]
	v_mfma_f32_16x16x32_bf16 v[80:83], v[154:157], v[198:201], v[80:83]
	v_mfma_f32_16x16x32_bf16 v[72:75], v[166:169], v[198:201], v[72:75]
	v_mfma_f32_16x16x32_bf16 v[68:71], v[154:157], v[212:215], v[68:71]
	v_mfma_f32_16x16x32_bf16 v[64:67], v[166:169], v[212:215], v[64:67]
	v_mfma_f32_16x16x32_bf16 v[116:119], v[158:161], v[182:185], v[116:119]
	v_mfma_f32_16x16x32_bf16 v[112:115], v[170:173], v[182:185], v[112:115]
	v_mfma_f32_16x16x32_bf16 v[100:103], v[158:161], v[190:193], v[100:103]
	v_mfma_f32_16x16x32_bf16 v[88:91], v[170:173], v[190:193], v[88:91]
	v_mfma_f32_16x16x32_bf16 v[80:83], v[158:161], v[208:211], v[80:83]
	v_mfma_f32_16x16x32_bf16 v[72:75], v[170:173], v[208:211], v[72:75]
	v_mfma_f32_16x16x32_bf16 v[68:71], v[158:161], v[216:219], v[68:71]
	v_mfma_f32_16x16x32_bf16 v[64:67], v[170:173], v[216:219], v[64:67]
	s_setprio 0
	s_barrier
; #define PG8_STAGE(bufoff, gbase, voff) do { _Pragma("unroll") for (int _i = 0; _i < 2; ++_i) \
;         __builtin_amdgcn_global_load_lds((const unsigned*)((const char*)(gbase) + (voff)[_i]), (LAS unsigned*)(lds + (bufoff) + ldsw + _i * 8192), 16, 0, 0); } while (0)
; #define PG8_LDA(dst, b, h) do { _Pragma("unroll") for (int m = 0; m < 4; ++m) _Pragma("unroll") for (int k = 0; k < 2; ++k) dst[m][k] = *(const LAS bf16x8*)(lds + PG8_SA(b, h) + aoff + m * 2048 + k * 1024); } while (0)
; #define PG8_WAIT_V(n) asm volatile("s_waitcnt vmcnt(" #n ")" ::: "memory")
; #define PG8_WAIT_L(n) asm volatile("s_waitcnt lgkmcnt(" #n ")" ::: "memory")
; #define PG8_BAR __builtin_amdgcn_s_barrier()
; #define PG8_SCHED __builtin_amdgcn_sched_barrier(0)
; template <bool F16, class Sched, class Epi>
; __device__ __forceinline__ void gemm_phase(LAS unsigned char* lds, const Gemm g, const Sched& S, const Epi& E, int wave_s) {
;     ...
;         for (int t = 0; t < nt; t += 2) {
;     ...
;             PG8_LDA(At, 1, 1); PG8_STAGE(PG8_SB(1, 0), b3, voffB); PG8_STAGE(PG8_SB(1, 1), b3 + hstepB, voffB); PG8_STAGE(PG8_SA(1, 0), a3, voffA);
;             PG8_WAIT_V(8); PG8_WAIT_L(0); PG8_BAR; PG8_MMA(1, 0, At, B0); PG8_MMA(1, 1, At, B1); PG8_BAR; PG8_SCHED;
	s_add_i32 s28, s64, s45
	v_lshl_add_u64 v[174:175], v[174:175], 0, s[54:55]
	s_mov_b32 m0, s28
	ds_read_b128 v[178:181], v165 offset:49152
	ds_read_b128 v[182:185], v165 offset:50176
	ds_read_b128 v[186:189], v165 offset:51200
	ds_read_b128 v[190:193], v165 offset:52224
	ds_read_b128 v[198:201], v165 offset:53248
	ds_read_b128 v[208:211], v165 offset:54272
	ds_read_b128 v[212:215], v165 offset:55296
	ds_read_b128 v[216:219], v165 offset:56320
	global_load_lds_dwordx4 v[174:175], off
	s_add_i32 m0, s28, 0x2000
	s_add_u32 s28, s34, 0x160080
	v_lshl_add_u64 v[174:175], v[194:195], 0, s[54:55]
	s_addc_u32 s29, s35, 0
	s_add_i32 s34, s65, s45
	global_load_lds_dwordx4 v[174:175], off
	v_lshl_add_u64 v[174:175], s[28:29], 0, v[176:177]
	s_mov_b32 m0, s34
	s_nop 0
	global_load_lds_dwordx4 v[174:175], off
	v_lshl_add_u64 v[174:175], s[28:29], 0, v[128:129]
	s_add_i32 m0, s34, 0x2000
	s_nop 0
	global_load_lds_dwordx4 v[174:175], off
	v_lshl_add_u64 v[174:175], v[202:203], 0, s[54:55]
	s_mov_b32 m0, s52
	s_nop 0
	global_load_lds_dwordx4 v[174:175], off
	v_lshl_add_u64 v[174:175], v[220:221], 0, s[54:55]
	s_mov_b32 m0, s53
	s_nop 0
	global_load_lds_dwordx4 v[174:175], off
	s_waitcnt vmcnt(8)
	s_waitcnt lgkmcnt(0)
	s_barrier
	s_setprio 1
	s_waitcnt lgkmcnt(0)
	v_mfma_f32_16x16x32_bf16 v[60:63], v[138:141], v[178:181], v[60:63]
	v_mfma_f32_16x16x32_bf16 v[56:59], v[146:149], v[178:181], v[56:59]
	v_mfma_f32_16x16x32_bf16 v[52:55], v[138:141], v[186:189], v[52:55]
	v_mfma_f32_16x16x32_bf16 v[44:47], v[146:149], v[186:189], v[44:47]
	v_mfma_f32_16x16x32_bf16 v[36:39], v[138:141], v[198:201], v[36:39]
	v_mfma_f32_16x16x32_bf16 v[28:31], v[146:149], v[198:201], v[28:31]
	v_mfma_f32_16x16x32_bf16 v[20:23], v[138:141], v[212:215], v[20:23]
	v_mfma_f32_16x16x32_bf16 v[12:15], v[146:149], v[212:215], v[12:15]
	v_mfma_f32_16x16x32_bf16 v[60:63], v[142:145], v[182:185], v[60:63]
	v_mfma_f32_16x16x32_bf16 v[56:59], v[150:153], v[182:185], v[56:59]
	v_mfma_f32_16x16x32_bf16 v[52:55], v[142:145], v[190:193], v[52:55]
	v_mfma_f32_16x16x32_bf16 v[44:47], v[150:153], v[190:193], v[44:47]
	v_mfma_f32_16x16x32_bf16 v[36:39], v[142:145], v[208:211], v[36:39]
	v_mfma_f32_16x16x32_bf16 v[28:31], v[150:153], v[208:211], v[28:31]
	v_mfma_f32_16x16x32_bf16 v[20:23], v[142:145], v[216:219], v[20:23]
	v_mfma_f32_16x16x32_bf16 v[12:15], v[150:153], v[216:219], v[12:15]
	s_setprio 0
	s_setprio 1
	v_mfma_f32_16x16x32_bf16 v[48:51], v[154:157], v[178:181], v[48:51]
	v_mfma_f32_16x16x32_bf16 v[40:43], v[166:169], v[178:181], v[40:43]
	v_mfma_f32_16x16x32_bf16 v[32:35], v[154:157], v[186:189], v[32:35]
	v_mfma_f32_16x16x32_bf16 v[24:27], v[166:169], v[186:189], v[24:27]
	v_mfma_f32_16x16x32_bf16 v[16:19], v[154:157], v[198:201], v[16:19]
	v_mfma_f32_16x16x32_bf16 v[8:11], v[166:169], v[198:201], v[8:11]
	v_mfma_f32_16x16x32_bf16 v[4:7], v[154:157], v[212:215], v[4:7]
	v_mfma_f32_16x16x32_bf16 v[0:3], v[166:169], v[212:215], v[0:3]
	v_mfma_f32_16x16x32_bf16 v[48:51], v[158:161], v[182:185], v[48:51]
	v_mfma_f32_16x16x32_bf16 v[40:43], v[170:173], v[182:185], v[40:43]
	v_mfma_f32_16x16x32_bf16 v[32:35], v[158:161], v[190:193], v[32:35]
	v_mfma_f32_16x16x32_bf16 v[24:27], v[170:173], v[190:193], v[24:27]
	v_mfma_f32_16x16x32_bf16 v[16:19], v[158:161], v[208:211], v[16:19]
	v_mfma_f32_16x16x32_bf16 v[8:11], v[170:173], v[208:211], v[8:11]
	v_mfma_f32_16x16x32_bf16 v[4:7], v[158:161], v[216:219], v[4:7]
	v_mfma_f32_16x16x32_bf16 v[0:3], v[170:173], v[216:219], v[0:3]
	s_add_i32 s63, s63, 2
	s_add_u32 s0, s0, 0x100
	s_addc_u32 s1, s1, 0
	s_cmpk_gt_u32 s63, 0x55
	s_mov_b64 s[28:29], s[30:31]
	s_setprio 0
	s_barrier
	s_cbranch_scc0 .LBB0_795
	s_and_b64 vcc, exec, s[12:13]
	s_cbranch_vccz .LBB0_798
	s_barrier

; #define PG8_STAGE(bufoff, gbase, voff) do { _Pragma("unroll") for (int _i = 0; _i < 2; ++_i) \
;         __builtin_amdgcn_global_load_lds((const unsigned*)((const char*)(gbase) + (voff)[_i]), (LAS unsigned*)(lds + (bufoff) + ldsw + _i * 8192), 16, 0, 0); } while (0)
; #define PG8_LDA(dst, b, h) do { _Pragma("unroll") for (int m = 0; m < 4; ++m) _Pragma("unroll") for (int k = 0; k < 2; ++k) dst[m][k] = *(const LAS bf16x8*)(lds + PG8_SA(b, h) + aoff + m * 2048 + k * 1024); } while (0)
; #define PG8_LDB(dst, b, h) do { _Pragma("unroll") for (int n = 0; n < 2; ++n) _Pragma("unroll") for (int k = 0; k < 2; ++k) dst[n][k] = *(const LAS bf16x8*)(lds + PG8_SB(b, h) + boff + n * 2048 + k * 1024); } while (0)
; #define PG8_WAIT_V(n) asm volatile("s_waitcnt vmcnt(" #n ")" ::: "memory")
; #define PG8_WAIT_L(n) asm volatile("s_waitcnt lgkmcnt(" #n ")" ::: "memory")
; #define PG8_BAR __builtin_amdgcn_s_barrier()
; #define PG8_SCHED __builtin_amdgcn_sched_barrier(0)
; template <bool F16, class Sched, class Epi>
; __device__ __forceinline__ void gemm_phase(LAS unsigned char* lds, const Gemm g, const Sched& S, const Epi& E, int wave_s) {
;     ...
;             const char* a2 = last ? nA : cA + (size_t)(t + 2) * kstep; const char* b2 = last ? nB : cB + (size_t)(t + 2) * kstep;
;             const char* a3 = a2 + kstep; const char* b3 = b2 + kstep;
;             PG8_LDB(B0, 0, 0); PG8_LDB(B1, 0, 1); PG8_SCHED; PG8_LDA(At, 0, 0); PG8_STAGE(PG8_SA(1, 1), a1 + hstepA, voffA);
;             PG8_WAIT_V(8); PG8_WAIT_L(0); PG8_BAR; PG8_MMA(0, 0, At, B0); PG8_MMA(0, 1, At, B1); PG8_BAR; PG8_SCHED;
;             PG8_LDA(At, 0, 1); PG8_STAGE(PG8_SB(0, 0), b2, voffB); PG8_STAGE(PG8_SB(0, 1), b2 + hstepB, voffB); PG8_STAGE(PG8_SA(0, 0), a2, voffA);
;             PG8_WAIT_V(8); PG8_WAIT_L(0); PG8_BAR; PG8_MMA(1, 0, At, B0); PG8_MMA(1, 1, At, B1); PG8_BAR; PG8_SCHED;
.LBB0_869:
	s_add_i32 s64, 0, 0x10000
	s_add_i32 s68, 0, 0x14000
	v_add_u32_e32 v44, s64, v208
	v_add_u32_e32 v156, s68, v208
	ds_read_b128 v[32:35], v44
	ds_read_b128 v[36:39], v44 offset:1024
	ds_read_b128 v[40:43], v44 offset:2048
	ds_read_b128 v[44:47], v44 offset:3072
	ds_read_b128 v[144:147], v156
	ds_read_b128 v[148:151], v156 offset:1024
	ds_read_b128 v[152:155], v156 offset:2048
	ds_read_b128 v[156:159], v156 offset:3072
	s_add_i32 m0, s44, 0xc000
	ds_read_b128 v[160:163], v210
	ds_read_b128 v[164:167], v210 offset:1024
	ds_read_b128 v[168:171], v210 offset:2048
	ds_read_b128 v[172:175], v210 offset:3072
	ds_read_b128 v[188:191], v210 offset:4096
	ds_read_b128 v[192:195], v210 offset:5120
	ds_read_b128 v[198:201], v210 offset:6144
	ds_read_b128 v[212:215], v210 offset:7168
	global_load_lds_dwordx4 v184, s[4:5]
	s_add_i32 m0, s44, 0xe000
	s_nop 0
	global_load_lds_dwordx4 v186, s[4:5]
	s_waitcnt vmcnt(8)
	s_waitcnt lgkmcnt(0)
	s_barrier
	s_setprio 1
	s_waitcnt lgkmcnt(0)
	v_mfma_f32_16x16x32_bf16 v[140:143], v[32:35], v[160:163], v[140:143]
	v_mfma_f32_16x16x32_bf16 v[136:139], v[40:43], v[160:163], v[136:139]
	v_mfma_f32_16x16x32_bf16 v[124:127], v[32:35], v[168:171], v[124:127]
	v_mfma_f32_16x16x32_bf16 v[120:123], v[40:43], v[168:171], v[120:123]
	v_mfma_f32_16x16x32_bf16 v[108:111], v[32:35], v[188:191], v[108:111]
	v_mfma_f32_16x16x32_bf16 v[104:107], v[40:43], v[188:191], v[104:107]
	v_mfma_f32_16x16x32_bf16 v[92:95], v[32:35], v[198:201], v[92:95]
	v_mfma_f32_16x16x32_bf16 v[88:91], v[40:43], v[198:201], v[88:91]
	v_mfma_f32_16x16x32_bf16 v[140:143], v[36:39], v[164:167], v[140:143]
	v_mfma_f32_16x16x32_bf16 v[136:139], v[44:47], v[164:167], v[136:139]
	v_mfma_f32_16x16x32_bf16 v[124:127], v[36:39], v[172:175], v[124:127]
	v_mfma_f32_16x16x32_bf16 v[120:123], v[44:47], v[172:175], v[120:123]
	v_mfma_f32_16x16x32_bf16 v[108:111], v[36:39], v[192:195], v[108:111]
	v_mfma_f32_16x16x32_bf16 v[104:107], v[44:47], v[192:195], v[104:107]
	v_mfma_f32_16x16x32_bf16 v[92:95], v[36:39], v[212:215], v[92:95]
	v_mfma_f32_16x16x32_bf16 v[88:91], v[44:47], v[212:215], v[88:91]
	s_setprio 0
	s_setprio 1
	v_mfma_f32_16x16x32_bf16 v[132:135], v[144:147], v[160:163], v[132:135]
	v_mfma_f32_16x16x32_bf16 v[128:131], v[152:155], v[160:163], v[128:131]
	v_mfma_f32_16x16x32_bf16 v[116:119], v[144:147], v[168:171], v[116:119]
	v_mfma_f32_16x16x32_bf16 v[112:115], v[152:155], v[168:171], v[112:115]
	v_mfma_f32_16x16x32_bf16 v[100:103], v[144:147], v[188:191], v[100:103]
	v_mfma_f32_16x16x32_bf16 v[96:99], v[152:155], v[188:191], v[96:99]
	v_mfma_f32_16x16x32_bf16 v[84:87], v[144:147], v[198:201], v[84:87]
	v_mfma_f32_16x16x32_bf16 v[80:83], v[152:155], v[198:201], v[80:83]
	v_mfma_f32_16x16x32_bf16 v[132:135], v[148:151], v[164:167], v[132:135]
	v_mfma_f32_16x16x32_bf16 v[128:131], v[156:159], v[164:167], v[128:131]
	v_mfma_f32_16x16x32_bf16 v[116:119], v[148:151], v[172:175], v[116:119]
	v_mfma_f32_16x16x32_bf16 v[112:115], v[156:159], v[172:175], v[112:115]
	v_mfma_f32_16x16x32_bf16 v[100:103], v[148:151], v[192:195], v[100:103]
	v_mfma_f32_16x16x32_bf16 v[96:99], v[156:159], v[192:195], v[96:99]
	v_mfma_f32_16x16x32_bf16 v[84:87], v[148:151], v[212:215], v[84:87]
	v_mfma_f32_16x16x32_bf16 v[80:83], v[156:159], v[212:215], v[80:83]
	s_setprio 0
	s_barrier
	s_add_u32 s30, s4, 0xfff80080
	s_addc_u32 s31, s5, -1
	s_cmp_eq_u32 s63, 28
	s_cselect_b32 s35, s53, s31
	s_cselect_b32 s34, s58, s30
	s_cselect_b32 s31, s59, s62
	s_cselect_b32 s30, s60, s61
	s_add_i32 s64, s64, s41
	v_lshl_add_u64 v[202:203], s[30:31], 0, v[176:177]
	s_mov_b32 m0, s64
	ds_read_b128 v[160:163], v210 offset:16384
	ds_read_b128 v[164:167], v210 offset:17408
	ds_read_b128 v[168:171], v210 offset:18432
	ds_read_b128 v[172:175], v210 offset:19456
	ds_read_b128 v[188:191], v210 offset:20480
	ds_read_b128 v[192:195], v210 offset:21504
	ds_read_b128 v[198:201], v210 offset:22528
	ds_read_b128 v[212:215], v210 offset:23552
	global_load_lds_dwordx4 v[202:203], off
	s_add_i32 m0, s64, 0x2000
	s_add_u32 s64, s30, 0x80000
	v_lshl_add_u64 v[216:217], s[30:31], 0, v[178:179]
	s_addc_u32 s65, s31, 0
	s_add_i32 s68, s68, s41
	global_load_lds_dwordx4 v[216:217], off
	v_lshl_add_u64 v[218:219], s[64:65], 0, v[176:177]
	s_mov_b32 m0, s68
	v_lshl_add_u64 v[220:221], s[34:35], 0, v[180:181]
	global_load_lds_dwordx4 v[218:219], off
	v_lshl_add_u64 v[218:219], s[64:65], 0, v[178:179]
	s_add_i32 m0, s68, 0x2000
	s_nop 0
	global_load_lds_dwordx4 v[218:219], off
	v_lshl_add_u64 v[218:219], s[34:35], 0, v[182:183]
	s_mov_b32 m0, s44
	s_nop 0
	global_load_lds_dwordx4 v[218:219], off
	s_mov_b32 m0, s45
	s_nop 0
	global_load_lds_dwordx4 v[220:221], off
	s_add_u32 s34, s34, 0x80000
	s_addc_u32 s35, s35, 0
	s_waitcnt vmcnt(8)
	s_waitcnt lgkmcnt(0)
	s_barrier
; #define PG8_STAGE(bufoff, gbase, voff) do { _Pragma("unroll") for (int _i = 0; _i < 2; ++_i) \
;         __builtin_amdgcn_global_load_lds((const unsigned*)((const char*)(gbase) + (voff)[_i]), (LAS unsigned*)(lds + (bufoff) + ldsw + _i * 8192), 16, 0, 0); } while (0)
; #define PG8_LDA(dst, b, h) do { _Pragma("unroll") for (int m = 0; m < 4; ++m) _Pragma("unroll") for (int k = 0; k < 2; ++k) dst[m][k] = *(const LAS bf16x8*)(lds + PG8_SA(b, h) + aoff + m * 2048 + k * 1024); } while (0)
; #define PG8_LDB(dst, b, h) do { _Pragma("unroll") for (int n = 0; n < 2; ++n) _Pragma("unroll") for (int k = 0; k < 2; ++k) dst[n][k] = *(const LAS bf16x8*)(lds + PG8_SB(b, h) + boff + n * 2048 + k * 1024); } while (0)
; #define PG8_WAIT_V(n) asm volatile("s_waitcnt vmcnt(" #n ")" ::: "memory")
; #define PG8_WAIT_L(n) asm volatile("s_waitcnt lgkmcnt(" #n ")" ::: "memory")
; #define PG8_BAR __builtin_amdgcn_s_barrier()
; #define PG8_SCHED __builtin_amdgcn_sched_barrier(0)
; template <bool F16, class Sched, class Epi>
; __device__ __forceinline__ void gemm_phase(LAS unsigned char* lds, const Gemm g, const Sched& S, const Epi& E, int wave_s) {
;     ...
;             PG8_WAIT_V(8); PG8_WAIT_L(0); PG8_BAR; PG8_MMA(1, 0, At, B0); PG8_MMA(1, 1, At, B1); PG8_BAR; PG8_SCHED;
;             PG8_LDB(B0, 1, 0); PG8_LDB(B1, 1, 1); PG8_SCHED; PG8_LDA(At, 1, 0); PG8_STAGE(PG8_SA(0, 1), a2 + hstepA, voffA);
;             PG8_WAIT_V(8); PG8_WAIT_L(0); PG8_BAR; PG8_MMA(0, 0, At, B0); PG8_MMA(0, 1, At, B1); PG8_BAR; PG8_SCHED;
	s_setprio 1
	s_waitcnt lgkmcnt(0)
	v_mfma_f32_16x16x32_bf16 v[76:79], v[32:35], v[160:163], v[76:79]
	v_mfma_f32_16x16x32_bf16 v[72:75], v[40:43], v[160:163], v[72:75]
	v_mfma_f32_16x16x32_bf16 v[60:63], v[32:35], v[168:171], v[60:63]
	v_mfma_f32_16x16x32_bf16 v[56:59], v[40:43], v[168:171], v[56:59]
	v_mfma_f32_16x16x32_bf16 v[28:31], v[32:35], v[188:191], v[28:31]
	v_mfma_f32_16x16x32_bf16 v[24:27], v[40:43], v[188:191], v[24:27]
	v_mfma_f32_16x16x32_bf16 v[12:15], v[32:35], v[198:201], v[12:15]
	v_mfma_f32_16x16x32_bf16 v[8:11], v[40:43], v[198:201], v[8:11]
	v_mfma_f32_16x16x32_bf16 v[76:79], v[36:39], v[164:167], v[76:79]
	v_mfma_f32_16x16x32_bf16 v[72:75], v[44:47], v[164:167], v[72:75]
	v_mfma_f32_16x16x32_bf16 v[60:63], v[36:39], v[172:175], v[60:63]
	v_mfma_f32_16x16x32_bf16 v[56:59], v[44:47], v[172:175], v[56:59]
	v_mfma_f32_16x16x32_bf16 v[28:31], v[36:39], v[192:195], v[28:31]
	v_mfma_f32_16x16x32_bf16 v[24:27], v[44:47], v[192:195], v[24:27]
	v_mfma_f32_16x16x32_bf16 v[12:15], v[36:39], v[212:215], v[12:15]
	v_mfma_f32_16x16x32_bf16 v[8:11], v[44:47], v[212:215], v[8:11]
	s_setprio 0
	s_setprio 1
	v_mfma_f32_16x16x32_bf16 v[20:23], v[144:147], v[188:191], v[20:23]
	v_mfma_f32_16x16x32_bf16 v[16:19], v[152:155], v[188:191], v[16:19]
	v_mfma_f32_16x16x32_bf16 v[4:7], v[144:147], v[198:201], v[4:7]
	v_mfma_f32_16x16x32_bf16 v[0:3], v[152:155], v[198:201], v[0:3]
	v_mfma_f32_16x16x32_bf16 v[32:35], v[144:147], v[160:163], v[68:71]
	v_mfma_f32_16x16x32_bf16 v[36:39], v[152:155], v[160:163], v[64:67]
	v_mfma_f32_16x16x32_bf16 v[40:43], v[144:147], v[168:171], v[52:55]
	v_mfma_f32_16x16x32_bf16 v[44:47], v[152:155], v[168:171], v[48:51]
	v_mfma_f32_16x16x32_bf16 v[20:23], v[148:151], v[192:195], v[20:23]
	v_mfma_f32_16x16x32_bf16 v[16:19], v[156:159], v[192:195], v[16:19]
	v_mfma_f32_16x16x32_bf16 v[4:7], v[148:151], v[212:215], v[4:7]
	v_mfma_f32_16x16x32_bf16 v[0:3], v[156:159], v[212:215], v[0:3]
	v_mfma_f32_16x16x32_bf16 v[32:35], v[148:151], v[164:167], v[32:35]
	v_mfma_f32_16x16x32_bf16 v[36:39], v[156:159], v[164:167], v[36:39]
	v_mfma_f32_16x16x32_bf16 v[40:43], v[148:151], v[172:175], v[40:43]
	v_mfma_f32_16x16x32_bf16 v[44:47], v[156:159], v[172:175], v[44:47]
	s_setprio 0
	s_barrier
	s_add_i32 s64, 0, 0x18000
	s_add_i32 s65, 0, 0x1c000
	v_add_u32_e32 v68, s64, v208
	v_add_u32_e32 v156, s65, v208
	ds_read_b128 v[48:51], v68
	ds_read_b128 v[52:55], v68 offset:1024
	ds_read_b128 v[64:67], v68 offset:2048
	ds_read_b128 v[68:71], v68 offset:3072
	ds_read_b128 v[144:147], v156
	ds_read_b128 v[148:151], v156 offset:1024
	ds_read_b128 v[152:155], v156 offset:2048
	ds_read_b128 v[156:159], v156 offset:3072
	s_mov_b32 m0, s46
	ds_read_b128 v[160:163], v210 offset:32768
	ds_read_b128 v[164:167], v210 offset:33792
	ds_read_b128 v[168:171], v210 offset:34816
	ds_read_b128 v[172:175], v210 offset:35840
	ds_read_b128 v[188:191], v210 offset:36864
	ds_read_b128 v[192:195], v210 offset:37888
	ds_read_b128 v[198:201], v210 offset:38912
	ds_read_b128 v[212:215], v210 offset:39936
	global_load_lds_dwordx4 v182, s[34:35]
	s_mov_b32 m0, s47
	s_nop 0
	global_load_lds_dwordx4 v180, s[34:35]
	s_waitcnt vmcnt(8)
	s_waitcnt lgkmcnt(0)
	s_barrier
	s_setprio 1
	s_waitcnt lgkmcnt(0)
	v_mfma_f32_16x16x32_bf16 v[140:143], v[48:51], v[160:163], v[140:143]
	v_mfma_f32_16x16x32_bf16 v[136:139], v[64:67], v[160:163], v[136:139]
	v_mfma_f32_16x16x32_bf16 v[124:127], v[48:51], v[168:171], v[124:127]
	v_mfma_f32_16x16x32_bf16 v[120:123], v[64:67], v[168:171], v[120:123]
	v_mfma_f32_16x16x32_bf16 v[108:111], v[48:51], v[188:191], v[108:111]
	v_mfma_f32_16x16x32_bf16 v[104:107], v[64:67], v[188:191], v[104:107]
	v_mfma_f32_16x16x32_bf16 v[92:95], v[48:51], v[198:201], v[92:95]
	v_mfma_f32_16x16x32_bf16 v[88:91], v[64:67], v[198:201], v[88:91]
	v_mfma_f32_16x16x32_bf16 v[140:143], v[52:55], v[164:167], v[140:143]
	v_mfma_f32_16x16x32_bf16 v[136:139], v[68:71], v[164:167], v[136:139]
	v_mfma_f32_16x16x32_bf16 v[124:127], v[52:55], v[172:175], v[124:127]
	v_mfma_f32_16x16x32_bf16 v[120:123], v[68:71], v[172:175], v[120:123]
	v_mfma_f32_16x16x32_bf16 v[108:111], v[52:55], v[192:195], v[108:111]
	v_mfma_f32_16x16x32_bf16 v[104:107], v[68:71], v[192:195], v[104:107]
	v_mfma_f32_16x16x32_bf16 v[92:95], v[52:55], v[212:215], v[92:95]
	v_mfma_f32_16x16x32_bf16 v[88:91], v[68:71], v[212:215], v[88:91]
	s_setprio 0
	s_setprio 1
	v_mfma_f32_16x16x32_bf16 v[132:135], v[144:147], v[160:163], v[132:135]
	v_mfma_f32_16x16x32_bf16 v[128:131], v[152:155], v[160:163], v[128:131]
	v_mfma_f32_16x16x32_bf16 v[116:119], v[144:147], v[168:171], v[116:119]
	v_mfma_f32_16x16x32_bf16 v[112:115], v[152:155], v[168:171], v[112:115]
	v_mfma_f32_16x16x32_bf16 v[100:103], v[144:147], v[188:191], v[100:103]
	v_mfma_f32_16x16x32_bf16 v[96:99], v[152:155], v[188:191], v[96:99]
	v_mfma_f32_16x16x32_bf16 v[84:87], v[144:147], v[198:201], v[84:87]
	v_mfma_f32_16x16x32_bf16 v[80:83], v[152:155], v[198:201], v[80:83]
	v_mfma_f32_16x16x32_bf16 v[132:135], v[148:151], v[164:167], v[132:135]
	v_mfma_f32_16x16x32_bf16 v[128:131], v[156:159], v[164:167], v[128:131]
	v_mfma_f32_16x16x32_bf16 v[116:119], v[148:151], v[172:175], v[116:119]
	v_mfma_f32_16x16x32_bf16 v[112:115], v[156:159], v[172:175], v[112:115]
	v_mfma_f32_16x16x32_bf16 v[100:103], v[148:151], v[192:195], v[100:103]
	v_mfma_f32_16x16x32_bf16 v[96:99], v[156:159], v[192:195], v[96:99]
	v_mfma_f32_16x16x32_bf16 v[84:87], v[148:151], v[212:215], v[84:87]
	v_mfma_f32_16x16x32_bf16 v[80:83], v[156:159], v[212:215], v[80:83]
	s_setprio 0
	s_barrier
; #define PG8_STAGE(bufoff, gbase, voff) do { _Pragma("unroll") for (int _i = 0; _i < 2; ++_i) \
;         __builtin_amdgcn_global_load_lds((const unsigned*)((const char*)(gbase) + (voff)[_i]), (LAS unsigned*)(lds + (bufoff) + ldsw + _i * 8192), 16, 0, 0); } while (0)
; #define PG8_LDA(dst, b, h) do { _Pragma("unroll") for (int m = 0; m < 4; ++m) _Pragma("unroll") for (int k = 0; k < 2; ++k) dst[m][k] = *(const LAS bf16x8*)(lds + PG8_SA(b, h) + aoff + m * 2048 + k * 1024); } while (0)
; #define PG8_WAIT_V(n) asm volatile("s_waitcnt vmcnt(" #n ")" ::: "memory")
; #define PG8_WAIT_L(n) asm volatile("s_waitcnt lgkmcnt(" #n ")" ::: "memory")
; #define PG8_BAR __builtin_amdgcn_s_barrier()
; #define PG8_SCHED __builtin_amdgcn_sched_barrier(0)
; template <bool F16, class Sched, class Epi>
; __device__ __forceinline__ void gemm_phase(LAS unsigned char* lds, const Gemm g, const Sched& S, const Epi& E, int wave_s) {
;     ...
;         for (int t = 0; t < nt; t += 2) {
;     ...
;             PG8_LDA(At, 1, 1); PG8_STAGE(PG8_SB(1, 0), b3, voffB); PG8_STAGE(PG8_SB(1, 1), b3 + hstepB, voffB); PG8_STAGE(PG8_SA(1, 0), a3, voffA);
;             PG8_WAIT_V(8); PG8_WAIT_L(0); PG8_BAR; PG8_MMA(1, 0, At, B0); PG8_MMA(1, 1, At, B1); PG8_BAR; PG8_SCHED;
	s_add_i32 s34, s64, s41
	v_lshl_add_u64 v[202:203], v[202:203], 0, s[54:55]
	s_mov_b32 m0, s34
	ds_read_b128 v[160:163], v210 offset:49152
	ds_read_b128 v[164:167], v210 offset:50176
	ds_read_b128 v[168:171], v210 offset:51200
	ds_read_b128 v[172:175], v210 offset:52224
	ds_read_b128 v[188:191], v210 offset:53248
	ds_read_b128 v[192:195], v210 offset:54272
	ds_read_b128 v[198:201], v210 offset:55296
	ds_read_b128 v[212:215], v210 offset:56320
	global_load_lds_dwordx4 v[202:203], off
	s_add_i32 m0, s34, 0x2000
	s_add_u32 s30, s30, 0x80080
	v_lshl_add_u64 v[202:203], v[216:217], 0, s[54:55]
	s_addc_u32 s31, s31, 0
	s_add_i32 s34, s65, s41
	global_load_lds_dwordx4 v[202:203], off
	v_lshl_add_u64 v[202:203], s[30:31], 0, v[176:177]
	s_mov_b32 m0, s34
	s_nop 0
	global_load_lds_dwordx4 v[202:203], off
	v_lshl_add_u64 v[202:203], s[30:31], 0, v[178:179]
	s_add_i32 m0, s34, 0x2000
	s_nop 0
	global_load_lds_dwordx4 v[202:203], off
	v_lshl_add_u64 v[202:203], v[218:219], 0, s[54:55]
	s_mov_b32 m0, s49
	s_nop 0
	global_load_lds_dwordx4 v[202:203], off
	v_lshl_add_u64 v[202:203], v[220:221], 0, s[54:55]
	s_mov_b32 m0, s52
	s_nop 0
	global_load_lds_dwordx4 v[202:203], off
	s_waitcnt vmcnt(8)
	s_waitcnt lgkmcnt(0)
	s_barrier
	s_setprio 1
	s_waitcnt lgkmcnt(0)
	v_mfma_f32_16x16x32_bf16 v[76:79], v[48:51], v[160:163], v[76:79]
	v_mfma_f32_16x16x32_bf16 v[72:75], v[64:67], v[160:163], v[72:75]
	v_mfma_f32_16x16x32_bf16 v[60:63], v[48:51], v[168:171], v[60:63]
	v_mfma_f32_16x16x32_bf16 v[56:59], v[64:67], v[168:171], v[56:59]
	v_mfma_f32_16x16x32_bf16 v[28:31], v[48:51], v[188:191], v[28:31]
	v_mfma_f32_16x16x32_bf16 v[24:27], v[64:67], v[188:191], v[24:27]
	v_mfma_f32_16x16x32_bf16 v[12:15], v[48:51], v[198:201], v[12:15]
	v_mfma_f32_16x16x32_bf16 v[8:11], v[64:67], v[198:201], v[8:11]
	v_mfma_f32_16x16x32_bf16 v[76:79], v[52:55], v[164:167], v[76:79]
	v_mfma_f32_16x16x32_bf16 v[72:75], v[68:71], v[164:167], v[72:75]
	v_mfma_f32_16x16x32_bf16 v[60:63], v[52:55], v[172:175], v[60:63]
	v_mfma_f32_16x16x32_bf16 v[56:59], v[68:71], v[172:175], v[56:59]
	v_mfma_f32_16x16x32_bf16 v[28:31], v[52:55], v[192:195], v[28:31]
	v_mfma_f32_16x16x32_bf16 v[24:27], v[68:71], v[192:195], v[24:27]
	v_mfma_f32_16x16x32_bf16 v[12:15], v[52:55], v[212:215], v[12:15]
	v_mfma_f32_16x16x32_bf16 v[8:11], v[68:71], v[212:215], v[8:11]
	s_setprio 0
	s_setprio 1
	v_mfma_f32_16x16x32_bf16 v[32:35], v[144:147], v[160:163], v[32:35]
	v_mfma_f32_16x16x32_bf16 v[68:71], v[148:151], v[164:167], v[32:35]
	v_mfma_f32_16x16x32_bf16 v[32:35], v[152:155], v[160:163], v[36:39]
	v_mfma_f32_16x16x32_bf16 v[64:67], v[156:159], v[164:167], v[32:35]
	v_mfma_f32_16x16x32_bf16 v[32:35], v[144:147], v[168:171], v[40:43]
	v_mfma_f32_16x16x32_bf16 v[52:55], v[148:151], v[172:175], v[32:35]
	v_mfma_f32_16x16x32_bf16 v[32:35], v[152:155], v[168:171], v[44:47]
	v_mfma_f32_16x16x32_bf16 v[20:23], v[144:147], v[188:191], v[20:23]
	v_mfma_f32_16x16x32_bf16 v[16:19], v[152:155], v[188:191], v[16:19]
	v_mfma_f32_16x16x32_bf16 v[4:7], v[144:147], v[198:201], v[4:7]
	v_mfma_f32_16x16x32_bf16 v[0:3], v[152:155], v[198:201], v[0:3]
	v_mfma_f32_16x16x32_bf16 v[48:51], v[156:159], v[172:175], v[32:35]
	v_mfma_f32_16x16x32_bf16 v[20:23], v[148:151], v[192:195], v[20:23]
	v_mfma_f32_16x16x32_bf16 v[16:19], v[156:159], v[192:195], v[16:19]
	v_mfma_f32_16x16x32_bf16 v[4:7], v[148:151], v[212:215], v[4:7]
	v_mfma_f32_16x16x32_bf16 v[0:3], v[156:159], v[212:215], v[0:3]
	s_add_i32 s63, s63, 2
	s_add_u32 s4, s4, 0x100
	s_addc_u32 s5, s5, 0
	s_add_u32 s61, s61, 0x100
	s_addc_u32 s62, s62, 0
	s_cmp_gt_u32 s63, 29
	s_setprio 0
	s_barrier
	s_cbranch_scc0 .LBB0_869
	s_and_b64 vcc, exec, s[26:27]
	s_cbranch_vccz .LBB0_872
	s_barrier

; #define PG8_STAGE(bufoff, gbase, voff) do { _Pragma("unroll") for (int _i = 0; _i < 2; ++_i) \
;         __builtin_amdgcn_global_load_lds((const unsigned*)((const char*)(gbase) + (voff)[_i]), (LAS unsigned*)(lds + (bufoff) + ldsw + _i * 8192), 16, 0, 0); } while (0)
; #define PG8_LDA(dst, b, h) do { _Pragma("unroll") for (int m = 0; m < 4; ++m) _Pragma("unroll") for (int k = 0; k < 2; ++k) dst[m][k] = *(const LAS bf16x8*)(lds + PG8_SA(b, h) + aoff + m * 2048 + k * 1024); } while (0)
; #define PG8_LDB(dst, b, h) do { _Pragma("unroll") for (int n = 0; n < 2; ++n) _Pragma("unroll") for (int k = 0; k < 2; ++k) dst[n][k] = *(const LAS bf16x8*)(lds + PG8_SB(b, h) + boff + n * 2048 + k * 1024); } while (0)
; #define PG8_WAIT_V(n) asm volatile("s_waitcnt vmcnt(" #n ")" ::: "memory")
; #define PG8_WAIT_L(n) asm volatile("s_waitcnt lgkmcnt(" #n ")" ::: "memory")
; #define PG8_BAR __builtin_amdgcn_s_barrier()
; #define PG8_SCHED __builtin_amdgcn_sched_barrier(0)
; template <bool F16, class Sched, class Epi>
; __device__ __forceinline__ void gemm_phase(LAS unsigned char* lds, const Gemm g, const Sched& S, const Epi& E, int wave_s) {
;     ...
;             const char* a2 = last ? nA : cA + (size_t)(t + 2) * kstep; const char* b2 = last ? nB : cB + (size_t)(t + 2) * kstep;
;             const char* a3 = a2 + kstep; const char* b3 = b2 + kstep;
;             PG8_LDB(B0, 0, 0); PG8_LDB(B1, 0, 1); PG8_SCHED; PG8_LDA(At, 0, 0); PG8_STAGE(PG8_SA(1, 1), a1 + hstepA, voffA);
;             PG8_WAIT_V(8); PG8_WAIT_L(0); PG8_BAR; PG8_MMA(0, 0, At, B0); PG8_MMA(0, 1, At, B1); PG8_BAR; PG8_SCHED;
;             PG8_LDA(At, 0, 1); PG8_STAGE(PG8_SB(0, 0), b2, voffB); PG8_STAGE(PG8_SB(0, 1), b2 + hstepB, voffB); PG8_STAGE(PG8_SA(0, 0), a2, voffA);
;             PG8_WAIT_V(8); PG8_WAIT_L(0); PG8_BAR; PG8_MMA(1, 0, At, B0); PG8_MMA(1, 1, At, B1); PG8_BAR; PG8_SCHED;
.LBB0_993:
	s_add_i32 s43, 0, 0x10000
	s_add_i32 s26, 0, 0x14000
	v_add_u32_e32 v68, s43, v208
	v_add_u32_e32 v156, s26, v208
	ds_read_b128 v[56:59], v68
	ds_read_b128 v[60:63], v68 offset:1024
	ds_read_b128 v[64:67], v68 offset:2048
	ds_read_b128 v[68:71], v68 offset:3072
	ds_read_b128 v[144:147], v156
	ds_read_b128 v[148:151], v156 offset:1024
	ds_read_b128 v[152:155], v156 offset:2048
	ds_read_b128 v[156:159], v156 offset:3072
	s_add_i32 m0, s18, 0xc000
	ds_read_b128 v[160:163], v210
	ds_read_b128 v[164:167], v210 offset:1024
	ds_read_b128 v[168:171], v210 offset:2048
	ds_read_b128 v[172:175], v210 offset:3072
	ds_read_b128 v[188:191], v210 offset:4096
	ds_read_b128 v[192:195], v210 offset:5120
	ds_read_b128 v[198:201], v210 offset:6144
	ds_read_b128 v[212:215], v210 offset:7168
	global_load_lds_dwordx4 v184, s[38:39]
	s_add_i32 m0, s18, 0xe000
	s_nop 0
	global_load_lds_dwordx4 v186, s[38:39]
	s_waitcnt vmcnt(8)
	s_waitcnt lgkmcnt(0)
	s_barrier
	s_setprio 1
	s_waitcnt lgkmcnt(0)
	v_mfma_f32_16x16x32_bf16 v[140:143], v[56:59], v[160:163], v[140:143]
	v_mfma_f32_16x16x32_bf16 v[136:139], v[64:67], v[160:163], v[136:139]
	v_mfma_f32_16x16x32_bf16 v[124:127], v[56:59], v[168:171], v[124:127]
	v_mfma_f32_16x16x32_bf16 v[120:123], v[64:67], v[168:171], v[120:123]
	v_mfma_f32_16x16x32_bf16 v[108:111], v[56:59], v[188:191], v[108:111]
	v_mfma_f32_16x16x32_bf16 v[104:107], v[64:67], v[188:191], v[104:107]
	v_mfma_f32_16x16x32_bf16 v[92:95], v[56:59], v[198:201], v[92:95]
	v_mfma_f32_16x16x32_bf16 v[88:91], v[64:67], v[198:201], v[88:91]
	v_mfma_f32_16x16x32_bf16 v[140:143], v[60:63], v[164:167], v[140:143]
	v_mfma_f32_16x16x32_bf16 v[136:139], v[68:71], v[164:167], v[136:139]
	v_mfma_f32_16x16x32_bf16 v[124:127], v[60:63], v[172:175], v[124:127]
	v_mfma_f32_16x16x32_bf16 v[120:123], v[68:71], v[172:175], v[120:123]
	v_mfma_f32_16x16x32_bf16 v[108:111], v[60:63], v[192:195], v[108:111]
	v_mfma_f32_16x16x32_bf16 v[104:107], v[68:71], v[192:195], v[104:107]
	v_mfma_f32_16x16x32_bf16 v[92:95], v[60:63], v[212:215], v[92:95]
	v_mfma_f32_16x16x32_bf16 v[88:91], v[68:71], v[212:215], v[88:91]
	s_setprio 0
	s_setprio 1
	v_mfma_f32_16x16x32_bf16 v[132:135], v[144:147], v[160:163], v[132:135]
	v_mfma_f32_16x16x32_bf16 v[128:131], v[152:155], v[160:163], v[128:131]
	v_mfma_f32_16x16x32_bf16 v[116:119], v[144:147], v[168:171], v[116:119]
	v_mfma_f32_16x16x32_bf16 v[112:115], v[152:155], v[168:171], v[112:115]
	v_mfma_f32_16x16x32_bf16 v[100:103], v[144:147], v[188:191], v[100:103]
	v_mfma_f32_16x16x32_bf16 v[96:99], v[152:155], v[188:191], v[96:99]
	v_mfma_f32_16x16x32_bf16 v[84:87], v[144:147], v[198:201], v[84:87]
	v_mfma_f32_16x16x32_bf16 v[80:83], v[152:155], v[198:201], v[80:83]
	v_mfma_f32_16x16x32_bf16 v[132:135], v[148:151], v[164:167], v[132:135]
	v_mfma_f32_16x16x32_bf16 v[128:131], v[156:159], v[164:167], v[128:131]
	v_mfma_f32_16x16x32_bf16 v[116:119], v[148:151], v[172:175], v[116:119]
	v_mfma_f32_16x16x32_bf16 v[112:115], v[156:159], v[172:175], v[112:115]
	v_mfma_f32_16x16x32_bf16 v[100:103], v[148:151], v[192:195], v[100:103]
	v_mfma_f32_16x16x32_bf16 v[96:99], v[156:159], v[192:195], v[96:99]
	v_mfma_f32_16x16x32_bf16 v[84:87], v[148:151], v[212:215], v[84:87]
	v_mfma_f32_16x16x32_bf16 v[80:83], v[156:159], v[212:215], v[80:83]
	s_setprio 0
	s_barrier
	s_add_u32 s24, s38, 0xfff80080
	s_addc_u32 s25, s39, -1
	s_cmp_eq_u32 s42, 28
	s_cselect_b32 s65, s4, s25
	s_cselect_b32 s64, s5, s24
	s_cselect_b32 vcc_hi, s6, s9
	s_cselect_b32 vcc_lo, s7, s8
	s_add_i32 s24, s43, s15
	v_lshl_add_u64 v[202:203], vcc, 0, v[176:177]
	s_mov_b32 m0, s24
	ds_read_b128 v[160:163], v210 offset:16384
	ds_read_b128 v[164:167], v210 offset:17408
	ds_read_b128 v[168:171], v210 offset:18432
	ds_read_b128 v[172:175], v210 offset:19456
	ds_read_b128 v[188:191], v210 offset:20480
	ds_read_b128 v[192:195], v210 offset:21504
	ds_read_b128 v[198:201], v210 offset:22528
	ds_read_b128 v[212:215], v210 offset:23552
	global_load_lds_dwordx4 v[202:203], off
	s_add_i32 m0, s24, 0x2000
	s_add_u32 s24, vcc_lo, 0x80000
	v_lshl_add_u64 v[216:217], vcc, 0, v[178:179]
	s_addc_u32 s25, vcc_hi, 0
	s_add_i32 s26, s26, s15
	global_load_lds_dwordx4 v[216:217], off
	v_lshl_add_u64 v[218:219], s[24:25], 0, v[176:177]
	s_mov_b32 m0, s26
	v_lshl_add_u64 v[220:221], s[64:65], 0, v[180:181]
	global_load_lds_dwordx4 v[218:219], off
	v_lshl_add_u64 v[218:219], s[24:25], 0, v[178:179]
	s_add_i32 m0, s26, 0x2000
	s_nop 0
	global_load_lds_dwordx4 v[218:219], off
	v_lshl_add_u64 v[218:219], s[64:65], 0, v[182:183]
	s_mov_b32 m0, s18
	s_nop 0
	global_load_lds_dwordx4 v[218:219], off
	s_mov_b32 m0, s19
	s_nop 0
	global_load_lds_dwordx4 v[220:221], off
	s_add_u32 s24, s64, 0x80000
	s_addc_u32 s25, s65, 0
	s_waitcnt vmcnt(8)
	s_waitcnt lgkmcnt(0)
	s_barrier
; #define PG8_STAGE(bufoff, gbase, voff) do { _Pragma("unroll") for (int _i = 0; _i < 2; ++_i) \
;         __builtin_amdgcn_global_load_lds((const unsigned*)((const char*)(gbase) + (voff)[_i]), (LAS unsigned*)(lds + (bufoff) + ldsw + _i * 8192), 16, 0, 0); } while (0)
; #define PG8_LDA(dst, b, h) do { _Pragma("unroll") for (int m = 0; m < 4; ++m) _Pragma("unroll") for (int k = 0; k < 2; ++k) dst[m][k] = *(const LAS bf16x8*)(lds + PG8_SA(b, h) + aoff + m * 2048 + k * 1024); } while (0)
; #define PG8_LDB(dst, b, h) do { _Pragma("unroll") for (int n = 0; n < 2; ++n) _Pragma("unroll") for (int k = 0; k < 2; ++k) dst[n][k] = *(const LAS bf16x8*)(lds + PG8_SB(b, h) + boff + n * 2048 + k * 1024); } while (0)
; #define PG8_WAIT_V(n) asm volatile("s_waitcnt vmcnt(" #n ")" ::: "memory")
; #define PG8_WAIT_L(n) asm volatile("s_waitcnt lgkmcnt(" #n ")" ::: "memory")
; #define PG8_BAR __builtin_amdgcn_s_barrier()
; #define PG8_SCHED __builtin_amdgcn_sched_barrier(0)
; template <bool F16, class Sched, class Epi>
; __device__ __forceinline__ void gemm_phase(LAS unsigned char* lds, const Gemm g, const Sched& S, const Epi& E, int wave_s) {
;     ...
;             PG8_WAIT_V(8); PG8_WAIT_L(0); PG8_BAR; PG8_MMA(1, 0, At, B0); PG8_MMA(1, 1, At, B1); PG8_BAR; PG8_SCHED;
;             PG8_LDB(B0, 1, 0); PG8_LDB(B1, 1, 1); PG8_SCHED; PG8_LDA(At, 1, 0); PG8_STAGE(PG8_SA(0, 1), a2 + hstepA, voffA);
;             PG8_WAIT_V(8); PG8_WAIT_L(0); PG8_BAR; PG8_MMA(0, 0, At, B0); PG8_MMA(0, 1, At, B1); PG8_BAR; PG8_SCHED;
	s_setprio 1
	s_waitcnt lgkmcnt(0)
	v_mfma_f32_16x16x32_bf16 v[76:79], v[56:59], v[160:163], v[76:79]
	v_mfma_f32_16x16x32_bf16 v[72:75], v[64:67], v[160:163], v[72:75]
	v_mfma_f32_16x16x32_bf16 v[44:47], v[56:59], v[168:171], v[44:47]
	v_mfma_f32_16x16x32_bf16 v[40:43], v[64:67], v[168:171], v[40:43]
	v_mfma_f32_16x16x32_bf16 v[28:31], v[56:59], v[188:191], v[28:31]
	v_mfma_f32_16x16x32_bf16 v[24:27], v[64:67], v[188:191], v[24:27]
	v_mfma_f32_16x16x32_bf16 v[12:15], v[56:59], v[198:201], v[12:15]
	v_mfma_f32_16x16x32_bf16 v[8:11], v[64:67], v[198:201], v[8:11]
	v_mfma_f32_16x16x32_bf16 v[76:79], v[60:63], v[164:167], v[76:79]
	v_mfma_f32_16x16x32_bf16 v[72:75], v[68:71], v[164:167], v[72:75]
	v_mfma_f32_16x16x32_bf16 v[44:47], v[60:63], v[172:175], v[44:47]
	v_mfma_f32_16x16x32_bf16 v[40:43], v[68:71], v[172:175], v[40:43]
	v_mfma_f32_16x16x32_bf16 v[28:31], v[60:63], v[192:195], v[28:31]
	v_mfma_f32_16x16x32_bf16 v[24:27], v[68:71], v[192:195], v[24:27]
	v_mfma_f32_16x16x32_bf16 v[12:15], v[60:63], v[212:215], v[12:15]
	v_mfma_f32_16x16x32_bf16 v[8:11], v[68:71], v[212:215], v[8:11]
	s_setprio 0
	s_setprio 1
	v_mfma_f32_16x16x32_bf16 v[52:55], v[144:147], v[160:163], v[52:55]
	v_mfma_f32_16x16x32_bf16 v[48:51], v[152:155], v[160:163], v[48:51]
	v_mfma_f32_16x16x32_bf16 v[36:39], v[144:147], v[168:171], v[36:39]
	v_mfma_f32_16x16x32_bf16 v[32:35], v[152:155], v[168:171], v[32:35]
	v_mfma_f32_16x16x32_bf16 v[20:23], v[144:147], v[188:191], v[20:23]
	v_mfma_f32_16x16x32_bf16 v[16:19], v[152:155], v[188:191], v[16:19]
	v_mfma_f32_16x16x32_bf16 v[4:7], v[144:147], v[198:201], v[4:7]
	v_mfma_f32_16x16x32_bf16 v[0:3], v[152:155], v[198:201], v[0:3]
	v_mfma_f32_16x16x32_bf16 v[52:55], v[148:151], v[164:167], v[52:55]
	v_mfma_f32_16x16x32_bf16 v[48:51], v[156:159], v[164:167], v[48:51]
	v_mfma_f32_16x16x32_bf16 v[36:39], v[148:151], v[172:175], v[36:39]
	v_mfma_f32_16x16x32_bf16 v[32:35], v[156:159], v[172:175], v[32:35]
	v_mfma_f32_16x16x32_bf16 v[20:23], v[148:151], v[192:195], v[20:23]
	v_mfma_f32_16x16x32_bf16 v[16:19], v[156:159], v[192:195], v[16:19]
	v_mfma_f32_16x16x32_bf16 v[4:7], v[148:151], v[212:215], v[4:7]
	v_mfma_f32_16x16x32_bf16 v[0:3], v[156:159], v[212:215], v[0:3]
	s_setprio 0
	s_barrier
	s_add_i32 s26, 0, 0x18000
	s_add_i32 s27, 0, 0x1c000
	v_add_u32_e32 v68, s26, v208
	v_add_u32_e32 v156, s27, v208
	ds_read_b128 v[56:59], v68
	ds_read_b128 v[60:63], v68 offset:1024
	ds_read_b128 v[64:67], v68 offset:2048
	ds_read_b128 v[68:71], v68 offset:3072
	ds_read_b128 v[144:147], v156
	ds_read_b128 v[148:151], v156 offset:1024
	ds_read_b128 v[152:155], v156 offset:2048
	ds_read_b128 v[156:159], v156 offset:3072
	s_mov_b32 m0, s20
	ds_read_b128 v[160:163], v210 offset:32768
	ds_read_b128 v[164:167], v210 offset:33792
	ds_read_b128 v[168:171], v210 offset:34816
	ds_read_b128 v[172:175], v210 offset:35840
	ds_read_b128 v[188:191], v210 offset:36864
	ds_read_b128 v[192:195], v210 offset:37888
	ds_read_b128 v[198:201], v210 offset:38912
	ds_read_b128 v[212:215], v210 offset:39936
	global_load_lds_dwordx4 v182, s[24:25]
	s_mov_b32 m0, s21
	s_nop 0
	global_load_lds_dwordx4 v180, s[24:25]
	s_waitcnt vmcnt(8)
	s_waitcnt lgkmcnt(0)
	s_barrier
	s_setprio 1
	s_waitcnt lgkmcnt(0)
	v_mfma_f32_16x16x32_bf16 v[140:143], v[56:59], v[160:163], v[140:143]
	v_mfma_f32_16x16x32_bf16 v[136:139], v[64:67], v[160:163], v[136:139]
	v_mfma_f32_16x16x32_bf16 v[124:127], v[56:59], v[168:171], v[124:127]
	v_mfma_f32_16x16x32_bf16 v[120:123], v[64:67], v[168:171], v[120:123]
	v_mfma_f32_16x16x32_bf16 v[108:111], v[56:59], v[188:191], v[108:111]
	v_mfma_f32_16x16x32_bf16 v[104:107], v[64:67], v[188:191], v[104:107]
	v_mfma_f32_16x16x32_bf16 v[92:95], v[56:59], v[198:201], v[92:95]
	v_mfma_f32_16x16x32_bf16 v[88:91], v[64:67], v[198:201], v[88:91]
	v_mfma_f32_16x16x32_bf16 v[140:143], v[60:63], v[164:167], v[140:143]
	v_mfma_f32_16x16x32_bf16 v[136:139], v[68:71], v[164:167], v[136:139]
	v_mfma_f32_16x16x32_bf16 v[124:127], v[60:63], v[172:175], v[124:127]
	v_mfma_f32_16x16x32_bf16 v[120:123], v[68:71], v[172:175], v[120:123]
	v_mfma_f32_16x16x32_bf16 v[108:111], v[60:63], v[192:195], v[108:111]
	v_mfma_f32_16x16x32_bf16 v[104:107], v[68:71], v[192:195], v[104:107]
	v_mfma_f32_16x16x32_bf16 v[92:95], v[60:63], v[212:215], v[92:95]
	v_mfma_f32_16x16x32_bf16 v[88:91], v[68:71], v[212:215], v[88:91]
	s_setprio 0
	s_setprio 1
	v_mfma_f32_16x16x32_bf16 v[132:135], v[144:147], v[160:163], v[132:135]
	v_mfma_f32_16x16x32_bf16 v[128:131], v[152:155], v[160:163], v[128:131]
	v_mfma_f32_16x16x32_bf16 v[116:119], v[144:147], v[168:171], v[116:119]
	v_mfma_f32_16x16x32_bf16 v[112:115], v[152:155], v[168:171], v[112:115]
	v_mfma_f32_16x16x32_bf16 v[100:103], v[144:147], v[188:191], v[100:103]
	v_mfma_f32_16x16x32_bf16 v[96:99], v[152:155], v[188:191], v[96:99]
	v_mfma_f32_16x16x32_bf16 v[84:87], v[144:147], v[198:201], v[84:87]
	v_mfma_f32_16x16x32_bf16 v[80:83], v[152:155], v[198:201], v[80:83]
	v_mfma_f32_16x16x32_bf16 v[132:135], v[148:151], v[164:167], v[132:135]
	v_mfma_f32_16x16x32_bf16 v[128:131], v[156:159], v[164:167], v[128:131]
	v_mfma_f32_16x16x32_bf16 v[116:119], v[148:151], v[172:175], v[116:119]
	v_mfma_f32_16x16x32_bf16 v[112:115], v[156:159], v[172:175], v[112:115]
	v_mfma_f32_16x16x32_bf16 v[100:103], v[148:151], v[192:195], v[100:103]
	v_mfma_f32_16x16x32_bf16 v[96:99], v[156:159], v[192:195], v[96:99]
	v_mfma_f32_16x16x32_bf16 v[84:87], v[148:151], v[212:215], v[84:87]
	v_mfma_f32_16x16x32_bf16 v[80:83], v[156:159], v[212:215], v[80:83]
	s_setprio 0
	s_barrier
; #define PG8_STAGE(bufoff, gbase, voff) do { _Pragma("unroll") for (int _i = 0; _i < 2; ++_i) \
;         __builtin_amdgcn_global_load_lds((const unsigned*)((const char*)(gbase) + (voff)[_i]), (LAS unsigned*)(lds + (bufoff) + ldsw + _i * 8192), 16, 0, 0); } while (0)
; #define PG8_LDA(dst, b, h) do { _Pragma("unroll") for (int m = 0; m < 4; ++m) _Pragma("unroll") for (int k = 0; k < 2; ++k) dst[m][k] = *(const LAS bf16x8*)(lds + PG8_SA(b, h) + aoff + m * 2048 + k * 1024); } while (0)
; #define PG8_WAIT_V(n) asm volatile("s_waitcnt vmcnt(" #n ")" ::: "memory")
; #define PG8_WAIT_L(n) asm volatile("s_waitcnt lgkmcnt(" #n ")" ::: "memory")
; #define PG8_BAR __builtin_amdgcn_s_barrier()
; #define PG8_SCHED __builtin_amdgcn_sched_barrier(0)
; template <bool F16, class Sched, class Epi>
; __device__ __forceinline__ void gemm_phase(LAS unsigned char* lds, const Gemm g, const Sched& S, const Epi& E, int wave_s) {
;     ...
;             PG8_LDA(At, 1, 1); PG8_STAGE(PG8_SB(1, 0), b3, voffB); PG8_STAGE(PG8_SB(1, 1), b3 + hstepB, voffB); PG8_STAGE(PG8_SA(1, 0), a3, voffA);
;             PG8_WAIT_V(8); PG8_WAIT_L(0); PG8_BAR; PG8_MMA(1, 0, At, B0); PG8_MMA(1, 1, At, B1); PG8_BAR; PG8_SCHED;
;         }
	s_add_i32 s24, s26, s15
	v_lshl_add_u64 v[202:203], v[202:203], 0, s[54:55]
	s_mov_b32 m0, s24
	ds_read_b128 v[160:163], v210 offset:49152
	ds_read_b128 v[164:167], v210 offset:50176
	ds_read_b128 v[168:171], v210 offset:51200
	ds_read_b128 v[172:175], v210 offset:52224
	ds_read_b128 v[188:191], v210 offset:53248
	ds_read_b128 v[192:195], v210 offset:54272
	ds_read_b128 v[198:201], v210 offset:55296
	ds_read_b128 v[212:215], v210 offset:56320
	global_load_lds_dwordx4 v[202:203], off
	s_add_i32 m0, s24, 0x2000
	s_add_u32 s24, vcc_lo, 0x80080
	v_lshl_add_u64 v[202:203], v[216:217], 0, s[54:55]
	s_addc_u32 s25, vcc_hi, 0
	s_add_i32 s26, s27, s15
	global_load_lds_dwordx4 v[202:203], off
	v_lshl_add_u64 v[202:203], s[24:25], 0, v[176:177]
	s_mov_b32 m0, s26
	s_nop 0
	global_load_lds_dwordx4 v[202:203], off
	v_lshl_add_u64 v[202:203], s[24:25], 0, v[178:179]
	s_add_i32 m0, s26, 0x2000
	s_nop 0
	global_load_lds_dwordx4 v[202:203], off
	v_lshl_add_u64 v[202:203], v[218:219], 0, s[54:55]
	s_mov_b32 m0, s50
	s_nop 0
	global_load_lds_dwordx4 v[202:203], off
	v_lshl_add_u64 v[202:203], v[220:221], 0, s[54:55]
	s_mov_b32 m0, s22
	s_nop 0
	global_load_lds_dwordx4 v[202:203], off
	s_waitcnt vmcnt(8)
	s_waitcnt lgkmcnt(0)
	s_barrier
	s_setprio 1
	s_waitcnt lgkmcnt(0)
	v_mfma_f32_16x16x32_bf16 v[76:79], v[56:59], v[160:163], v[76:79]
	v_mfma_f32_16x16x32_bf16 v[72:75], v[64:67], v[160:163], v[72:75]
	v_mfma_f32_16x16x32_bf16 v[44:47], v[56:59], v[168:171], v[44:47]
	v_mfma_f32_16x16x32_bf16 v[40:43], v[64:67], v[168:171], v[40:43]
	v_mfma_f32_16x16x32_bf16 v[28:31], v[56:59], v[188:191], v[28:31]
	v_mfma_f32_16x16x32_bf16 v[24:27], v[64:67], v[188:191], v[24:27]
	v_mfma_f32_16x16x32_bf16 v[12:15], v[56:59], v[198:201], v[12:15]
	v_mfma_f32_16x16x32_bf16 v[8:11], v[64:67], v[198:201], v[8:11]
	v_mfma_f32_16x16x32_bf16 v[76:79], v[60:63], v[164:167], v[76:79]
	v_mfma_f32_16x16x32_bf16 v[72:75], v[68:71], v[164:167], v[72:75]
	v_mfma_f32_16x16x32_bf16 v[44:47], v[60:63], v[172:175], v[44:47]
	v_mfma_f32_16x16x32_bf16 v[40:43], v[68:71], v[172:175], v[40:43]
	v_mfma_f32_16x16x32_bf16 v[28:31], v[60:63], v[192:195], v[28:31]
	v_mfma_f32_16x16x32_bf16 v[24:27], v[68:71], v[192:195], v[24:27]
	v_mfma_f32_16x16x32_bf16 v[12:15], v[60:63], v[212:215], v[12:15]
	v_mfma_f32_16x16x32_bf16 v[8:11], v[68:71], v[212:215], v[8:11]
	s_setprio 0
	s_setprio 1
	v_mfma_f32_16x16x32_bf16 v[52:55], v[144:147], v[160:163], v[52:55]
	v_mfma_f32_16x16x32_bf16 v[48:51], v[152:155], v[160:163], v[48:51]
	v_mfma_f32_16x16x32_bf16 v[36:39], v[144:147], v[168:171], v[36:39]
	v_mfma_f32_16x16x32_bf16 v[32:35], v[152:155], v[168:171], v[32:35]
	v_mfma_f32_16x16x32_bf16 v[20:23], v[144:147], v[188:191], v[20:23]
	v_mfma_f32_16x16x32_bf16 v[16:19], v[152:155], v[188:191], v[16:19]
	v_mfma_f32_16x16x32_bf16 v[4:7], v[144:147], v[198:201], v[4:7]
	v_mfma_f32_16x16x32_bf16 v[0:3], v[152:155], v[198:201], v[0:3]
	v_mfma_f32_16x16x32_bf16 v[52:55], v[148:151], v[164:167], v[52:55]
	v_mfma_f32_16x16x32_bf16 v[48:51], v[156:159], v[164:167], v[48:51]
	v_mfma_f32_16x16x32_bf16 v[36:39], v[148:151], v[172:175], v[36:39]
	v_mfma_f32_16x16x32_bf16 v[32:35], v[156:159], v[172:175], v[32:35]
	v_mfma_f32_16x16x32_bf16 v[20:23], v[148:151], v[192:195], v[20:23]
	v_mfma_f32_16x16x32_bf16 v[16:19], v[156:159], v[192:195], v[16:19]
	v_mfma_f32_16x16x32_bf16 v[4:7], v[148:151], v[212:215], v[4:7]
	v_mfma_f32_16x16x32_bf16 v[0:3], v[156:159], v[212:215], v[0:3]
	s_add_i32 s42, s42, 2
	s_add_u32 s38, s38, 0x100
	s_addc_u32 s39, s39, 0
	s_add_u32 s8, s8, 0x100
	s_addc_u32 s9, s9, 0
	s_cmp_gt_u32 s42, 29
	s_setprio 0
	s_barrier
	s_cbranch_scc0 .LBB0_993
	s_and_b64 vcc, exec, s[88:89]
	s_cbranch_vccz .LBB0_996
	s_barrier
